# v71 plus memory-attention query rows software-pipelined one 128-row pass ahead (loads into spare registers mid-pass, copied at the top of the next pass); LDS read blocks of 5
# baseline (speedup 1.0000x reference)
; #define LAS __attribute__((address_space(3)))
; template <bool SAMPLE>
; __device__ __forceinline__ void mem_unit(const Params& p, int l, LAS unsigned char* lds, int unit, int tid, int wave, int lane) {
;     ...
;         for (int hb = 0; hb < 2; ++hb) {
;             float kk[4][8], vv[4][8];
; #pragma unroll
;             for (int it = 0; it < 4; ++it) { const int s = (tid >> 4) + 32 * (4 * hb + it);
;                 const float* kp; const float* vp;
;                 if (!SAMPLE) { kp = (const float*)(p.ws + W_MKV) + ((size_t)l * 1024 + b * 256 + s) * 1024 + h * 128 + sub * 8; vp = kp + 512; }
;                 else { const size_t o = ((((size_t)l * 128 + b) * 256 + s) * 4 + h) * 128 + sub * 8; kp = p.in[I_CMK] + o; vp = p.in[I_CMV] + o; }
;                 if (SAMPLE) { pg8::ld8f_nt(kp, kk[it]); pg8::ld8f_nt(vp, vv[it]); } else { pg8::ld8f(kp, kk[it]); pg8::ld8f(vp, vv[it]); } }
; #pragma unroll
;             for (int it = 0; it < 4; ++it) { const int s = (tid >> 4) + 32 * (4 * hb + it);
;                 float (&k)[8] = kk[it]; float (&v)[8] = vv[it];
;                 if (!SAMPLE) { float ss = 0.f;
; #pragma unroll
;                     for (int e = 0; e < 8; ++e) ss += k[e] * k[e];
;                     ss += __shfl_xor(ss, 1); ss += __shfl_xor(ss, 2); ss += __shfl_xor(ss, 4); ss += __shfl_xor(ss, 8);
;                     const float rs = rsqrtf(ss * (1.f / 128.f) + EPS);
; #pragma unroll
;                     for (int e = 0; e < 8; ++e) k[e] *= rs * kg[e];
;                     if (qt == 0) { const size_t o = ((((size_t)l * 4 + b) * 256 + s) * 4 + h) * 128 + sub * 8;
;                         *(f32x4*)(p.out + O_MKP + o) = (f32x4){k[0], k[1], k[2], k[3]}; *(f32x4*)(p.out + O_MKP + o + 4) = (f32x4){k[4], k[5], k[6], k[7]};
;                         *(f32x4*)(p.out + O_MVP + o) = (f32x4){v[0], v[1], v[2], v[3]}; *(f32x4*)(p.out + O_MVP + o + 4) = (f32x4){v[4], v[5], v[6], v[7]}; }
;                 }
;                 *(LAS bf16x8*)(Kl + s * MEM_KS + sub * 8) = pack8(k);
;                 *(LAS bf16x8*)(Vt + s * MEM_VS + sub * 8) = pack8(v);
;     ...
;     __syncthreads();
;     if (!SAMPLE || wave == 0) {
; #pragma unroll 1
;       for (int qq = 0; qq < (SAMPLE ? 1 : 4); ++qq) {
;         int q16 = lane & 15, kq = lane >> 4; asm volatile("" : "+v"(q16), "+v"(kq));
;         size_t row; bool st;
.LBB0_599:
	s_waitcnt vmcnt(1)
	v_add_u32_e32 v66, s8, v81
	v_ashrrev_i32_e32 v67, 31, v66
	v_add_u32_e32 v6, 0x60, v66
	v_lshl_add_u64 v[8:9], v[66:67], 0, s[10:11]
	v_add_u32_e32 v2, 32, v66
	v_add_u32_e32 v4, 64, v66
	v_ashrrev_i32_e32 v7, 31, v6
	v_lshlrev_b64 v[8:9], 11, v[8:9]
	v_ashrrev_i32_e32 v3, 31, v2
	v_ashrrev_i32_e32 v5, 31, v4
	v_lshl_add_u64 v[6:7], v[6:7], 0, s[10:11]
	v_or_b32_e32 v8, v8, v0
	v_lshl_add_u64 v[2:3], v[2:3], 0, s[10:11]
	v_lshl_add_u64 v[4:5], v[4:5], 0, s[10:11]
	v_lshlrev_b64 v[22:23], 11, v[6:7]
	v_lshl_add_u64 v[6:7], s[78:79], 0, v[8:9]
	v_lshl_add_u64 v[14:15], s[80:81], 0, v[8:9]
	v_lshlrev_b64 v[18:19], 11, v[2:3]
	v_lshlrev_b64 v[20:21], 11, v[4:5]
	global_load_dwordx4 v[2:5], v[6:7], off nt
	s_nop 0
	global_load_dwordx4 v[6:9], v[6:7], off offset:16 nt
	s_nop 0
	global_load_dwordx4 v[10:13], v[14:15], off offset:16 nt
	s_nop 0
	global_load_dwordx4 v[14:17], v[14:15], off nt
	v_or_b32_e32 v18, v18, v0
	v_or_b32_e32 v20, v20, v0
	v_or_b32_e32 v22, v22, v0
	v_lshl_add_u64 v[24:25], s[78:79], 0, v[18:19]
	v_lshl_add_u64 v[30:31], s[80:81], 0, v[18:19]
	s_waitcnt vmcnt(4)
	v_lshl_add_u64 v[38:39], s[78:79], 0, v[20:21]
	v_lshl_add_u64 v[46:47], s[80:81], 0, v[20:21]
	v_lshl_add_u64 v[54:55], s[78:79], 0, v[22:23]
	v_lshl_add_u64 v[62:63], s[80:81], 0, v[22:23]
	global_load_dwordx4 v[18:21], v[24:25], off nt
	s_nop 0
	global_load_dwordx4 v[22:25], v[24:25], off offset:16 nt
	s_nop 0
	global_load_dwordx4 v[26:29], v[30:31], off nt
	s_nop 0
	global_load_dwordx4 v[30:33], v[30:31], off offset:16 nt
	s_nop 0
	global_load_dwordx4 v[34:37], v[38:39], off nt
	s_nop 0
	global_load_dwordx4 v[38:41], v[38:39], off offset:16 nt
	s_nop 0
	global_load_dwordx4 v[42:45], v[46:47], off nt
	s_nop 0
	global_load_dwordx4 v[46:49], v[46:47], off offset:16 nt
	s_nop 0
	global_load_dwordx4 v[50:53], v[54:55], off nt
	s_nop 0
	global_load_dwordx4 v[54:57], v[54:55], off offset:16 nt
	s_nop 0
	global_load_dwordx4 v[58:61], v[62:63], off nt
	s_nop 0
	global_load_dwordx4 v[62:65], v[62:63], off offset:16 nt
	v_cndmask_b32_e64 v1, 0, 1, s[0:1]
	v_cmp_ne_u32_e32 vcc, 1, v1
	v_mul_lo_u32 v1, v66, s30
	v_add_u32_e32 v66, v96, v1
	v_add_u32_e32 v1, v97, v1
	s_movk_i32 s8, 0x80
	s_mov_b64 s[0:1], 0
	s_and_b64 vcc, exec, vcc
	s_waitcnt vmcnt(15)
	v_cvt_pk_bf16_f32 v2, v2, v3
	v_cvt_pk_bf16_f32 v3, v4, v5
	s_waitcnt vmcnt(14)
	v_cvt_pk_bf16_f32 v4, v6, v7
	v_cvt_pk_bf16_f32 v5, v8, v9
	ds_write_b128 v66, v[2:5]
	s_waitcnt vmcnt(12)
	v_cvt_pk_bf16_f32 v2, v14, v15
	v_cvt_pk_bf16_f32 v3, v16, v17
	v_cvt_pk_bf16_f32 v4, v10, v11
	v_cvt_pk_bf16_f32 v5, v12, v13
	ds_write_b128 v1, v[2:5]
	s_waitcnt vmcnt(11)
	v_cvt_pk_bf16_f32 v2, v18, v19
	v_cvt_pk_bf16_f32 v3, v20, v21
	s_waitcnt vmcnt(10)
	v_cvt_pk_bf16_f32 v4, v22, v23
	v_cvt_pk_bf16_f32 v5, v24, v25
	ds_write_b128 v66, v[2:5] offset:8704
	s_waitcnt vmcnt(9)
	v_cvt_pk_bf16_f32 v2, v26, v27
	v_cvt_pk_bf16_f32 v3, v28, v29
	s_waitcnt vmcnt(8)
	v_cvt_pk_bf16_f32 v4, v30, v31
	v_cvt_pk_bf16_f32 v5, v32, v33
	ds_write_b128 v1, v[2:5] offset:8704
	s_waitcnt vmcnt(7)
	v_cvt_pk_bf16_f32 v2, v34, v35
	v_cvt_pk_bf16_f32 v3, v36, v37
	s_waitcnt vmcnt(6)
	v_cvt_pk_bf16_f32 v4, v38, v39
	v_cvt_pk_bf16_f32 v5, v40, v41
	ds_write_b128 v66, v[2:5] offset:17408
	s_waitcnt vmcnt(5)
	v_cvt_pk_bf16_f32 v2, v42, v43
	v_cvt_pk_bf16_f32 v3, v44, v45
	s_waitcnt vmcnt(4)
	v_cvt_pk_bf16_f32 v4, v46, v47
	v_cvt_pk_bf16_f32 v5, v48, v49
	ds_write_b128 v1, v[2:5] offset:17408
	s_waitcnt vmcnt(3)
	v_cvt_pk_bf16_f32 v2, v50, v51
	v_cvt_pk_bf16_f32 v3, v52, v53
	s_waitcnt vmcnt(2)
	v_cvt_pk_bf16_f32 v4, v54, v55
	v_cvt_pk_bf16_f32 v5, v56, v57
	ds_write_b128 v66, v[2:5] offset:26112
	s_waitcnt vmcnt(1)
	v_cvt_pk_bf16_f32 v2, v58, v59
	v_cvt_pk_bf16_f32 v3, v60, v61
	s_waitcnt vmcnt(0)
	v_cvt_pk_bf16_f32 v4, v62, v63
	v_cvt_pk_bf16_f32 v5, v64, v65
	ds_write_b128 v1, v[2:5] offset:26112
	s_cbranch_vccz .LBB0_599
	s_andn2_b64 vcc, exec, s[4:5]
	s_waitcnt lgkmcnt(0)
	s_barrier
	s_cbranch_vccnz .LBB0_618
	s_lshl_b32 s0, s2, 3
	s_add_i32 s1, s0, 0x8000
	s_lshl_b32 s0, s3, 1
	v_mov_b32_e32 v37, v95
	v_mov_b32_e32 v36, v94
	s_add_u32 s2, s64, s0
	s_addc_u32 s3, s65, 0
	v_and_or_b32 v0, v36, 7, s1
	v_lshlrev_b32_e32 v82, 10, v0
	v_lshlrev_b32_e32 v16, 3, v37
	v_lshl_add_u64 v[0:1], s[2:3], 0, v[82:83]
	v_ashrrev_i32_e32 v17, 31, v16
	v_lshl_add_u64 v[12:13], v[16:17], 1, v[0:1]
	global_load_dwordx4 v[0:3], v[12:13], off
	global_load_dwordx4 v[4:7], v[12:13], off offset:64
	global_load_dwordx4 v[8:11], v[12:13], off offset:128
	s_nop 0
	global_load_dwordx4 v[12:15], v[12:13], off offset:192
	v_and_b32_e32 v19, 64, v99
	v_xor_b32_e32 v18, 16, v99
	v_add_u32_e32 v34, 64, v19
	v_cmp_lt_i32_e32 vcc, v18, v34
	v_lshl_add_u64 v[24:25], v[16:17], 2, s[46:47]
	s_waitcnt vmcnt(3)
	v_and_b32_e32 v40, 0xffff0000, v0
	v_cndmask_b32_e32 v18, v99, v18, vcc
	v_lshlrev_b32_e32 v38, 2, v18
	global_load_dwordx4 v[16:19], v[24:25], off offset:16
	global_load_dwordx4 v[20:23], v[24:25], off
	v_lshlrev_b32_e32 v35, 16, v0
	s_waitcnt vmcnt(3)
; __device__ __forceinline__ void unpack8(const v4u w, float (&o)[8]) { o[0] = bflo(w.x); o[1] = bfhi(w.x); o[2] = bflo(w.y); o[3] = bfhi(w.y); o[4] = bflo(w.z); o[5] = bfhi(w.z); o[6] = bflo(w.w); o[7] = bfhi(w.w); }
; __device__ __forceinline__ bf16x8 pack8(const float (&o)[8]) { v4u w; w.x = pk2(o[0], o[1]); w.y = pk2(o[2], o[3]); w.z = pk2(o[4], o[5]); w.w = pk2(o[6], o[7]); return __builtin_bit_cast(bf16x8, w); }
; template <bool SAMPLE>
; __device__ __forceinline__ void mem_unit(const Params& p, int l, LAS unsigned char* lds, int unit, int tid, int wave, int lane) {
;     ...
;             float qv[4][8]; float ss = 0.f;
; #pragma unroll
;             for (int dc = 0; dc < 4; ++dc) { unpack8(*(const v4u*)(MQ + row * 512 + h * 128 + 32 * dc + 8 * kq), qv[dc]);
; #pragma unroll
;                 for (int e = 0; e < 8; ++e) ss += qv[dc][e] * qv[dc][e]; }
;             ss += __shfl_xor(ss, 16); ss += __shfl_xor(ss, 32);
;             const float rs = rsqrtf(ss * (1.f / 128.f) + EPS) * 0.08838834764831845f;
; #pragma unroll
;             for (int dc = 0; dc < 4; ++dc) { float qg[8]; pg8::ld8f(p.in[I_MQG] + l * 128 + 32 * dc + 8 * kq, qg);
; #pragma unroll
;                 for (int e = 0; e < 8; ++e) qv[dc][e] *= rs * qg[e];
;                 qf[dc] = pack8(qv[dc]); }
	v_lshlrev_b32_e32 v55, 16, v8
	v_and_b32_e32 v56, 0xffff0000, v8
	v_mul_f32_e32 v8, v40, v40
	v_lshlrev_b32_e32 v41, 16, v1
	v_fmac_f32_e32 v8, v35, v35
	v_and_b32_e32 v42, 0xffff0000, v1
	v_fmac_f32_e32 v8, v41, v41
	v_lshlrev_b32_e32 v43, 16, v2
	v_fmac_f32_e32 v8, v42, v42
	v_and_b32_e32 v44, 0xffff0000, v2
	v_fmac_f32_e32 v8, v43, v43
	v_lshlrev_b32_e32 v45, 16, v3
	v_fmac_f32_e32 v8, v44, v44
	v_and_b32_e32 v46, 0xffff0000, v3
	v_fmac_f32_e32 v8, v45, v45
	v_lshlrev_b32_e32 v47, 16, v4
	v_fmac_f32_e32 v8, v46, v46
	v_and_b32_e32 v48, 0xffff0000, v4
	v_fmac_f32_e32 v8, v47, v47
	v_lshlrev_b32_e32 v49, 16, v5
	v_fmac_f32_e32 v8, v48, v48
	v_and_b32_e32 v50, 0xffff0000, v5
	v_fmac_f32_e32 v8, v49, v49
	v_lshlrev_b32_e32 v51, 16, v6
	v_fmac_f32_e32 v8, v50, v50
	v_and_b32_e32 v52, 0xffff0000, v6
	v_fmac_f32_e32 v8, v51, v51
	v_lshlrev_b32_e32 v53, 16, v7
	v_fmac_f32_e32 v8, v52, v52
	v_and_b32_e32 v54, 0xffff0000, v7
	v_fmac_f32_e32 v8, v53, v53
	v_fmac_f32_e32 v8, v54, v54
	v_fmac_f32_e32 v8, v55, v55
	v_lshlrev_b32_e32 v57, 16, v9
	v_fmac_f32_e32 v8, v56, v56
	v_and_b32_e32 v58, 0xffff0000, v9
	v_fmac_f32_e32 v8, v57, v57
	v_lshlrev_b32_e32 v59, 16, v10
	v_fmac_f32_e32 v8, v58, v58
	v_and_b32_e32 v60, 0xffff0000, v10
	v_fmac_f32_e32 v8, v59, v59
	v_lshlrev_b32_e32 v61, 16, v11
	v_fmac_f32_e32 v8, v60, v60
	v_and_b32_e32 v62, 0xffff0000, v11
	s_waitcnt vmcnt(2)
	v_and_b32_e32 v26, 0xffff0000, v12
	v_lshlrev_b32_e32 v27, 16, v12
	v_fmac_f32_e32 v8, v61, v61
	v_pk_mul_f32 v[0:1], v[26:27], v[26:27]
	v_fmac_f32_e32 v8, v62, v62
	v_and_b32_e32 v28, 0xffff0000, v13
	v_lshlrev_b32_e32 v29, 16, v13
	v_add_f32_e32 v1, v1, v8
	v_pk_mul_f32 v[2:3], v[28:29], v[28:29]
	v_add_f32_e32 v0, v0, v1
	v_and_b32_e32 v30, 0xffff0000, v14
	v_lshlrev_b32_e32 v31, 16, v14
	v_add_f32_e32 v0, v3, v0
	v_pk_mul_f32 v[4:5], v[30:31], v[30:31]
	v_add_f32_e32 v0, v2, v0
	v_and_b32_e32 v32, 0xffff0000, v15
	v_lshlrev_b32_e32 v33, 16, v15
	v_add_f32_e32 v0, v5, v0
	v_pk_mul_f32 v[6:7], v[32:33], v[32:33]
	v_add_f32_e32 v0, v4, v0
	v_add_f32_e32 v0, v7, v0
	v_add_f32_e32 v0, v6, v0
	ds_bpermute_b32 v1, v38, v0
	v_xor_b32_e32 v2, 32, v99
	v_cmp_lt_i32_e32 vcc, v2, v34
	s_waitcnt lgkmcnt(0)
	v_add_f32_e32 v0, v0, v1
	v_cndmask_b32_e32 v2, v99, v2, vcc
	v_lshlrev_b32_e32 v39, 2, v2
	ds_bpermute_b32 v1, v39, v0
	s_waitcnt lgkmcnt(0)
	v_add_f32_e32 v0, v0, v1
	v_fmamk_f32 v0, v0, 0x3c000000, v98
	v_mul_f32_e32 v1, 0x4b800000, v0
	v_cmp_gt_f32_e32 vcc, s31, v0
	s_nop 1
	v_cndmask_b32_e32 v0, v0, v1, vcc
	v_rsq_f32_e32 v0, v0
	s_nop 0
	v_mul_f32_e32 v1, 0x45800000, v0
	v_cndmask_b32_e32 v0, v0, v1, vcc
	v_mul_f32_e32 v34, 0x3db504f3, v0
	s_waitcnt vmcnt(0)
	v_mul_f32_e32 v0, v20, v34
	v_mul_f32_e32 v1, v21, v34
	v_mul_f32_e32 v2, v22, v34
	v_mul_f32_e32 v3, v23, v34
	v_mul_f32_e32 v4, v16, v34
	v_mul_f32_e32 v5, v17, v34
	v_mul_f32_e32 v6, v18, v34
	v_mul_f32_e32 v7, v19, v34
	v_mul_f32_e32 v0, v0, v35
	v_mul_f32_e32 v1, v1, v40
	v_mul_f32_e32 v2, v2, v41
	v_mul_f32_e32 v3, v3, v42
	v_mul_f32_e32 v4, v4, v43
	v_mul_f32_e32 v5, v5, v44
	v_mul_f32_e32 v6, v6, v45
	v_mul_f32_e32 v7, v7, v46
	v_cvt_pk_bf16_f32 v0, v0, v1
	v_cvt_pk_bf16_f32 v1, v2, v3
	v_cvt_pk_bf16_f32 v2, v4, v5
	v_cvt_pk_bf16_f32 v3, v6, v7
	global_load_dwordx4 v[4:7], v[24:25], off offset:128
	global_load_dwordx4 v[8:11], v[24:25], off offset:144
	v_lshlrev_b32_e32 v20, 4, v37
	v_mul_lo_u32 v21, v36, s30
	v_add3_u32 v92, 0, v20, v21
	s_waitcnt vmcnt(1)
	v_mul_f32_e32 v4, v4, v34
	v_mul_f32_e32 v5, v5, v34
	v_mul_f32_e32 v6, v6, v34
	v_mul_f32_e32 v7, v7, v34
	s_waitcnt vmcnt(0)
	v_mul_f32_e32 v8, v8, v34
	v_mul_f32_e32 v9, v9, v34
	v_mul_f32_e32 v10, v10, v34
	v_mul_f32_e32 v11, v11, v34
	v_mul_f32_e32 v4, v4, v47
	v_mul_f32_e32 v5, v5, v48
	v_mul_f32_e32 v6, v6, v49
	v_mul_f32_e32 v7, v7, v50
	v_mul_f32_e32 v12, v8, v51
	v_mul_f32_e32 v13, v9, v52
	v_mul_f32_e32 v14, v10, v53
	v_mul_f32_e32 v11, v11, v54
	v_cvt_pk_bf16_f32 v8, v4, v5
	v_cvt_pk_bf16_f32 v9, v6, v7
	v_cvt_pk_bf16_f32 v10, v12, v13
	v_cvt_pk_bf16_f32 v11, v14, v11
	global_load_dwordx4 v[4:7], v[24:25], off offset:256
	global_load_dwordx4 v[12:15], v[24:25], off offset:272
	s_waitcnt vmcnt(1)
	v_mul_f32_e32 v4, v4, v34
	v_mul_f32_e32 v5, v5, v34
	v_mul_f32_e32 v6, v6, v34
	v_mul_f32_e32 v7, v7, v34
	s_waitcnt vmcnt(0)
	v_mul_f32_e32 v12, v12, v34
	v_mul_f32_e32 v13, v13, v34
	v_mul_f32_e32 v14, v14, v34
	v_mul_f32_e32 v15, v15, v34
	v_mul_f32_e32 v4, v4, v55
	v_mul_f32_e32 v5, v5, v56
	v_mul_f32_e32 v6, v6, v57
	v_mul_f32_e32 v7, v7, v58
	v_mul_f32_e32 v12, v12, v59
	v_mul_f32_e32 v13, v13, v60
	v_mul_f32_e32 v14, v14, v61
	v_mul_f32_e32 v15, v15, v62
	v_cvt_pk_bf16_f32 v4, v4, v5
	v_cvt_pk_bf16_f32 v5, v6, v7
	v_cvt_pk_bf16_f32 v6, v12, v13
	v_cvt_pk_bf16_f32 v7, v14, v15
	global_load_dwordx4 v[12:15], v[24:25], off offset:384
	global_load_dwordx4 v[16:19], v[24:25], off offset:400
	s_waitcnt vmcnt(1)
	v_mul_f32_e32 v12, v12, v34
	v_mul_f32_e32 v13, v13, v34
	v_mul_f32_e32 v14, v14, v34
	v_mul_f32_e32 v15, v15, v34
	s_waitcnt vmcnt(0)
; #define LAS __attribute__((address_space(3)))
; template <bool SAMPLE>
; __device__ __forceinline__ void mem_unit(const Params& p, int l, LAS unsigned char* lds, int unit, int tid, int wave, int lane) {
;     ...
;         f32x4 S[8][2]; float mx = -INFINITY;
; #pragma unroll
;         for (int cc = 0; cc < 8; ++cc)
; #pragma unroll
;             for (int tt = 0; tt < 2; ++tt) { const int kb = 32 * cc + 16 * tt; f32x4 a = (f32x4){0.f, 0.f, 0.f, 0.f};
; #pragma unroll
;                 for (int dc = 0; dc < 4; ++dc) { const bf16x8 kf = *(const LAS bf16x8*)(Kl + (kb + q16) * MEM_KS + 32 * dc + 8 * kq);
;                     a = __builtin_amdgcn_mfma_f32_16x16x32_bf16(kf, qf[dc], a, 0, 0, 0); }
; #pragma unroll
;                 for (int e = 0; e < 4; ++e) mx = fmaxf(mx, a[e]);
;                 S[cc][tt] = a; }
	v_mul_f32_e32 v16, v16, v34
	v_mul_f32_e32 v17, v17, v34
	v_mul_f32_e32 v18, v18, v34
	v_mul_f32_e32 v19, v19, v34
	v_mul_f32_e32 v12, v12, v27
	v_mul_f32_e32 v13, v13, v26
	v_mul_f32_e32 v14, v14, v29
	v_mul_f32_e32 v15, v15, v28
	v_mul_f32_e32 v16, v16, v31
	v_mul_f32_e32 v17, v17, v30
	v_mul_f32_e32 v18, v18, v33
	v_mul_f32_e32 v19, v19, v32
	v_cvt_pk_bf16_f32 v32, v12, v13
	v_cvt_pk_bf16_f32 v33, v14, v15
	v_cvt_pk_bf16_f32 v34, v16, v17
	v_cvt_pk_bf16_f32 v35, v18, v19
	ds_read_b128 v[186:189], v92
	ds_read_b128 v[190:193], v92 offset:4352
	ds_read_b128 v[194:197], v92 offset:8704
	ds_read_b128 v[198:201], v92 offset:13056
	ds_read_b128 v[202:205], v92 offset:17408
	s_nop 0
	ds_read_b128 v[16:19], v92 offset:64
	s_nop 0
	ds_read_b128 v[24:27], v92 offset:4416
	s_nop 0
	ds_read_b128 v[40:43], v92 offset:8768
	s_nop 0
	ds_read_b128 v[48:51], v92 offset:13120
	s_nop 0
	ds_read_b128 v[56:59], v92 offset:17472
	ds_read_b128 v[60:63], v92 offset:21760
	ds_read_b128 v[64:67], v92 offset:21824
	ds_read_b128 v[68:71], v92 offset:26112
	ds_read_b128 v[72:75], v92 offset:26176
	ds_read_b128 v[76:79], v92 offset:30464
	ds_read_b128 v[88:91], v92 offset:30528
	ds_read_b128 v[100:103], v92 offset:34816
	ds_read_b128 v[104:107], v92 offset:34880
	ds_read_b128 v[108:111], v92 offset:39168
	ds_read_b128 v[112:115], v92 offset:39232
	ds_read_b128 v[116:119], v92 offset:43520
	ds_read_b128 v[120:123], v92 offset:43584
	ds_read_b128 v[124:127], v92 offset:47872
	ds_read_b128 v[128:131], v92 offset:47936
	ds_read_b128 v[132:135], v92 offset:52224
	ds_read_b128 v[136:139], v92 offset:52288
	ds_read_b128 v[140:143], v92 offset:56576
	ds_read_b128 v[144:147], v92 offset:56640
	ds_read_b128 v[148:151], v92 offset:60928
	ds_read_b128 v[152:155], v92 offset:60992
	ds_read_b128 v[156:159], v92 offset:65280
	ds_read_b128 v[160:163], v92 offset:65344
	s_waitcnt lgkmcnt(14)
	v_mfma_f32_16x16x32_bf16 v[12:15], v[186:189], v[0:3], 0
	v_mfma_f32_16x16x32_bf16 v[20:23], v[190:193], v[0:3], 0
	v_mfma_f32_16x16x32_bf16 v[28:31], v[194:197], v[0:3], 0
	v_mfma_f32_16x16x32_bf16 v[44:47], v[198:201], v[0:3], 0
	v_mfma_f32_16x16x32_bf16 v[52:55], v[202:205], v[0:3], 0
	v_mfma_f32_16x16x32_bf16 v[60:63], v[60:63], v[0:3], 0
	v_mfma_f32_16x16x32_bf16 v[68:71], v[68:71], v[0:3], 0
	v_mfma_f32_16x16x32_bf16 v[76:79], v[76:79], v[0:3], 0
	v_mfma_f32_16x16x32_bf16 v[100:103], v[100:103], v[0:3], 0
	s_waitcnt lgkmcnt(13)
	v_mfma_f32_16x16x32_bf16 v[108:111], v[108:111], v[0:3], 0
	s_waitcnt lgkmcnt(11)
	v_mfma_f32_16x16x32_bf16 v[116:119], v[116:119], v[0:3], 0
	s_waitcnt lgkmcnt(9)
	v_mfma_f32_16x16x32_bf16 v[124:127], v[124:127], v[0:3], 0
	s_waitcnt lgkmcnt(7)
	v_mfma_f32_16x16x32_bf16 v[132:135], v[132:135], v[0:3], 0
	s_waitcnt lgkmcnt(5)
	v_mfma_f32_16x16x32_bf16 v[140:143], v[140:143], v[0:3], 0
	s_waitcnt lgkmcnt(3)
	v_mfma_f32_16x16x32_bf16 v[148:151], v[148:151], v[0:3], 0
	s_waitcnt lgkmcnt(1)
	v_mfma_f32_16x16x32_bf16 v[0:3], v[156:159], v[0:3], 0
	v_mfma_f32_16x16x32_bf16 v[12:15], v[16:19], v[8:11], v[12:15]
	v_mfma_f32_16x16x32_bf16 v[16:19], v[24:27], v[8:11], v[20:23]
	v_mfma_f32_16x16x32_bf16 v[20:23], v[40:43], v[8:11], v[28:31]
	v_mfma_f32_16x16x32_bf16 v[24:27], v[48:51], v[8:11], v[44:47]
	v_mfma_f32_16x16x32_bf16 v[28:31], v[56:59], v[8:11], v[52:55]
	v_mfma_f32_16x16x32_bf16 v[40:43], v[64:67], v[8:11], v[60:63]
	v_mfma_f32_16x16x32_bf16 v[44:47], v[72:75], v[8:11], v[68:71]
	v_mfma_f32_16x16x32_bf16 v[48:51], v[88:91], v[8:11], v[76:79]
	v_mfma_f32_16x16x32_bf16 v[52:55], v[104:107], v[8:11], v[100:103]
	ds_read_b128 v[190:193], v92 offset:128
	ds_read_b128 v[194:197], v92 offset:4480
	ds_read_b128 v[198:201], v92 offset:8832
	ds_read_b128 v[202:205], v92 offset:13184
	v_mfma_f32_16x16x32_bf16 v[56:59], v[112:115], v[8:11], v[108:111]
	v_mfma_f32_16x16x32_bf16 v[60:63], v[120:123], v[8:11], v[116:119]
	v_mfma_f32_16x16x32_bf16 v[64:67], v[128:131], v[8:11], v[124:127]
	v_mfma_f32_16x16x32_bf16 v[68:71], v[136:139], v[8:11], v[132:135]
	v_mfma_f32_16x16x32_bf16 v[72:75], v[144:147], v[8:11], v[140:143]
	ds_read_b128 v[206:209], v92 offset:17536
	ds_read_b128 v[210:213], v92 offset:21888
	ds_read_b128 v[218:221], v92 offset:26240
	ds_read_b128 v[222:225], v92 offset:30592
	ds_read_b128 v[226:229], v92 offset:34944
	v_mfma_f32_16x16x32_bf16 v[76:79], v[152:155], v[8:11], v[148:151]
	s_waitcnt lgkmcnt(9)
	v_mfma_f32_16x16x32_bf16 v[0:3], v[160:163], v[8:11], v[0:3]
	s_nop 0
	ds_read_b128 v[88:91], v92 offset:192
	s_waitcnt lgkmcnt(9)
	v_mfma_f32_16x16x32_bf16 v[8:11], v[190:193], v[4:7], v[12:15]
	s_nop 2
	s_nop 0
	ds_read_b128 v[100:103], v92 offset:4544
	s_waitcnt lgkmcnt(9)
	v_mfma_f32_16x16x32_bf16 v[12:15], v[194:197], v[4:7], v[16:19]
	s_nop 2
	s_nop 0
	ds_read_b128 v[104:107], v92 offset:8896
	s_waitcnt lgkmcnt(9)
	v_mfma_f32_16x16x32_bf16 v[16:19], v[198:201], v[4:7], v[20:23]
	s_nop 2
	s_nop 0
	ds_read_b128 v[108:111], v92 offset:13248
	s_waitcnt lgkmcnt(9)
	v_mfma_f32_16x16x32_bf16 v[20:23], v[202:205], v[4:7], v[24:27]
	s_nop 2
	s_nop 0
	ds_read_b128 v[112:115], v92 offset:17600
	s_waitcnt lgkmcnt(9)
	ds_read_b128 v[186:189], v92 offset:39296
	ds_read_b128 v[190:193], v92 offset:43648
	ds_read_b128 v[194:197], v92 offset:48000
	ds_read_b128 v[198:201], v92 offset:52352
	ds_read_b128 v[202:205], v92 offset:56704
	v_mfma_f32_16x16x32_bf16 v[24:27], v[206:209], v[4:7], v[28:31]
	s_nop 2
	s_nop 0
	ds_read_b128 v[116:119], v92 offset:21952
	s_waitcnt lgkmcnt(14)
	v_mfma_f32_16x16x32_bf16 v[28:31], v[210:213], v[4:7], v[40:43]
	s_nop 2
	s_nop 0
	ds_read_b128 v[120:123], v92 offset:26304
	s_waitcnt lgkmcnt(14)
; #define LAS __attribute__((address_space(3)))
; template <bool SAMPLE>
; __device__ __forceinline__ void mem_unit(const Params& p, int l, LAS unsigned char* lds, int unit, int tid, int wave, int lane) {
;     ...
;         f32x4 S[8][2]; float mx = -INFINITY;
; #pragma unroll
;         for (int cc = 0; cc < 8; ++cc)
; #pragma unroll
;             for (int tt = 0; tt < 2; ++tt) { const int kb = 32 * cc + 16 * tt; f32x4 a = (f32x4){0.f, 0.f, 0.f, 0.f};
; #pragma unroll
;                 for (int dc = 0; dc < 4; ++dc) { const bf16x8 kf = *(const LAS bf16x8*)(Kl + (kb + q16) * MEM_KS + 32 * dc + 8 * kq);
;                     a = __builtin_amdgcn_mfma_f32_16x16x32_bf16(kf, qf[dc], a, 0, 0, 0); }
; #pragma unroll
;                 for (int e = 0; e < 4; ++e) mx = fmaxf(mx, a[e]);
;                 S[cc][tt] = a; }
;         mx = fmaxf(mx, __shfl_xor(mx, 16)); mx = fmaxf(mx, __shfl_xor(mx, 32));
;         float den = 0.f;
; #pragma unroll
;         for (int cc = 0; cc < 8; ++cc)
; #pragma unroll
;             for (int tt = 0; tt < 2; ++tt)
; #pragma unroll
;                 for (int e = 0; e < 4; ++e) { const float pe = __expf(S[cc][tt][e] - mx); S[cc][tt][e] = pe; den += pe; }
;         den += __shfl_xor(den, 16); den += __shfl_xor(den, 32);
;         const float rden = 1.f / den;
	v_mfma_f32_16x16x32_bf16 v[40:43], v[218:221], v[4:7], v[44:47]
	s_nop 2
	s_nop 0
	ds_read_b128 v[124:127], v92 offset:30656
	s_waitcnt lgkmcnt(14)
	v_mfma_f32_16x16x32_bf16 v[44:47], v[222:225], v[4:7], v[48:51]
	s_nop 2
	s_nop 0
	ds_read_b128 v[128:131], v92 offset:35008
	s_waitcnt lgkmcnt(14)
	v_mfma_f32_16x16x32_bf16 v[48:51], v[226:229], v[4:7], v[52:55]
	s_nop 2
	s_nop 0
	ds_read_b128 v[132:135], v92 offset:39360
	s_waitcnt lgkmcnt(9)
	ds_read_b128 v[206:209], v92 offset:61056
	ds_read_b128 v[210:213], v92 offset:65408
	v_mfma_f32_16x16x32_bf16 v[52:55], v[186:189], v[4:7], v[56:59]
	s_nop 2
	s_nop 0
	ds_read_b128 v[136:139], v92 offset:43712
	s_waitcnt lgkmcnt(11)
	v_mfma_f32_16x16x32_bf16 v[56:59], v[190:193], v[4:7], v[60:63]
	s_nop 2
	s_nop 0
	ds_read_b128 v[140:143], v92 offset:48064
	s_waitcnt lgkmcnt(11)
	v_mfma_f32_16x16x32_bf16 v[60:63], v[194:197], v[4:7], v[64:67]
	s_nop 2
	s_nop 0
	ds_read_b128 v[144:147], v92 offset:52416
	s_waitcnt lgkmcnt(11)
	v_mfma_f32_16x16x32_bf16 v[64:67], v[198:201], v[4:7], v[68:71]
	s_nop 2
	s_nop 0
	ds_read_b128 v[148:151], v92 offset:56768
	s_waitcnt lgkmcnt(11)
	v_mfma_f32_16x16x32_bf16 v[68:71], v[202:205], v[4:7], v[72:75]
	s_nop 2
	s_nop 0
	ds_read_b128 v[152:155], v92 offset:61120
	s_waitcnt lgkmcnt(6)
	v_mfma_f32_16x16x32_bf16 v[72:75], v[206:209], v[4:7], v[76:79]
	s_nop 2
	s_nop 0
	ds_read_b128 v[156:159], v92 offset:65472
	s_waitcnt lgkmcnt(6)
	v_mfma_f32_16x16x32_bf16 v[0:3], v[210:213], v[4:7], v[0:3]
	v_mfma_f32_16x16x32_bf16 v[76:79], v[88:91], v[32:35], v[8:11]
	v_mfma_f32_16x16x32_bf16 v[88:91], v[100:103], v[32:35], v[12:15]
	v_mfma_f32_16x16x32_bf16 v[100:103], v[104:107], v[32:35], v[16:19]
	v_mfma_f32_16x16x32_bf16 v[104:107], v[108:111], v[32:35], v[20:23]
	v_mfma_f32_16x16x32_bf16 v[108:111], v[112:115], v[32:35], v[24:27]
	v_mfma_f32_16x16x32_bf16 v[112:115], v[116:119], v[32:35], v[28:31]
	v_mfma_f32_16x16x32_bf16 v[40:43], v[120:123], v[32:35], v[40:43]
	v_mfma_f32_16x16x32_bf16 v[44:47], v[124:127], v[32:35], v[44:47]
	v_mfma_f32_16x16x32_bf16 v[28:31], v[128:131], v[32:35], v[48:51]
	v_mfma_f32_16x16x32_bf16 v[24:27], v[132:135], v[32:35], v[52:55]
	v_mfma_f32_16x16x32_bf16 v[20:23], v[136:139], v[32:35], v[56:59]
	v_mfma_f32_16x16x32_bf16 v[16:19], v[140:143], v[32:35], v[60:63]
	v_mfma_f32_16x16x32_bf16 v[12:15], v[144:147], v[32:35], v[64:67]
	v_mfma_f32_16x16x32_bf16 v[8:11], v[148:151], v[32:35], v[68:71]
	v_mfma_f32_16x16x32_bf16 v[4:7], v[152:155], v[32:35], v[72:75]
	s_waitcnt lgkmcnt(0)
	v_mfma_f32_16x16x32_bf16 v[0:3], v[156:159], v[32:35], v[0:3]
	v_max3_f32 v32, v76, s33, v77
	v_max3_f32 v32, v32, v78, v79
	v_max3_f32 v32, v32, v88, v89
	v_max3_f32 v32, v32, v90, v91
	v_max3_f32 v32, v32, v100, v101
	v_max3_f32 v32, v32, v102, v103
	v_max3_f32 v32, v32, v104, v105
	v_max3_f32 v32, v32, v106, v107
	v_max3_f32 v32, v32, v108, v109
	v_max3_f32 v32, v32, v110, v111
	v_max3_f32 v32, v32, v112, v113
	v_max3_f32 v32, v32, v114, v115
	v_max3_f32 v32, v32, v40, v41
	v_max3_f32 v32, v32, v42, v43
	v_max3_f32 v32, v32, v44, v45
	v_max3_f32 v32, v32, v46, v47
	v_max3_f32 v32, v32, v28, v29
	v_max3_f32 v32, v32, v30, v31
	v_max3_f32 v32, v32, v24, v25
	v_max3_f32 v32, v32, v26, v27
	v_max3_f32 v32, v32, v20, v21
	v_max3_f32 v32, v32, v22, v23
	v_max3_f32 v32, v32, v16, v17
	v_max3_f32 v32, v32, v18, v19
	v_max3_f32 v32, v32, v12, v13
	v_max3_f32 v32, v32, v14, v15
	v_max3_f32 v32, v32, v8, v9
	v_max3_f32 v32, v32, v10, v11
	v_max3_f32 v32, v32, v4, v5
	v_max3_f32 v32, v32, v6, v7
	v_max3_f32 v32, v32, v0, v1
	v_max3_f32 v32, v32, v2, v3
	ds_bpermute_b32 v33, v38, v32
	s_waitcnt lgkmcnt(0)
	v_max_f32_e32 v33, v33, v33
	v_max_f32_e32 v32, v32, v33
	ds_bpermute_b32 v33, v39, v32
	s_waitcnt lgkmcnt(0)
	v_max_f32_e32 v33, v33, v33
	v_max_f32_e32 v32, v32, v33
	v_sub_f32_e32 v33, v76, v32
	v_sub_f32_e32 v34, v77, v32
	v_mul_f32_e32 v33, 0x3fb8aa3b, v33
	v_sub_f32_e32 v35, v78, v32
	v_mul_f32_e32 v34, 0x3fb8aa3b, v34
	v_exp_f32_e32 v33, v33
	v_sub_f32_e32 v48, v79, v32
	v_mul_f32_e32 v35, 0x3fb8aa3b, v35
	v_exp_f32_e32 v34, v34
	v_sub_f32_e32 v49, v88, v32
	v_mul_f32_e32 v48, 0x3fb8aa3b, v48
	v_exp_f32_e32 v35, v35
	v_sub_f32_e32 v50, v89, v32
	v_mul_f32_e32 v49, 0x3fb8aa3b, v49
	v_exp_f32_e32 v48, v48
	v_sub_f32_e32 v51, v90, v32
	v_mul_f32_e32 v50, 0x3fb8aa3b, v50
	v_exp_f32_e32 v49, v49
	v_add_f32_e32 v69, 0, v33
	v_sub_f32_e32 v52, v91, v32
	v_mul_f32_e32 v51, 0x3fb8aa3b, v51
	v_exp_f32_e32 v50, v50
	v_add_f32_e32 v69, v34, v69
	v_sub_f32_e32 v53, v100, v32
	v_mul_f32_e32 v52, 0x3fb8aa3b, v52
	v_exp_f32_e32 v51, v51
	v_add_f32_e32 v69, v35, v69
	v_sub_f32_e32 v54, v101, v32
	v_mul_f32_e32 v53, 0x3fb8aa3b, v53
	v_exp_f32_e32 v52, v52
	v_add_f32_e32 v69, v48, v69
	v_sub_f32_e32 v55, v102, v32
	v_mul_f32_e32 v54, 0x3fb8aa3b, v54
	v_exp_f32_e32 v53, v53
	v_add_f32_e32 v69, v49, v69
	v_sub_f32_e32 v56, v103, v32
	v_mul_f32_e32 v55, 0x3fb8aa3b, v55
	v_exp_f32_e32 v54, v54
	v_add_f32_e32 v69, v50, v69
	v_sub_f32_e32 v57, v104, v32
	v_mul_f32_e32 v56, 0x3fb8aa3b, v56
	v_exp_f32_e32 v55, v55
	v_add_f32_e32 v69, v51, v69
	v_sub_f32_e32 v58, v105, v32
	v_mul_f32_e32 v57, 0x3fb8aa3b, v57
	v_exp_f32_e32 v56, v56
	v_add_f32_e32 v69, v52, v69
	v_sub_f32_e32 v59, v106, v32
	v_mul_f32_e32 v58, 0x3fb8aa3b, v58
	v_exp_f32_e32 v57, v57
	v_add_f32_e32 v69, v53, v69
	v_sub_f32_e32 v60, v107, v32
	v_mul_f32_e32 v59, 0x3fb8aa3b, v59
	v_exp_f32_e32 v58, v58
	v_add_f32_e32 v69, v54, v69
	v_sub_f32_e32 v61, v108, v32
	v_mul_f32_e32 v60, 0x3fb8aa3b, v60
	v_exp_f32_e32 v59, v59
	v_add_f32_e32 v69, v55, v69
	v_sub_f32_e32 v62, v109, v32
	v_mul_f32_e32 v61, 0x3fb8aa3b, v61
	v_exp_f32_e32 v60, v60
; template <bool SAMPLE>
; __device__ __forceinline__ void mem_unit(const Params& p, int l, LAS unsigned char* lds, int unit, int tid, int wave, int lane) {
;     ...
;         mx = fmaxf(mx, __shfl_xor(mx, 16)); mx = fmaxf(mx, __shfl_xor(mx, 32));
;         float den = 0.f;
; #pragma unroll
;         for (int cc = 0; cc < 8; ++cc)
; #pragma unroll
;             for (int tt = 0; tt < 2; ++tt)
; #pragma unroll
;                 for (int e = 0; e < 4; ++e) { const float pe = __expf(S[cc][tt][e] - mx); S[cc][tt][e] = pe; den += pe; }
;         den += __shfl_xor(den, 16); den += __shfl_xor(den, 32);
;         const float rden = 1.f / den;
	v_add_f32_e32 v69, v56, v69
	v_sub_f32_e32 v63, v110, v32
	v_mul_f32_e32 v62, 0x3fb8aa3b, v62
	v_exp_f32_e32 v61, v61
	v_add_f32_e32 v69, v57, v69
	v_sub_f32_e32 v64, v111, v32
	v_mul_f32_e32 v63, 0x3fb8aa3b, v63
	v_exp_f32_e32 v62, v62
	v_add_f32_e32 v69, v58, v69
	v_sub_f32_e32 v65, v112, v32
	v_mul_f32_e32 v64, 0x3fb8aa3b, v64
	v_exp_f32_e32 v63, v63
	v_add_f32_e32 v69, v59, v69
	v_sub_f32_e32 v66, v113, v32
	v_mul_f32_e32 v65, 0x3fb8aa3b, v65
	v_exp_f32_e32 v64, v64
	v_add_f32_e32 v69, v60, v69
	v_sub_f32_e32 v67, v114, v32
	v_mul_f32_e32 v66, 0x3fb8aa3b, v66
	v_exp_f32_e32 v65, v65
	v_add_f32_e32 v69, v61, v69
	v_sub_f32_e32 v68, v115, v32
	v_mul_f32_e32 v67, 0x3fb8aa3b, v67
	v_exp_f32_e32 v66, v66
	v_add_f32_e32 v69, v62, v69
	v_sub_f32_e32 v40, v40, v32
	v_mul_f32_e32 v68, 0x3fb8aa3b, v68
	v_exp_f32_e32 v67, v67
	v_add_f32_e32 v69, v63, v69
	v_sub_f32_e32 v41, v41, v32
	v_mul_f32_e32 v40, 0x3fb8aa3b, v40
	v_exp_f32_e32 v68, v68
	v_add_f32_e32 v69, v64, v69
	v_sub_f32_e32 v42, v42, v32
	v_mul_f32_e32 v41, 0x3fb8aa3b, v41
	v_exp_f32_e32 v40, v40
	v_add_f32_e32 v69, v65, v69
	v_sub_f32_e32 v43, v43, v32
	v_mul_f32_e32 v42, 0x3fb8aa3b, v42
	v_exp_f32_e32 v41, v41
	v_add_f32_e32 v69, v66, v69
	v_sub_f32_e32 v44, v44, v32
	v_mul_f32_e32 v43, 0x3fb8aa3b, v43
	v_exp_f32_e32 v42, v42
	v_add_f32_e32 v69, v67, v69
	v_sub_f32_e32 v45, v45, v32
	v_mul_f32_e32 v44, 0x3fb8aa3b, v44
	v_exp_f32_e32 v43, v43
	v_add_f32_e32 v69, v68, v69
	v_sub_f32_e32 v46, v46, v32
	v_mul_f32_e32 v45, 0x3fb8aa3b, v45
	v_exp_f32_e32 v44, v44
	v_add_f32_e32 v69, v40, v69
	v_sub_f32_e32 v47, v47, v32
	v_mul_f32_e32 v46, 0x3fb8aa3b, v46
	v_exp_f32_e32 v45, v45
	v_add_f32_e32 v69, v41, v69
	v_sub_f32_e32 v28, v28, v32
	v_mul_f32_e32 v47, 0x3fb8aa3b, v47
	v_exp_f32_e32 v46, v46
	v_add_f32_e32 v69, v42, v69
	v_sub_f32_e32 v29, v29, v32
	v_mul_f32_e32 v28, 0x3fb8aa3b, v28
	v_exp_f32_e32 v47, v47
	v_add_f32_e32 v69, v43, v69
	v_exp_f32_e32 v28, v28
	v_add_f32_e32 v69, v44, v69
	v_mul_f32_e32 v29, 0x3fb8aa3b, v29
	v_sub_f32_e32 v30, v30, v32
	v_sub_f32_e32 v24, v24, v32
	v_add_f32_e32 v69, v45, v69
	v_exp_f32_e32 v29, v29
	v_mul_f32_e32 v30, 0x3fb8aa3b, v30
	v_sub_f32_e32 v31, v31, v32
	v_mul_f32_e32 v24, 0x3fb8aa3b, v24
	v_add_f32_e32 v69, v46, v69
	v_exp_f32_e32 v30, v30
	v_mul_f32_e32 v31, 0x3fb8aa3b, v31
	v_exp_f32_e32 v70, v24
	v_sub_f32_e32 v24, v25, v32
	v_add_f32_e32 v69, v47, v69
	v_exp_f32_e32 v31, v31
	v_mul_f32_e32 v24, 0x3fb8aa3b, v24
	v_add_f32_e32 v69, v28, v69
	v_exp_f32_e32 v71, v24
	v_sub_f32_e32 v24, v26, v32
	v_add_f32_e32 v69, v29, v69
	v_mul_f32_e32 v24, 0x3fb8aa3b, v24
	v_add_f32_e32 v69, v30, v69
	v_exp_f32_e32 v72, v24
	v_sub_f32_e32 v24, v27, v32
	v_sub_f32_e32 v20, v20, v32
	v_add_f32_e32 v69, v31, v69
	v_mul_f32_e32 v24, 0x3fb8aa3b, v24
	v_mul_f32_e32 v20, 0x3fb8aa3b, v20
	v_exp_f32_e32 v73, v24
	v_add_f32_e32 v24, v70, v69
	v_exp_f32_e32 v69, v20
	v_sub_f32_e32 v20, v21, v32
	v_mul_f32_e32 v20, 0x3fb8aa3b, v20
	v_exp_f32_e32 v74, v20
	v_sub_f32_e32 v20, v22, v32
	v_sub_f32_e32 v16, v16, v32
	v_mul_f32_e32 v20, 0x3fb8aa3b, v20
	v_mul_f32_e32 v16, 0x3fb8aa3b, v16
	v_add_f32_e32 v24, v71, v24
	v_exp_f32_e32 v75, v20
	v_sub_f32_e32 v20, v23, v32
	v_exp_f32_e32 v77, v16
	v_sub_f32_e32 v16, v17, v32
	v_add_f32_e32 v24, v72, v24
	v_mul_f32_e32 v20, 0x3fb8aa3b, v20
	v_mul_f32_e32 v16, 0x3fb8aa3b, v16
	v_add_f32_e32 v24, v73, v24
	v_exp_f32_e32 v76, v20
	v_exp_f32_e32 v78, v16
	v_sub_f32_e32 v16, v18, v32
	v_sub_f32_e32 v12, v12, v32
	v_add_f32_e32 v20, v69, v24
	v_mul_f32_e32 v16, 0x3fb8aa3b, v16
	v_mul_f32_e32 v12, 0x3fb8aa3b, v12
	v_add_f32_e32 v20, v74, v20
	v_exp_f32_e32 v79, v16
	v_sub_f32_e32 v16, v19, v32
	v_exp_f32_e32 v89, v12
	v_sub_f32_e32 v12, v13, v32
	v_add_f32_e32 v20, v75, v20
	v_mul_f32_e32 v16, 0x3fb8aa3b, v16
	v_mul_f32_e32 v12, 0x3fb8aa3b, v12
	v_add_f32_e32 v20, v76, v20
	v_exp_f32_e32 v88, v16
	v_exp_f32_e32 v90, v12
	v_sub_f32_e32 v12, v14, v32
	v_sub_f32_e32 v8, v8, v32
	v_add_f32_e32 v16, v77, v20
	v_mul_f32_e32 v12, 0x3fb8aa3b, v12
	v_mul_f32_e32 v8, 0x3fb8aa3b, v8
	v_add_f32_e32 v16, v78, v16
	v_exp_f32_e32 v91, v12
	v_sub_f32_e32 v12, v15, v32
	v_exp_f32_e32 v93, v8
	v_sub_f32_e32 v8, v9, v32
	v_add_f32_e32 v16, v79, v16
	v_mul_f32_e32 v12, 0x3fb8aa3b, v12
	v_mul_f32_e32 v8, 0x3fb8aa3b, v8
	v_add_f32_e32 v16, v88, v16
	v_exp_f32_e32 v92, v12
	v_exp_f32_e32 v100, v8
	v_sub_f32_e32 v8, v10, v32
	v_sub_f32_e32 v4, v4, v32
	v_add_f32_e32 v12, v89, v16
	v_mul_f32_e32 v8, 0x3fb8aa3b, v8
	v_mul_f32_e32 v4, 0x3fb8aa3b, v4
	v_add_f32_e32 v12, v90, v12
	v_exp_f32_e32 v101, v8
	v_sub_f32_e32 v8, v11, v32
	v_exp_f32_e32 v103, v4
	v_sub_f32_e32 v4, v5, v32
	v_add_f32_e32 v12, v91, v12
	v_mul_f32_e32 v8, 0x3fb8aa3b, v8
	v_mul_f32_e32 v4, 0x3fb8aa3b, v4
	v_add_f32_e32 v12, v92, v12
	v_exp_f32_e32 v102, v8
	v_exp_f32_e32 v104, v4
	v_sub_f32_e32 v4, v6, v32
	v_sub_f32_e32 v0, v0, v32
	v_add_f32_e32 v8, v93, v12
	v_mul_f32_e32 v4, 0x3fb8aa3b, v4
	v_mul_f32_e32 v0, 0x3fb8aa3b, v0
	v_add_f32_e32 v8, v100, v8
	v_exp_f32_e32 v105, v4
	v_sub_f32_e32 v4, v7, v32
	v_exp_f32_e32 v107, v0
	v_sub_f32_e32 v0, v1, v32
	v_add_f32_e32 v8, v101, v8
	v_mul_f32_e32 v4, 0x3fb8aa3b, v4
	v_mul_f32_e32 v0, 0x3fb8aa3b, v0
	v_add_f32_e32 v8, v102, v8
	v_exp_f32_e32 v106, v4
	v_exp_f32_e32 v108, v0
	v_sub_f32_e32 v0, v2, v32
	v_add_f32_e32 v4, v103, v8
	v_mul_f32_e32 v0, 0x3fb8aa3b, v0
	v_add_f32_e32 v4, v104, v4
	v_exp_f32_e32 v109, v0
	v_sub_f32_e32 v0, v3, v32
	v_add_f32_e32 v4, v105, v4
	v_mul_f32_e32 v0, 0x3fb8aa3b, v0
	v_add_f32_e32 v4, v106, v4
	v_exp_f32_e32 v32, v0
	v_add_f32_e32 v0, v107, v4
	v_add_f32_e32 v0, v108, v0
	v_add_f32_e32 v0, v109, v0
	v_add_f32_e32 v0, v32, v0
	ds_bpermute_b32 v1, v38, v0
	v_cvt_pk_bf16_f32 v24, v33, v34
	v_cvt_pk_bf16_f32 v25, v35, v48
	v_cvt_pk_bf16_f32 v26, v49, v50
	v_cvt_pk_bf16_f32 v27, v51, v52
	s_waitcnt lgkmcnt(0)
; #define LAS __attribute__((address_space(3)))
; __device__ __forceinline__ unsigned pk2(float lo, float hi) { return pg8::cvt_pk_bf16(lo, hi); }
; __device__ __forceinline__ bf16x8 pack8(const float (&o)[8]) { v4u w; w.x = pk2(o[0], o[1]); w.y = pk2(o[2], o[3]); w.z = pk2(o[4], o[5]); w.w = pk2(o[6], o[7]); return __builtin_bit_cast(bf16x8, w); }
; __device__ __forceinline__ v2u vtr(const LAS bf16* p) { return __builtin_bit_cast(v2u, __builtin_amdgcn_ds_read_tr16_b64_v4i16((LAS v4i16_t*)p)); }
; template <bool SAMPLE>
; __device__ __forceinline__ void mem_unit(const Params& p, int l, LAS unsigned char* lds, int unit, int tid, int wave, int lane) {
;     ...
;         den += __shfl_xor(den, 16); den += __shfl_xor(den, 32);
;         const float rden = 1.f / den;
;         bf16x8 pf[8];
; #pragma unroll
;         for (int cc = 0; cc < 8; ++cc) { float t8[8];
; #pragma unroll
;             for (int e = 0; e < 4; ++e) { t8[e] = S[cc][0][e]; t8[4 + e] = S[cc][1][e]; }
;             pf[cc] = pack8(t8); }
; #pragma unroll
;         for (int dt = 0; dt < 8; ++dt) { f32x4 o = (f32x4){0.f, 0.f, 0.f, 0.f};
; #pragma unroll
;             for (int cc = 0; cc < 8; ++cc) { const LAS bf16* vp = Vt + (32 * cc + 4 * kq + (q16 >> 2)) * MEM_VS + 16 * dt + 4 * (q16 & 3);
;                 const v2u lo = vtr(vp), hi = vtr(vp + 16 * MEM_VS);
;                 v4u av; av.x = lo.x; av.y = lo.y; av.z = hi.x; av.w = hi.y;
;                 o = __builtin_amdgcn_mfma_f32_16x16x32_bf16(__builtin_bit_cast(bf16x8, av), pf[cc], o, 0, 0, 0); }
;             if (st) { v2u w; w.x = pk2(o[0] * rden, o[1] * rden); w.y = pk2(o[2] * rden, o[3] * rden);
;                 *(v2u*)(MO + row * 512 + h * 128 + 16 * dt + 4 * kq) = w; } }
	v_add_f32_e32 v0, v0, v1
	ds_bpermute_b32 v1, v39, v0
	v_cvt_pk_bf16_f32 v20, v53, v54
	v_cvt_pk_bf16_f32 v21, v55, v56
	v_cvt_pk_bf16_f32 v22, v57, v58
	v_cvt_pk_bf16_f32 v23, v59, v60
	s_waitcnt lgkmcnt(0)
	v_add_f32_e32 v39, v0, v1
	v_cvt_pk_bf16_f32 v16, v61, v62
	v_cvt_pk_bf16_f32 v17, v63, v64
	v_cvt_pk_bf16_f32 v18, v65, v66
	v_cvt_pk_bf16_f32 v19, v67, v68
	v_cvt_pk_bf16_f32 v12, v40, v41
	v_cvt_pk_bf16_f32 v13, v42, v43
	v_cvt_pk_bf16_f32 v14, v44, v45
	v_cvt_pk_bf16_f32 v15, v46, v47
	v_cvt_pk_bf16_f32 v8, v28, v29
	v_cvt_pk_bf16_f32 v9, v30, v31
	v_cvt_pk_bf16_f32 v10, v70, v71
	v_cvt_pk_bf16_f32 v11, v72, v73
	v_cvt_pk_bf16_f32 v4, v69, v74
	v_cvt_pk_bf16_f32 v5, v75, v76
	v_cvt_pk_bf16_f32 v6, v77, v78
	v_cvt_pk_bf16_f32 v7, v79, v88
	v_cvt_pk_bf16_f32 v0, v89, v90
	v_cvt_pk_bf16_f32 v1, v91, v92
	v_cvt_pk_bf16_f32 v2, v93, v100
	v_cvt_pk_bf16_f32 v3, v101, v102
	v_cvt_pk_bf16_f32 v28, v103, v104
	v_cvt_pk_bf16_f32 v29, v105, v106
	v_cvt_pk_bf16_f32 v30, v107, v108
	v_cvt_pk_bf16_f32 v31, v109, v32
	v_lshlrev_b32_e32 v52, 2, v37
	v_lshrrev_b32_e32 v32, 2, v36
	v_add_u32_e32 v32, v32, v52
	v_lshlrev_b32_e32 v33, 3, v36
	v_and_b32_e32 v33, 24, v33
	v_mul_lo_u32 v32, v32, s30
	v_add3_u32 v38, s90, v33, v32
	ds_read_b64_tr_b16 v[194:195], v38
	ds_read_b64_tr_b16 v[196:197], v38 offset:4352
	ds_read_b64_tr_b16 v[198:199], v38 offset:8704
	ds_read_b64_tr_b16 v[200:201], v38 offset:13056
	ds_read_b64_tr_b16 v[202:203], v38 offset:17408
	ds_read_b64_tr_b16 v[204:205], v38 offset:21760
	ds_read_b64_tr_b16 v[206:207], v38 offset:26112
	ds_read_b64_tr_b16 v[208:209], v38 offset:30464
	ds_read_b64_tr_b16 v[210:211], v38 offset:34816
	ds_read_b64_tr_b16 v[212:213], v38 offset:39168
	s_nop 3
	s_waitcnt lgkmcnt(8)
	v_mfma_f32_16x16x32_bf16 v[32:35], v[194:197], v[24:27], 0
	s_nop 3
	v_div_scale_f32 v53, s[2:3], v39, v39, 1.0
	s_waitcnt lgkmcnt(6)
	v_mfma_f32_16x16x32_bf16 v[32:35], v[198:201], v[20:23], v[32:35]
	s_nop 1
	v_rcp_f32_e32 v37, v53
	s_add_u32 s2, s28, s0
	s_waitcnt lgkmcnt(4)
	v_mfma_f32_16x16x32_bf16 v[32:35], v[202:205], v[16:19], v[32:35]
	ds_read_b64_tr_b16 v[44:45], v38 offset:43520
	ds_read_b64_tr_b16 v[46:47], v38 offset:47872
	v_cmp_gt_i32_e64 s[0:1], 8, v36
	v_fma_f32 v36, -v53, v37, 1.0
	s_waitcnt lgkmcnt(4)
	v_mfma_f32_16x16x32_bf16 v[32:35], v[206:209], v[12:15], v[32:35]
	ds_read_b64_tr_b16 v[48:49], v38 offset:52224
	ds_read_b64_tr_b16 v[50:51], v38 offset:56576
	v_fmac_f32_e32 v37, v36, v37
	v_div_scale_f32 v36, vcc, 1.0, v39, 1.0
	s_waitcnt lgkmcnt(4)
	v_mfma_f32_16x16x32_bf16 v[32:35], v[210:213], v[8:11], v[32:35]
	ds_read_b64_tr_b16 v[40:41], v38 offset:60928
	ds_read_b64_tr_b16 v[42:43], v38 offset:65280
	v_mul_f32_e32 v54, v36, v37
	v_fma_f32 v55, -v53, v54, v36
	s_waitcnt lgkmcnt(4)
	v_mfma_f32_16x16x32_bf16 v[32:35], v[44:47], v[4:7], v[32:35]
	v_fmac_f32_e32 v54, v55, v37
	v_fma_f32 v36, -v53, v54, v36
	s_addc_u32 s3, s29, 0
	s_waitcnt lgkmcnt(2)
	v_mfma_f32_16x16x32_bf16 v[32:35], v[48:51], v[0:3], v[32:35]
	v_div_fmas_f32 v36, v36, v37, v54
	v_div_fixup_f32 v39, v36, v39, 1.0
	v_lshl_add_u64 v[36:37], s[2:3], 0, v[82:83]
	s_waitcnt lgkmcnt(0)
	v_mfma_f32_16x16x32_bf16 v[32:35], v[40:43], v[28:31], v[32:35]
	v_ashrrev_i32_e32 v53, 31, v52
	v_lshl_add_u64 v[36:37], v[52:53], 1, v[36:37]
	s_and_saveexec_b64 s[2:3], s[0:1]
	s_cbranch_execz .LBB0_603
	s_nop 3
	v_mul_f32_e32 v32, v32, v39
	v_mul_f32_e32 v33, v33, v39
	v_cvt_pk_bf16_f32 v32, v32, v33
	v_mul_f32_e32 v33, v34, v39
	v_mul_f32_e32 v34, v35, v39
	v_cvt_pk_bf16_f32 v33, v33, v34
	global_store_dwordx2 v[36:37], v[32:33], off
.LBB0_603:
	s_or_b64 exec, exec, s[2:3]
	s_nop 2
	ds_read_b64_tr_b16 v[186:187], v38 offset:32
	ds_read_b64_tr_b16 v[188:189], v38 offset:4384
	ds_read_b64_tr_b16 v[190:191], v38 offset:8736
	ds_read_b64_tr_b16 v[192:193], v38 offset:13088
	ds_read_b64_tr_b16 v[194:195], v38 offset:17440
	ds_read_b64_tr_b16 v[196:197], v38 offset:21792
	ds_read_b64_tr_b16 v[198:199], v38 offset:26144
	ds_read_b64_tr_b16 v[200:201], v38 offset:30496
	ds_read_b64_tr_b16 v[202:203], v38 offset:34848
	ds_read_b64_tr_b16 v[204:205], v38 offset:39200
	s_nop 5
	s_waitcnt lgkmcnt(8)
	ds_read_b64_tr_b16 v[206:207], v38 offset:43552
	ds_read_b64_tr_b16 v[208:209], v38 offset:47904
	v_mfma_f32_16x16x32_bf16 v[32:35], v[186:189], v[24:27], 0
	s_waitcnt lgkmcnt(8)
	v_mfma_f32_16x16x32_bf16 v[32:35], v[190:193], v[20:23], v[32:35]
	s_nop 1
	s_waitcnt lgkmcnt(6)
	v_mfma_f32_16x16x32_bf16 v[32:35], v[194:197], v[16:19], v[32:35]
	s_nop 1
	s_waitcnt lgkmcnt(4)
	v_mfma_f32_16x16x32_bf16 v[32:35], v[198:201], v[12:15], v[32:35]
	s_nop 1
	s_waitcnt lgkmcnt(2)
	v_mfma_f32_16x16x32_bf16 v[32:35], v[202:205], v[8:11], v[32:35]
	ds_read_b64_tr_b16 v[44:45], v38 offset:52256
	ds_read_b64_tr_b16 v[46:47], v38 offset:56608
	s_waitcnt lgkmcnt(2)
	v_mfma_f32_16x16x32_bf16 v[32:35], v[206:209], v[4:7], v[32:35]
	ds_read_b64_tr_b16 v[40:41], v38 offset:60960
	ds_read_b64_tr_b16 v[42:43], v38 offset:65312
	s_waitcnt lgkmcnt(2)
	v_mfma_f32_16x16x32_bf16 v[32:35], v[44:47], v[0:3], v[32:35]
	s_waitcnt lgkmcnt(0)
	v_mfma_f32_16x16x32_bf16 v[32:35], v[40:43], v[28:31], v[32:35]
	s_and_saveexec_b64 s[2:3], s[0:1]
	s_cbranch_execz .LBB0_605
	s_nop 5
	v_mul_f32_e32 v32, v39, v32
	v_mul_f32_e32 v33, v39, v33
	v_cvt_pk_bf16_f32 v32, v32, v33
	v_mul_f32_e32 v33, v39, v34
	v_mul_f32_e32 v34, v39, v35
	v_cvt_pk_bf16_f32 v33, v33, v34
	global_store_dwordx2 v[36:37], v[32:33], off offset:32
; #define LAS __attribute__((address_space(3)))
; __device__ __forceinline__ unsigned pk2(float lo, float hi) { return pg8::cvt_pk_bf16(lo, hi); }
; __device__ __forceinline__ v2u vtr(const LAS bf16* p) { return __builtin_bit_cast(v2u, __builtin_amdgcn_ds_read_tr16_b64_v4i16((LAS v4i16_t*)p)); }
; template <bool SAMPLE>
; __device__ __forceinline__ void mem_unit(const Params& p, int l, LAS unsigned char* lds, int unit, int tid, int wave, int lane) {
;     ...
; #pragma unroll
;         for (int dt = 0; dt < 8; ++dt) { f32x4 o = (f32x4){0.f, 0.f, 0.f, 0.f};
; #pragma unroll
;             for (int cc = 0; cc < 8; ++cc) { const LAS bf16* vp = Vt + (32 * cc + 4 * kq + (q16 >> 2)) * MEM_VS + 16 * dt + 4 * (q16 & 3);
;                 const v2u lo = vtr(vp), hi = vtr(vp + 16 * MEM_VS);
;                 v4u av; av.x = lo.x; av.y = lo.y; av.z = hi.x; av.w = hi.y;
;                 o = __builtin_amdgcn_mfma_f32_16x16x32_bf16(__builtin_bit_cast(bf16x8, av), pf[cc], o, 0, 0, 0); }
;             if (st) { v2u w; w.x = pk2(o[0] * rden, o[1] * rden); w.y = pk2(o[2] * rden, o[3] * rden);
;                 *(v2u*)(MO + row * 512 + h * 128 + 16 * dt + 4 * kq) = w; } }
.LBB0_605:
	s_or_b64 exec, exec, s[2:3]
	s_nop 4
	ds_read_b64_tr_b16 v[186:187], v38 offset:64
	ds_read_b64_tr_b16 v[188:189], v38 offset:4416
	ds_read_b64_tr_b16 v[190:191], v38 offset:8768
	ds_read_b64_tr_b16 v[192:193], v38 offset:13120
	ds_read_b64_tr_b16 v[194:195], v38 offset:17472
	ds_read_b64_tr_b16 v[196:197], v38 offset:21824
	ds_read_b64_tr_b16 v[198:199], v38 offset:26176
	ds_read_b64_tr_b16 v[200:201], v38 offset:30528
	ds_read_b64_tr_b16 v[202:203], v38 offset:34880
	ds_read_b64_tr_b16 v[204:205], v38 offset:39232
	s_nop 5
	s_waitcnt lgkmcnt(8)
	ds_read_b64_tr_b16 v[206:207], v38 offset:43584
	ds_read_b64_tr_b16 v[208:209], v38 offset:47936
	v_mfma_f32_16x16x32_bf16 v[32:35], v[186:189], v[24:27], 0
	s_waitcnt lgkmcnt(8)
	v_mfma_f32_16x16x32_bf16 v[32:35], v[190:193], v[20:23], v[32:35]
	s_nop 1
	s_waitcnt lgkmcnt(6)
	v_mfma_f32_16x16x32_bf16 v[32:35], v[194:197], v[16:19], v[32:35]
	s_nop 1
	s_waitcnt lgkmcnt(4)
	v_mfma_f32_16x16x32_bf16 v[32:35], v[198:201], v[12:15], v[32:35]
	s_nop 1
	s_waitcnt lgkmcnt(2)
	v_mfma_f32_16x16x32_bf16 v[32:35], v[202:205], v[8:11], v[32:35]
	ds_read_b64_tr_b16 v[44:45], v38 offset:52288
	ds_read_b64_tr_b16 v[46:47], v38 offset:56640
	s_waitcnt lgkmcnt(2)
	v_mfma_f32_16x16x32_bf16 v[32:35], v[206:209], v[4:7], v[32:35]
	ds_read_b64_tr_b16 v[40:41], v38 offset:60992
	ds_read_b64_tr_b16 v[42:43], v38 offset:65344
	s_waitcnt lgkmcnt(2)
	v_mfma_f32_16x16x32_bf16 v[32:35], v[44:47], v[0:3], v[32:35]
	s_waitcnt lgkmcnt(0)
	v_mfma_f32_16x16x32_bf16 v[32:35], v[40:43], v[28:31], v[32:35]
	s_and_saveexec_b64 s[2:3], s[0:1]
	s_cbranch_execz .LBB0_607
	s_nop 5
	v_mul_f32_e32 v32, v39, v32
	v_mul_f32_e32 v33, v39, v33
	v_cvt_pk_bf16_f32 v32, v32, v33
	v_mul_f32_e32 v33, v39, v34
	v_mul_f32_e32 v34, v39, v35
	v_cvt_pk_bf16_f32 v33, v33, v34
	global_store_dwordx2 v[36:37], v[32:33], off offset:64
.LBB0_607:
	s_or_b64 exec, exec, s[2:3]
	s_nop 4
	ds_read_b64_tr_b16 v[186:187], v38 offset:96
	ds_read_b64_tr_b16 v[188:189], v38 offset:4448
	ds_read_b64_tr_b16 v[190:191], v38 offset:8800
	ds_read_b64_tr_b16 v[192:193], v38 offset:13152
	ds_read_b64_tr_b16 v[194:195], v38 offset:17504
	ds_read_b64_tr_b16 v[196:197], v38 offset:21856
	ds_read_b64_tr_b16 v[198:199], v38 offset:26208
	ds_read_b64_tr_b16 v[200:201], v38 offset:30560
	ds_read_b64_tr_b16 v[202:203], v38 offset:34912
	ds_read_b64_tr_b16 v[204:205], v38 offset:39264
	s_nop 5
	s_waitcnt lgkmcnt(8)
	ds_read_b64_tr_b16 v[206:207], v38 offset:43616
	ds_read_b64_tr_b16 v[208:209], v38 offset:47968
	v_mfma_f32_16x16x32_bf16 v[32:35], v[186:189], v[24:27], 0
	s_waitcnt lgkmcnt(8)
	v_mfma_f32_16x16x32_bf16 v[32:35], v[190:193], v[20:23], v[32:35]
	s_nop 1
	s_waitcnt lgkmcnt(6)
	v_mfma_f32_16x16x32_bf16 v[32:35], v[194:197], v[16:19], v[32:35]
	s_nop 1
	s_waitcnt lgkmcnt(4)
	v_mfma_f32_16x16x32_bf16 v[32:35], v[198:201], v[12:15], v[32:35]
	s_nop 1
	s_waitcnt lgkmcnt(2)
	v_mfma_f32_16x16x32_bf16 v[32:35], v[202:205], v[8:11], v[32:35]
	ds_read_b64_tr_b16 v[44:45], v38 offset:52320
	ds_read_b64_tr_b16 v[46:47], v38 offset:56672
	s_waitcnt lgkmcnt(2)
	v_mfma_f32_16x16x32_bf16 v[32:35], v[206:209], v[4:7], v[32:35]
	ds_read_b64_tr_b16 v[40:41], v38 offset:61024
	ds_read_b64_tr_b16 v[42:43], v38 offset:65376
	s_waitcnt lgkmcnt(2)
	v_mfma_f32_16x16x32_bf16 v[32:35], v[44:47], v[0:3], v[32:35]
	s_waitcnt lgkmcnt(0)
	v_mfma_f32_16x16x32_bf16 v[32:35], v[40:43], v[28:31], v[32:35]
	s_and_saveexec_b64 s[2:3], s[0:1]
	s_cbranch_execz .LBB0_609
	s_nop 5
	v_mul_f32_e32 v32, v39, v32
	v_mul_f32_e32 v33, v39, v33
	v_cvt_pk_bf16_f32 v32, v32, v33
	v_mul_f32_e32 v33, v39, v34
	v_mul_f32_e32 v34, v39, v35
	v_cvt_pk_bf16_f32 v33, v33, v34
	global_store_dwordx2 v[36:37], v[32:33], off offset:96
.LBB0_609:
	s_or_b64 exec, exec, s[2:3]
	s_nop 4
	ds_read_b64_tr_b16 v[186:187], v38 offset:128
	ds_read_b64_tr_b16 v[188:189], v38 offset:4480
	ds_read_b64_tr_b16 v[190:191], v38 offset:8832
	ds_read_b64_tr_b16 v[192:193], v38 offset:13184
	ds_read_b64_tr_b16 v[194:195], v38 offset:17536
	ds_read_b64_tr_b16 v[196:197], v38 offset:21888
	ds_read_b64_tr_b16 v[198:199], v38 offset:26240
	ds_read_b64_tr_b16 v[200:201], v38 offset:30592
	ds_read_b64_tr_b16 v[202:203], v38 offset:34944
	ds_read_b64_tr_b16 v[204:205], v38 offset:39296
	s_nop 5
	s_waitcnt lgkmcnt(8)
	ds_read_b64_tr_b16 v[206:207], v38 offset:43648
	ds_read_b64_tr_b16 v[208:209], v38 offset:48000
	v_mfma_f32_16x16x32_bf16 v[32:35], v[186:189], v[24:27], 0
	s_waitcnt lgkmcnt(8)
	v_mfma_f32_16x16x32_bf16 v[32:35], v[190:193], v[20:23], v[32:35]
	s_nop 1
	s_waitcnt lgkmcnt(6)
	v_mfma_f32_16x16x32_bf16 v[32:35], v[194:197], v[16:19], v[32:35]
	s_nop 1
	s_waitcnt lgkmcnt(4)
	v_mfma_f32_16x16x32_bf16 v[32:35], v[198:201], v[12:15], v[32:35]
	s_nop 1
	s_waitcnt lgkmcnt(2)
	v_mfma_f32_16x16x32_bf16 v[32:35], v[202:205], v[8:11], v[32:35]
	ds_read_b64_tr_b16 v[44:45], v38 offset:52352
	ds_read_b64_tr_b16 v[46:47], v38 offset:56704
	s_waitcnt lgkmcnt(2)
	v_mfma_f32_16x16x32_bf16 v[32:35], v[206:209], v[4:7], v[32:35]
	ds_read_b64_tr_b16 v[40:41], v38 offset:61056
	ds_read_b64_tr_b16 v[42:43], v38 offset:65408
	s_waitcnt lgkmcnt(2)
	v_mfma_f32_16x16x32_bf16 v[32:35], v[44:47], v[0:3], v[32:35]
	s_waitcnt lgkmcnt(0)
	v_mfma_f32_16x16x32_bf16 v[32:35], v[40:43], v[28:31], v[32:35]
	s_and_saveexec_b64 s[2:3], s[0:1]
	s_cbranch_execz .LBB0_611
	s_nop 5
	v_mul_f32_e32 v32, v39, v32
	v_mul_f32_e32 v33, v39, v33
	v_cvt_pk_bf16_f32 v32, v32, v33
	v_mul_f32_e32 v33, v39, v34
	v_mul_f32_e32 v34, v39, v35
	v_cvt_pk_bf16_f32 v33, v33, v34
	global_store_dwordx2 v[36:37], v[32:33], off offset:128
; #define LAS __attribute__((address_space(3)))
; __device__ __forceinline__ unsigned pk2(float lo, float hi) { return pg8::cvt_pk_bf16(lo, hi); }
; __device__ __forceinline__ v2u vtr(const LAS bf16* p) { return __builtin_bit_cast(v2u, __builtin_amdgcn_ds_read_tr16_b64_v4i16((LAS v4i16_t*)p)); }
; template <bool SAMPLE>
; __device__ __forceinline__ void mem_unit(const Params& p, int l, LAS unsigned char* lds, int unit, int tid, int wave, int lane) {
;     ...
; #pragma unroll
;         for (int dt = 0; dt < 8; ++dt) { f32x4 o = (f32x4){0.f, 0.f, 0.f, 0.f};
; #pragma unroll
;             for (int cc = 0; cc < 8; ++cc) { const LAS bf16* vp = Vt + (32 * cc + 4 * kq + (q16 >> 2)) * MEM_VS + 16 * dt + 4 * (q16 & 3);
;                 const v2u lo = vtr(vp), hi = vtr(vp + 16 * MEM_VS);
;                 v4u av; av.x = lo.x; av.y = lo.y; av.z = hi.x; av.w = hi.y;
;                 o = __builtin_amdgcn_mfma_f32_16x16x32_bf16(__builtin_bit_cast(bf16x8, av), pf[cc], o, 0, 0, 0); }
;             if (st) { v2u w; w.x = pk2(o[0] * rden, o[1] * rden); w.y = pk2(o[2] * rden, o[3] * rden);
;                 *(v2u*)(MO + row * 512 + h * 128 + 16 * dt + 4 * kq) = w; } }
.LBB0_611:
	s_or_b64 exec, exec, s[2:3]
	s_nop 4
	ds_read_b64_tr_b16 v[186:187], v38 offset:160
	ds_read_b64_tr_b16 v[188:189], v38 offset:4512
	ds_read_b64_tr_b16 v[190:191], v38 offset:8864
	ds_read_b64_tr_b16 v[192:193], v38 offset:13216
	ds_read_b64_tr_b16 v[194:195], v38 offset:17568
	ds_read_b64_tr_b16 v[196:197], v38 offset:21920
	ds_read_b64_tr_b16 v[198:199], v38 offset:26272
	ds_read_b64_tr_b16 v[200:201], v38 offset:30624
	ds_read_b64_tr_b16 v[202:203], v38 offset:34976
	ds_read_b64_tr_b16 v[204:205], v38 offset:39328
	s_nop 5
	s_waitcnt lgkmcnt(8)
	ds_read_b64_tr_b16 v[206:207], v38 offset:43680
	ds_read_b64_tr_b16 v[208:209], v38 offset:48032
	v_mfma_f32_16x16x32_bf16 v[32:35], v[186:189], v[24:27], 0
	s_waitcnt lgkmcnt(8)
	v_mfma_f32_16x16x32_bf16 v[32:35], v[190:193], v[20:23], v[32:35]
	s_nop 1
	s_waitcnt lgkmcnt(6)
	v_mfma_f32_16x16x32_bf16 v[32:35], v[194:197], v[16:19], v[32:35]
	s_nop 1
	s_waitcnt lgkmcnt(4)
	v_mfma_f32_16x16x32_bf16 v[32:35], v[198:201], v[12:15], v[32:35]
	s_nop 1
	s_waitcnt lgkmcnt(2)
	v_mfma_f32_16x16x32_bf16 v[32:35], v[202:205], v[8:11], v[32:35]
	ds_read_b64_tr_b16 v[44:45], v38 offset:52384
	ds_read_b64_tr_b16 v[46:47], v38 offset:56736
	s_waitcnt lgkmcnt(2)
	v_mfma_f32_16x16x32_bf16 v[32:35], v[206:209], v[4:7], v[32:35]
	ds_read_b64_tr_b16 v[40:41], v38 offset:61088
	ds_read_b64_tr_b16 v[42:43], v38 offset:65440
	s_waitcnt lgkmcnt(2)
	v_mfma_f32_16x16x32_bf16 v[32:35], v[44:47], v[0:3], v[32:35]
	s_waitcnt lgkmcnt(0)
	v_mfma_f32_16x16x32_bf16 v[32:35], v[40:43], v[28:31], v[32:35]
	s_and_saveexec_b64 s[2:3], s[0:1]
	s_cbranch_execz .LBB0_613
	s_nop 5
	v_mul_f32_e32 v32, v39, v32
	v_mul_f32_e32 v33, v39, v33
	v_cvt_pk_bf16_f32 v32, v32, v33
	v_mul_f32_e32 v33, v39, v34
	v_mul_f32_e32 v34, v39, v35
	v_cvt_pk_bf16_f32 v33, v33, v34
	global_store_dwordx2 v[36:37], v[32:33], off offset:160
.LBB0_613:
	s_or_b64 exec, exec, s[2:3]
	s_nop 4
	ds_read_b64_tr_b16 v[186:187], v38 offset:192
	ds_read_b64_tr_b16 v[188:189], v38 offset:4544
	ds_read_b64_tr_b16 v[190:191], v38 offset:8896
	ds_read_b64_tr_b16 v[192:193], v38 offset:13248
	ds_read_b64_tr_b16 v[194:195], v38 offset:17600
	ds_read_b64_tr_b16 v[196:197], v38 offset:21952
	ds_read_b64_tr_b16 v[198:199], v38 offset:26304
	ds_read_b64_tr_b16 v[200:201], v38 offset:30656
	ds_read_b64_tr_b16 v[202:203], v38 offset:35008
	ds_read_b64_tr_b16 v[204:205], v38 offset:39360
	s_nop 5
	s_waitcnt lgkmcnt(8)
	ds_read_b64_tr_b16 v[206:207], v38 offset:43712
	ds_read_b64_tr_b16 v[208:209], v38 offset:48064
	v_mfma_f32_16x16x32_bf16 v[32:35], v[186:189], v[24:27], 0
	s_waitcnt lgkmcnt(8)
	v_mfma_f32_16x16x32_bf16 v[32:35], v[190:193], v[20:23], v[32:35]
	s_nop 1
	s_waitcnt lgkmcnt(6)
	v_mfma_f32_16x16x32_bf16 v[32:35], v[194:197], v[16:19], v[32:35]
	s_nop 1
	s_waitcnt lgkmcnt(4)
	v_mfma_f32_16x16x32_bf16 v[32:35], v[198:201], v[12:15], v[32:35]
	s_nop 1
	s_waitcnt lgkmcnt(2)
	v_mfma_f32_16x16x32_bf16 v[32:35], v[202:205], v[8:11], v[32:35]
	ds_read_b64_tr_b16 v[44:45], v38 offset:52416
	ds_read_b64_tr_b16 v[46:47], v38 offset:56768
	s_waitcnt lgkmcnt(2)
	v_mfma_f32_16x16x32_bf16 v[32:35], v[206:209], v[4:7], v[32:35]
	ds_read_b64_tr_b16 v[40:41], v38 offset:61120
	ds_read_b64_tr_b16 v[42:43], v38 offset:65472
	s_waitcnt lgkmcnt(2)
	v_mfma_f32_16x16x32_bf16 v[32:35], v[44:47], v[0:3], v[32:35]
	s_waitcnt lgkmcnt(0)
	v_mfma_f32_16x16x32_bf16 v[32:35], v[40:43], v[28:31], v[32:35]
	s_and_saveexec_b64 s[2:3], s[0:1]
	s_cbranch_execz .LBB0_615
	s_nop 5
	v_mul_f32_e32 v32, v39, v32
	v_mul_f32_e32 v33, v39, v33
	v_cvt_pk_bf16_f32 v32, v32, v33
	v_mul_f32_e32 v33, v39, v34
	v_mul_f32_e32 v34, v39, v35
	v_cvt_pk_bf16_f32 v33, v33, v34
	global_store_dwordx2 v[36:37], v[32:33], off offset:192

; template <bool SAMPLE>
; __device__ __forceinline__ void mem_unit(const Params& p, int l, LAS unsigned char* lds, int unit, int tid, int wave, int lane) {
;     ...
;     __syncthreads();
.LBB0_618:
	s_nop 0
	s_nop 0
	s_nop 0
	s_nop 0
	s_nop 0
	s_nop 0
	s_nop 0
	s_nop 0
	s_mov_b64 s[0:1], 0
	s_barrier

; __device__ __forceinline__ void unpack8(const v4u w, float (&o)[8]) { o[0] = bflo(w.x); o[1] = bfhi(w.x); o[2] = bflo(w.y); o[3] = bfhi(w.y); o[4] = bflo(w.z); o[5] = bfhi(w.z); o[6] = bflo(w.w); o[7] = bfhi(w.w); }
; template <bool SAMPLE>
; __device__ __forceinline__ void mem_unit(const Params& p, int l, LAS unsigned char* lds, int unit, int tid, int wave, int lane) {
;     ...
;       for (int qq = 0; qq < (SAMPLE ? 1 : 4); ++qq) {
;         int q16 = lane & 15, kq = lane >> 4; asm volatile("" : "+v"(q16), "+v"(kq));
;         size_t row; bool st;
;         if (!SAMPLE) { row = (size_t)b * 8192 + (qt * 4 + qq) * 128 + 16 * wave + q16; st = true; } else { row = (size_t)MP + 8 * b + (q16 & 7); st = q16 < 8; }
;         bf16x8 qf[4];
;         {
;             float qv[4][8]; float ss = 0.f;
; #pragma unroll
;             for (int dc = 0; dc < 4; ++dc) { unpack8(*(const v4u*)(MQ + row * 512 + h * 128 + 32 * dc + 8 * kq), qv[dc]);
.LBB0_630:
	s_and_b32 s0, s34, 15
	s_lshl_b32 s10, s0, 9
	s_lshl_b64 s[8:9], s[2:3], 13
	s_lshl_b32 s2, s36, 1
	s_add_u32 s0, s64, s2
	s_addc_u32 s1, s65, 0
	v_xor_b32_e32 v0, 16, v99
	s_add_u32 s2, s28, s2
	v_cmp_lt_i32_e32 vcc, v0, v92
	s_addc_u32 s3, s29, 0
	s_add_u32 s8, s6, s8
	v_cndmask_b32_e32 v0, v99, v0, vcc
	v_lshlrev_b32_e32 v82, 2, v0
	v_xor_b32_e32 v0, 32, v99
	v_cmp_lt_i32_e32 vcc, v0, v92
	s_addc_u32 s9, s7, s9
	s_add_u32 s10, s8, s10
	v_cndmask_b32_e32 v0, v99, v0, vcc
	v_lshlrev_b32_e32 v100, 2, v0
	s_addc_u32 s18, s9, 0
	s_mov_b64 s[8:9], 0
	s_waitcnt lgkmcnt(0)
	s_barrier
	s_mov_b32 s100, 0
.LBB0_631:
	v_mov_b32_e32 v90, v94
	v_mov_b32_e32 v92, v95
	s_add_u32 s16, s10, s8
	s_addc_u32 s17, s18, s9
	v_ashrrev_i32_e32 v91, 31, v90
	v_lshl_add_u64 v[0:1], s[16:17], 0, v[90:91]
	v_lshlrev_b32_e32 v8, 3, v92
	v_lshlrev_b64 v[88:89], 10, v[0:1]
	v_ashrrev_i32_e32 v9, 31, v8
	v_lshl_add_u64 v[10:11], s[0:1], 0, v[88:89]
	v_lshlrev_b32_e32 v2, 4, v92
	v_mul_lo_u32 v3, v90, s30
	v_lshl_add_u64 v[24:25], v[8:9], 2, s[46:47]
	v_lshl_add_u64 v[20:21], v[8:9], 1, v[10:11]
	v_add3_u32 v91, 0, v2, v3
	global_load_dwordx4 v[0:3], v[24:25], off offset:16
	global_load_dwordx4 v[4:7], v[24:25], off
	s_cmp_lg_u32 s100, 0
	s_cbranch_scc1 .Lqpf_have_0
	global_load_dwordx4 v[234:237], v[20:21], off
	global_load_dwordx4 v[242:245], v[20:21], off offset:64
	global_load_dwordx4 v[246:249], v[20:21], off offset:128
	global_load_dwordx4 v[250:253], v[20:21], off offset:192
	s_waitcnt vmcnt(0)
	s_branch .Lqpf_go_0

; __device__ __forceinline__ void unpack8(const v4u w, float (&o)[8]) { o[0] = bflo(w.x); o[1] = bfhi(w.x); o[2] = bflo(w.y); o[3] = bfhi(w.y); o[4] = bflo(w.z); o[5] = bfhi(w.z); o[6] = bflo(w.w); o[7] = bfhi(w.w); }
; __device__ __forceinline__ bf16x8 pack8(const float (&o)[8]) { v4u w; w.x = pk2(o[0], o[1]); w.y = pk2(o[2], o[3]); w.z = pk2(o[4], o[5]); w.w = pk2(o[6], o[7]); return __builtin_bit_cast(bf16x8, w); }
; template <bool SAMPLE>
; __device__ __forceinline__ void mem_unit(const Params& p, int l, LAS unsigned char* lds, int unit, int tid, int wave, int lane) {
;     ...
;             float qv[4][8]; float ss = 0.f;
; #pragma unroll
;             for (int dc = 0; dc < 4; ++dc) { unpack8(*(const v4u*)(MQ + row * 512 + h * 128 + 32 * dc + 8 * kq), qv[dc]);
; #pragma unroll
;                 for (int e = 0; e < 8; ++e) ss += qv[dc][e] * qv[dc][e]; }
;             ss += __shfl_xor(ss, 16); ss += __shfl_xor(ss, 32);
;             const float rs = rsqrtf(ss * (1.f / 128.f) + EPS) * 0.08838834764831845f;
; #pragma unroll
;             for (int dc = 0; dc < 4; ++dc) { float qg[8]; pg8::ld8f(p.in[I_MQG] + l * 128 + 32 * dc + 8 * kq, qg);
; #pragma unroll
;                 for (int e = 0; e < 8; ++e) qv[dc][e] *= rs * qg[e];
;                 qf[dc] = pack8(qv[dc]); }
.Lqpf_go_0:
	s_mov_b32 s98, 0x20000
	s_mov_b32 s99, 0
	s_mov_b32 s100, 1
	v_lshl_add_u64 v[230:231], v[20:21], 0, s[98:99]
	v_mov_b32_e32 v8, v234
	v_mov_b32_e32 v9, v235
	v_mov_b32_e32 v10, v236
	v_mov_b32_e32 v11, v237
	v_mov_b32_e32 v12, v242
	v_mov_b32_e32 v13, v243
	v_mov_b32_e32 v14, v244
	v_mov_b32_e32 v15, v245
	v_mov_b32_e32 v16, v246
	v_mov_b32_e32 v17, v247
	v_mov_b32_e32 v18, v248
	v_mov_b32_e32 v19, v249
	v_mov_b32_e32 v20, v250
	v_mov_b32_e32 v21, v251
	v_mov_b32_e32 v22, v252
	v_mov_b32_e32 v23, v253
	v_lshlrev_b32_e32 v92, 2, v92
	v_ashrrev_i32_e32 v93, 31, v92
	s_add_u32 s8, s8, 0x80
	s_addc_u32 s9, s9, 0
	s_cmpk_lg_i32 s8, 0x200
	s_waitcnt vmcnt(0)
	v_and_b32_e32 v31, 0xffff0000, v8
	v_lshlrev_b32_e32 v30, 16, v8
	v_mul_f32_e32 v50, v31, v31
	v_lshlrev_b32_e32 v32, 16, v9
	v_fmac_f32_e32 v50, v30, v30
	v_and_b32_e32 v33, 0xffff0000, v9
	v_fmac_f32_e32 v50, v32, v32
	v_lshlrev_b32_e32 v34, 16, v10
	v_fmac_f32_e32 v50, v33, v33
	v_and_b32_e32 v35, 0xffff0000, v10
	v_fmac_f32_e32 v50, v34, v34
	v_lshlrev_b32_e32 v36, 16, v11
	v_fmac_f32_e32 v50, v35, v35
	v_and_b32_e32 v37, 0xffff0000, v11
	v_fmac_f32_e32 v50, v36, v36
	s_waitcnt vmcnt(2)
	v_lshlrev_b32_e32 v38, 16, v12
	v_fmac_f32_e32 v50, v37, v37
	v_and_b32_e32 v39, 0xffff0000, v12
	v_fmac_f32_e32 v50, v38, v38
	v_lshlrev_b32_e32 v40, 16, v13
	v_fmac_f32_e32 v50, v39, v39
	v_and_b32_e32 v41, 0xffff0000, v13
	v_fmac_f32_e32 v50, v40, v40
	v_lshlrev_b32_e32 v42, 16, v14
	v_fmac_f32_e32 v50, v41, v41
	v_and_b32_e32 v43, 0xffff0000, v14
	v_fmac_f32_e32 v50, v42, v42
	v_lshlrev_b32_e32 v44, 16, v15
	v_fmac_f32_e32 v50, v43, v43
	v_and_b32_e32 v45, 0xffff0000, v15
	v_fmac_f32_e32 v50, v44, v44
	s_waitcnt vmcnt(1)
	v_lshlrev_b32_e32 v46, 16, v16
	v_fmac_f32_e32 v50, v45, v45
	v_and_b32_e32 v16, 0xffff0000, v16
	v_fmac_f32_e32 v50, v46, v46
	v_lshlrev_b32_e32 v47, 16, v17
	v_fmac_f32_e32 v50, v16, v16
	v_and_b32_e32 v17, 0xffff0000, v17
	v_fmac_f32_e32 v50, v47, v47
	v_lshlrev_b32_e32 v48, 16, v18
	v_fmac_f32_e32 v50, v17, v17
	v_and_b32_e32 v18, 0xffff0000, v18
	v_fmac_f32_e32 v50, v48, v48
	v_lshlrev_b32_e32 v49, 16, v19
	v_fmac_f32_e32 v50, v18, v18
	v_and_b32_e32 v19, 0xffff0000, v19
	s_waitcnt vmcnt(0)
	v_and_b32_e32 v26, 0xffff0000, v20
	v_lshlrev_b32_e32 v27, 16, v20
	v_fmac_f32_e32 v50, v49, v49
	v_pk_mul_f32 v[8:9], v[26:27], v[26:27]
	v_fmac_f32_e32 v50, v19, v19
	v_and_b32_e32 v20, 0xffff0000, v21
	v_lshlrev_b32_e32 v21, 16, v21
	v_add_f32_e32 v9, v9, v50
	v_pk_mul_f32 v[10:11], v[20:21], v[20:21]
	v_add_f32_e32 v8, v8, v9
	v_and_b32_e32 v28, 0xffff0000, v22
	v_lshlrev_b32_e32 v29, 16, v22
	v_add_f32_e32 v8, v11, v8
	v_pk_mul_f32 v[12:13], v[28:29], v[28:29]
	v_add_f32_e32 v8, v10, v8
	v_and_b32_e32 v22, 0xffff0000, v23
	v_lshlrev_b32_e32 v23, 16, v23
	v_add_f32_e32 v8, v13, v8
	v_pk_mul_f32 v[14:15], v[22:23], v[22:23]
	v_add_f32_e32 v8, v12, v8
	v_add_f32_e32 v8, v15, v8
	v_add_f32_e32 v8, v14, v8
	ds_bpermute_b32 v9, v82, v8
	s_waitcnt lgkmcnt(0)
	v_add_f32_e32 v8, v8, v9
	ds_bpermute_b32 v9, v100, v8
	s_waitcnt lgkmcnt(0)
	v_add_f32_e32 v8, v8, v9
	v_fmamk_f32 v8, v8, 0x3c000000, v98
	v_mul_f32_e32 v9, 0x4b800000, v8
	v_cmp_gt_f32_e32 vcc, s31, v8
	s_nop 1
	v_cndmask_b32_e32 v8, v8, v9, vcc
	v_rsq_f32_e32 v8, v8
	s_nop 0
	v_mul_f32_e32 v9, 0x45800000, v8
	v_cndmask_b32_e32 v8, v8, v9, vcc
	v_mul_f32_e32 v50, 0x3db504f3, v8
	v_mul_f32_e32 v4, v4, v50
	v_mul_f32_e32 v5, v5, v50
	v_mul_f32_e32 v6, v6, v50
	v_mul_f32_e32 v7, v7, v50
	v_mul_f32_e32 v0, v0, v50
	v_mul_f32_e32 v1, v1, v50
	v_mul_f32_e32 v2, v2, v50
	v_mul_f32_e32 v3, v3, v50
	v_mul_f32_e32 v4, v4, v30
	v_mul_f32_e32 v5, v5, v31
	v_mul_f32_e32 v6, v6, v32
	v_mul_f32_e32 v7, v7, v33
	v_mul_f32_e32 v0, v0, v34
	v_mul_f32_e32 v1, v1, v35
	v_mul_f32_e32 v2, v2, v36
	v_mul_f32_e32 v3, v3, v37
	v_cvt_pk_bf16_f32 v8, v4, v5
	v_cvt_pk_bf16_f32 v9, v6, v7
	v_cvt_pk_bf16_f32 v10, v0, v1
	v_cvt_pk_bf16_f32 v11, v2, v3
	global_load_dwordx4 v[0:3], v[24:25], off offset:128
	global_load_dwordx4 v[4:7], v[24:25], off offset:144
	s_waitcnt vmcnt(1)
	v_mul_f32_e32 v0, v0, v50
	v_mul_f32_e32 v1, v1, v50
	v_mul_f32_e32 v2, v2, v50
	v_mul_f32_e32 v3, v3, v50
	s_waitcnt vmcnt(0)
	v_mul_f32_e32 v4, v4, v50
	v_mul_f32_e32 v5, v5, v50
	v_mul_f32_e32 v6, v6, v50
	v_mul_f32_e32 v7, v7, v50
	v_mul_f32_e32 v0, v0, v38
	v_mul_f32_e32 v1, v1, v39
	v_mul_f32_e32 v2, v2, v40
	v_mul_f32_e32 v3, v3, v41
	v_mul_f32_e32 v4, v4, v42
	v_mul_f32_e32 v5, v5, v43
	v_mul_f32_e32 v6, v6, v44
	v_mul_f32_e32 v7, v7, v45
	v_cvt_pk_bf16_f32 v12, v0, v1
	v_cvt_pk_bf16_f32 v13, v2, v3
	v_cvt_pk_bf16_f32 v14, v4, v5
	v_cvt_pk_bf16_f32 v15, v6, v7
	global_load_dwordx4 v[0:3], v[24:25], off offset:256
	global_load_dwordx4 v[4:7], v[24:25], off offset:272
	s_waitcnt vmcnt(1)
	v_mul_f32_e32 v0, v0, v50
	v_mul_f32_e32 v1, v1, v50
	v_mul_f32_e32 v2, v2, v50
	v_mul_f32_e32 v3, v3, v50
	s_waitcnt vmcnt(0)
	v_mul_f32_e32 v4, v4, v50
	v_mul_f32_e32 v5, v5, v50
	v_mul_f32_e32 v6, v6, v50
	v_mul_f32_e32 v7, v7, v50
	v_mul_f32_e32 v0, v0, v46
	v_mul_f32_e32 v1, v1, v16
	v_mul_f32_e32 v2, v2, v47
	v_mul_f32_e32 v3, v3, v17
	v_mul_f32_e32 v16, v4, v48
	v_mul_f32_e32 v17, v5, v18
	v_mul_f32_e32 v18, v6, v49
	v_mul_f32_e32 v7, v7, v19
	v_cvt_pk_bf16_f32 v4, v0, v1
	v_cvt_pk_bf16_f32 v5, v2, v3
	v_cvt_pk_bf16_f32 v6, v16, v17
	v_cvt_pk_bf16_f32 v7, v18, v7
	global_load_dwordx4 v[0:3], v[24:25], off offset:384
	global_load_dwordx4 v[16:19], v[24:25], off offset:400
	s_waitcnt vmcnt(1)
	v_mul_f32_e32 v0, v0, v50
	v_mul_f32_e32 v1, v1, v50
	v_mul_f32_e32 v2, v2, v50
	v_mul_f32_e32 v3, v3, v50
	s_waitcnt vmcnt(0)
; #define LAS __attribute__((address_space(3)))
; __device__ __forceinline__ void unpack8(const v4u w, float (&o)[8]) { o[0] = bflo(w.x); o[1] = bfhi(w.x); o[2] = bflo(w.y); o[3] = bfhi(w.y); o[4] = bflo(w.z); o[5] = bfhi(w.z); o[6] = bflo(w.w); o[7] = bfhi(w.w); }
; template <bool SAMPLE>
; __device__ __forceinline__ void mem_unit(const Params& p, int l, LAS unsigned char* lds, int unit, int tid, int wave, int lane) {
;     ...
;             for (int dc = 0; dc < 4; ++dc) { unpack8(*(const v4u*)(MQ + row * 512 + h * 128 + 32 * dc + 8 * kq), qv[dc]);
;     ...
;         f32x4 S[8][2]; float mx = -INFINITY;
; #pragma unroll
;         for (int cc = 0; cc < 8; ++cc)
; #pragma unroll
;             for (int tt = 0; tt < 2; ++tt) { const int kb = 32 * cc + 16 * tt; f32x4 a = (f32x4){0.f, 0.f, 0.f, 0.f};
; #pragma unroll
;                 for (int dc = 0; dc < 4; ++dc) { const bf16x8 kf = *(const LAS bf16x8*)(Kl + (kb + q16) * MEM_KS + 32 * dc + 8 * kq);
;                     a = __builtin_amdgcn_mfma_f32_16x16x32_bf16(kf, qf[dc], a, 0, 0, 0); }
; #pragma unroll
;                 for (int e = 0; e < 4; ++e) mx = fmaxf(mx, a[e]);
;                 S[cc][tt] = a; }
	global_load_dwordx4 v[234:237], v[230:231], off
	global_load_dwordx4 v[242:245], v[230:231], off offset:64
	global_load_dwordx4 v[246:249], v[230:231], off offset:128
	global_load_dwordx4 v[250:253], v[230:231], off offset:192
	v_mul_f32_e32 v16, v16, v50
	v_mul_f32_e32 v17, v17, v50
	v_mul_f32_e32 v18, v18, v50
	v_mul_f32_e32 v19, v19, v50
	v_mul_f32_e32 v0, v0, v27
	v_mul_f32_e32 v1, v1, v26
	v_mul_f32_e32 v2, v2, v21
	v_mul_f32_e32 v3, v3, v20
	v_mul_f32_e32 v16, v16, v29
	v_mul_f32_e32 v17, v17, v28
	v_mul_f32_e32 v18, v18, v23
	v_mul_f32_e32 v19, v19, v22
	v_cvt_pk_bf16_f32 v0, v0, v1
	v_cvt_pk_bf16_f32 v1, v2, v3
	v_cvt_pk_bf16_f32 v2, v16, v17
	v_cvt_pk_bf16_f32 v3, v18, v19
	ds_read_b128 v[186:189], v91
	ds_read_b128 v[190:193], v91 offset:4352
	ds_read_b128 v[194:197], v91 offset:8704
	ds_read_b128 v[198:201], v91 offset:13056
	ds_read_b128 v[202:205], v91 offset:17408
	s_nop 0
	ds_read_b128 v[20:23], v91 offset:64
	s_nop 0
	ds_read_b128 v[28:31], v91 offset:4416
	s_nop 0
	ds_read_b128 v[36:39], v91 offset:8768
	s_nop 0
	ds_read_b128 v[44:47], v91 offset:13120
	s_nop 0
	ds_read_b128 v[52:55], v91 offset:17472
	ds_read_b128 v[56:59], v91 offset:21760
	ds_read_b128 v[60:63], v91 offset:21824
	ds_read_b128 v[64:67], v91 offset:26112
	ds_read_b128 v[68:71], v91 offset:26176
	ds_read_b128 v[72:75], v91 offset:30464
	ds_read_b128 v[76:79], v91 offset:30528
	ds_read_b128 v[102:105], v91 offset:34816
	ds_read_b128 v[106:109], v91 offset:34880
	ds_read_b128 v[110:113], v91 offset:39168
	ds_read_b128 v[114:117], v91 offset:39232
	ds_read_b128 v[118:121], v91 offset:43520
	ds_read_b128 v[122:125], v91 offset:43584
	ds_read_b128 v[126:129], v91 offset:47872
	ds_read_b128 v[130:133], v91 offset:47936
	ds_read_b128 v[134:137], v91 offset:52224
	ds_read_b128 v[138:141], v91 offset:52288
	ds_read_b128 v[142:145], v91 offset:56576
	ds_read_b128 v[146:149], v91 offset:56640
	ds_read_b128 v[150:153], v91 offset:60928
	ds_read_b128 v[154:157], v91 offset:60992
	ds_read_b128 v[158:161], v91 offset:65280
	ds_read_b128 v[162:165], v91 offset:65344
	s_waitcnt lgkmcnt(14)
	v_mfma_f32_16x16x32_bf16 v[16:19], v[186:189], v[8:11], 0
	v_mfma_f32_16x16x32_bf16 v[24:27], v[190:193], v[8:11], 0
	v_mfma_f32_16x16x32_bf16 v[32:35], v[194:197], v[8:11], 0
	v_mfma_f32_16x16x32_bf16 v[40:43], v[198:201], v[8:11], 0
	v_mfma_f32_16x16x32_bf16 v[48:51], v[202:205], v[8:11], 0
	v_mfma_f32_16x16x32_bf16 v[56:59], v[56:59], v[8:11], 0
	v_mfma_f32_16x16x32_bf16 v[64:67], v[64:67], v[8:11], 0
	v_mfma_f32_16x16x32_bf16 v[72:75], v[72:75], v[8:11], 0
	v_mfma_f32_16x16x32_bf16 v[102:105], v[102:105], v[8:11], 0
	s_waitcnt lgkmcnt(13)
	v_mfma_f32_16x16x32_bf16 v[110:113], v[110:113], v[8:11], 0
	s_waitcnt lgkmcnt(11)
	v_mfma_f32_16x16x32_bf16 v[118:121], v[118:121], v[8:11], 0
	s_waitcnt lgkmcnt(9)
	v_mfma_f32_16x16x32_bf16 v[126:129], v[126:129], v[8:11], 0
	s_waitcnt lgkmcnt(7)
	v_mfma_f32_16x16x32_bf16 v[134:137], v[134:137], v[8:11], 0
	s_waitcnt lgkmcnt(5)
	v_mfma_f32_16x16x32_bf16 v[142:145], v[142:145], v[8:11], 0
	s_waitcnt lgkmcnt(3)
	v_mfma_f32_16x16x32_bf16 v[150:153], v[150:153], v[8:11], 0
	s_waitcnt lgkmcnt(1)
	v_mfma_f32_16x16x32_bf16 v[8:11], v[158:161], v[8:11], 0
	v_mfma_f32_16x16x32_bf16 v[16:19], v[20:23], v[12:15], v[16:19]
	v_mfma_f32_16x16x32_bf16 v[20:23], v[28:31], v[12:15], v[24:27]
	v_mfma_f32_16x16x32_bf16 v[24:27], v[36:39], v[12:15], v[32:35]
	v_mfma_f32_16x16x32_bf16 v[28:31], v[44:47], v[12:15], v[40:43]
	v_mfma_f32_16x16x32_bf16 v[32:35], v[52:55], v[12:15], v[48:51]
	v_mfma_f32_16x16x32_bf16 v[36:39], v[60:63], v[12:15], v[56:59]
	v_mfma_f32_16x16x32_bf16 v[40:43], v[68:71], v[12:15], v[64:67]
	v_mfma_f32_16x16x32_bf16 v[44:47], v[76:79], v[12:15], v[72:75]
	v_mfma_f32_16x16x32_bf16 v[48:51], v[106:109], v[12:15], v[102:105]
	ds_read_b128 v[194:197], v91 offset:128
	ds_read_b128 v[198:201], v91 offset:4480
	ds_read_b128 v[202:205], v91 offset:8832
	v_mfma_f32_16x16x32_bf16 v[52:55], v[114:117], v[12:15], v[110:113]
	v_mfma_f32_16x16x32_bf16 v[56:59], v[122:125], v[12:15], v[118:121]
	v_mfma_f32_16x16x32_bf16 v[60:63], v[130:133], v[12:15], v[126:129]
	v_mfma_f32_16x16x32_bf16 v[64:67], v[138:141], v[12:15], v[134:137]
	v_mfma_f32_16x16x32_bf16 v[68:71], v[146:149], v[12:15], v[142:145]
	ds_read_b128 v[206:209], v91 offset:13184
	ds_read_b128 v[210:213], v91 offset:17536
	ds_read_b128 v[218:221], v91 offset:21888
	ds_read_b128 v[222:225], v91 offset:26240
	ds_read_b128 v[226:229], v91 offset:30592
	v_mfma_f32_16x16x32_bf16 v[102:105], v[154:157], v[12:15], v[150:153]
	s_waitcnt lgkmcnt(8)
	v_mfma_f32_16x16x32_bf16 v[8:11], v[162:165], v[12:15], v[8:11]
	s_nop 0
	ds_read_b128 v[106:109], v91 offset:192
	s_waitcnt lgkmcnt(8)
	v_mfma_f32_16x16x32_bf16 v[12:15], v[194:197], v[4:7], v[16:19]
	s_nop 2
	s_nop 0
	ds_read_b128 v[110:113], v91 offset:4544
	s_waitcnt lgkmcnt(8)
	v_mfma_f32_16x16x32_bf16 v[16:19], v[198:201], v[4:7], v[20:23]
	s_nop 2
	s_nop 0
	ds_read_b128 v[114:117], v91 offset:8896
	s_waitcnt lgkmcnt(8)
	v_mfma_f32_16x16x32_bf16 v[20:23], v[202:205], v[4:7], v[24:27]
	s_nop 2
	s_nop 0
	ds_read_b128 v[118:121], v91 offset:13248
	s_waitcnt lgkmcnt(8)
	ds_read_b128 v[186:189], v91 offset:34944
	ds_read_b128 v[190:193], v91 offset:39296
	ds_read_b128 v[194:197], v91 offset:43648
	ds_read_b128 v[198:201], v91 offset:48000
	ds_read_b128 v[202:205], v91 offset:52352
	v_mfma_f32_16x16x32_bf16 v[24:27], v[206:209], v[4:7], v[28:31]
	s_nop 2
	s_nop 0
	ds_read_b128 v[122:125], v91 offset:17600
	s_waitcnt lgkmcnt(13)
	v_mfma_f32_16x16x32_bf16 v[28:31], v[210:213], v[4:7], v[32:35]
	s_nop 2
	s_nop 0
	ds_read_b128 v[126:129], v91 offset:21952
	s_waitcnt lgkmcnt(13)
; #define LAS __attribute__((address_space(3)))
; __device__ __forceinline__ v2u vtr(const LAS bf16* p) { return __builtin_bit_cast(v2u, __builtin_amdgcn_ds_read_tr16_b64_v4i16((LAS v4i16_t*)p)); }
; template <bool SAMPLE>
; __device__ __forceinline__ void mem_unit(const Params& p, int l, LAS unsigned char* lds, int unit, int tid, int wave, int lane) {
;     ...
;         for (int cc = 0; cc < 8; ++cc)
; #pragma unroll
;             for (int tt = 0; tt < 2; ++tt) { const int kb = 32 * cc + 16 * tt; f32x4 a = (f32x4){0.f, 0.f, 0.f, 0.f};
; #pragma unroll
;                 for (int dc = 0; dc < 4; ++dc) { const bf16x8 kf = *(const LAS bf16x8*)(Kl + (kb + q16) * MEM_KS + 32 * dc + 8 * kq);
;                     a = __builtin_amdgcn_mfma_f32_16x16x32_bf16(kf, qf[dc], a, 0, 0, 0); }
; #pragma unroll
;                 for (int e = 0; e < 4; ++e) mx = fmaxf(mx, a[e]);
;                 S[cc][tt] = a; }
;         mx = fmaxf(mx, __shfl_xor(mx, 16)); mx = fmaxf(mx, __shfl_xor(mx, 32));
;     ...
; #pragma unroll
;         for (int dt = 0; dt < 8; ++dt) { f32x4 o = (f32x4){0.f, 0.f, 0.f, 0.f};
; #pragma unroll
;             for (int cc = 0; cc < 8; ++cc) { const LAS bf16* vp = Vt + (32 * cc + 4 * kq + (q16 >> 2)) * MEM_VS + 16 * dt + 4 * (q16 & 3);
;                 const v2u lo = vtr(vp), hi = vtr(vp + 16 * MEM_VS);
	v_mfma_f32_16x16x32_bf16 v[32:35], v[218:221], v[4:7], v[36:39]
	s_nop 2
	s_nop 0
	ds_read_b128 v[130:133], v91 offset:26304
	s_waitcnt lgkmcnt(13)
	v_mfma_f32_16x16x32_bf16 v[134:137], v[222:225], v[4:7], v[40:43]
	s_nop 0
	ds_read_b128 v[138:141], v91 offset:30656
	s_waitcnt lgkmcnt(13)
	v_mfma_f32_16x16x32_bf16 v[142:145], v[226:229], v[4:7], v[44:47]
	s_nop 0
	ds_read_b128 v[146:149], v91 offset:35008
	s_waitcnt lgkmcnt(9)
	ds_read_b128 v[206:209], v91 offset:56704
	ds_read_b128 v[210:213], v91 offset:61056
	ds_read_b128 v[218:221], v91 offset:65408
	v_mfma_f32_16x16x32_bf16 v[150:153], v[186:189], v[4:7], v[48:51]
	s_nop 0
	ds_read_b128 v[154:157], v91 offset:39360
	s_waitcnt lgkmcnt(12)
	v_mfma_f32_16x16x32_bf16 v[158:161], v[190:193], v[4:7], v[52:55]
	s_nop 0
	ds_read_b128 v[162:165], v91 offset:43712
	s_waitcnt lgkmcnt(12)
	v_mfma_f32_16x16x32_bf16 v[166:169], v[194:197], v[4:7], v[56:59]
	s_nop 0
	ds_read_b128 v[170:173], v91 offset:48064
	s_waitcnt lgkmcnt(12)
	v_mfma_f32_16x16x32_bf16 v[174:177], v[198:201], v[4:7], v[60:63]
	s_nop 0
	ds_read_b128 v[178:181], v91 offset:52416
	s_waitcnt lgkmcnt(12)
	v_mfma_f32_16x16x32_bf16 v[182:185], v[202:205], v[4:7], v[64:67]
	s_nop 0
	ds_read_b128 v[72:75], v91 offset:56768
	s_waitcnt lgkmcnt(7)
	v_mfma_f32_16x16x32_bf16 v[76:79], v[206:209], v[4:7], v[68:71]
	s_nop 0
	ds_read_b128 v[64:67], v91 offset:61120
	s_waitcnt lgkmcnt(7)
	v_mfma_f32_16x16x32_bf16 v[68:71], v[210:213], v[4:7], v[102:105]
	s_nop 0
	ds_read_b128 v[56:59], v91 offset:65472
	v_lshrrev_b32_e32 v91, 2, v90
	s_waitcnt lgkmcnt(7)
	v_mfma_f32_16x16x32_bf16 v[60:63], v[218:221], v[4:7], v[8:11]
	v_mfma_f32_16x16x32_bf16 v[52:55], v[106:109], v[0:3], v[12:15]
	v_mfma_f32_16x16x32_bf16 v[48:51], v[110:113], v[0:3], v[16:19]
	v_mfma_f32_16x16x32_bf16 v[44:47], v[114:117], v[0:3], v[20:23]
	v_mfma_f32_16x16x32_bf16 v[40:43], v[118:121], v[0:3], v[24:27]
	v_mfma_f32_16x16x32_bf16 v[36:39], v[122:125], v[0:3], v[28:31]
	v_mfma_f32_16x16x32_bf16 v[32:35], v[126:129], v[0:3], v[32:35]
	v_mfma_f32_16x16x32_bf16 v[28:31], v[130:133], v[0:3], v[134:137]
	v_mfma_f32_16x16x32_bf16 v[24:27], v[138:141], v[0:3], v[142:145]
	v_mfma_f32_16x16x32_bf16 v[20:23], v[146:149], v[0:3], v[150:153]
	v_mfma_f32_16x16x32_bf16 v[16:19], v[154:157], v[0:3], v[158:161]
	v_mfma_f32_16x16x32_bf16 v[12:15], v[162:165], v[0:3], v[166:169]
	v_mfma_f32_16x16x32_bf16 v[8:11], v[170:173], v[0:3], v[174:177]
	v_mfma_f32_16x16x32_bf16 v[4:7], v[178:181], v[0:3], v[182:185]
	v_mfma_f32_16x16x32_bf16 v[72:75], v[72:75], v[0:3], v[76:79]
	v_mfma_f32_16x16x32_bf16 v[66:69], v[64:67], v[0:3], v[68:71]
	s_nop 1
	v_lshlrev_b32_e32 v76, 3, v90
	v_add_u32_e32 v77, v91, v92
	v_and_b32_e32 v76, 24, v76
	s_waitcnt lgkmcnt(0)
	v_mfma_f32_16x16x32_bf16 v[0:3], v[56:59], v[0:3], v[60:63]
	v_max3_f32 v56, v52, s33, v53
	v_max3_f32 v56, v56, v54, v55
	v_max3_f32 v56, v56, v48, v49
	v_max3_f32 v56, v56, v50, v51
	v_max3_f32 v56, v56, v44, v45
	v_max3_f32 v56, v56, v46, v47
	v_max3_f32 v56, v56, v40, v41
	v_max3_f32 v56, v56, v42, v43
	v_max3_f32 v56, v56, v36, v37
	v_max3_f32 v56, v56, v38, v39
	v_max3_f32 v56, v56, v32, v33
	v_max3_f32 v56, v56, v34, v35
	v_max3_f32 v56, v56, v28, v29
	v_max3_f32 v56, v56, v30, v31
	v_max3_f32 v56, v56, v24, v25
	v_max3_f32 v56, v56, v26, v27
	v_max3_f32 v56, v56, v20, v21
	v_max3_f32 v56, v56, v22, v23
	v_max3_f32 v56, v56, v16, v17
	v_max3_f32 v56, v56, v18, v19
	v_max3_f32 v56, v56, v12, v13
	v_max3_f32 v56, v56, v14, v15
	v_max3_f32 v56, v56, v8, v9
	v_max3_f32 v56, v56, v10, v11
	v_max3_f32 v56, v56, v4, v5
	v_max3_f32 v56, v56, v6, v7
	v_max3_f32 v56, v56, v72, v73
	v_max3_f32 v56, v56, v74, v75
	v_max3_f32 v56, v56, v66, v67
	v_max3_f32 v56, v56, v68, v69
	v_max3_f32 v56, v56, v0, v1
	v_max3_f32 v56, v56, v2, v3
	ds_bpermute_b32 v57, v82, v56
	v_mul_lo_u32 v64, v77, s30
	v_add3_u32 v64, s90, v76, v64
	ds_read_b64_tr_b16 v[226:227], v64
	ds_read_b64_tr_b16 v[228:229], v64 offset:4352
	ds_read_b64_tr_b16 v[186:187], v64 offset:8704
	ds_read_b64_tr_b16 v[188:189], v64 offset:13056
	ds_read_b64_tr_b16 v[190:191], v64 offset:17408
	ds_read_b64_tr_b16 v[192:193], v64 offset:21760
	ds_read_b64_tr_b16 v[194:195], v64 offset:26112
	ds_read_b64_tr_b16 v[196:197], v64 offset:30464
	ds_read_b64_tr_b16 v[198:199], v64 offset:34816
	ds_read_b64_tr_b16 v[200:201], v64 offset:39168
	ds_read_b64_tr_b16 v[202:203], v64 offset:32
	ds_read_b64_tr_b16 v[204:205], v64 offset:4384
	s_waitcnt lgkmcnt(12)
	v_max_f32_e32 v57, v57, v57
	v_max_f32_e32 v56, v56, v57
	ds_bpermute_b32 v57, v100, v56
	s_waitcnt lgkmcnt(0)
; __device__ __forceinline__ bf16x8 pack8(const float (&o)[8]) { v4u w; w.x = pk2(o[0], o[1]); w.y = pk2(o[2], o[3]); w.z = pk2(o[4], o[5]); w.w = pk2(o[6], o[7]); return __builtin_bit_cast(bf16x8, w); }
; template <bool SAMPLE>
; __device__ __forceinline__ void mem_unit(const Params& p, int l, LAS unsigned char* lds, int unit, int tid, int wave, int lane) {
;     ...
;         mx = fmaxf(mx, __shfl_xor(mx, 16)); mx = fmaxf(mx, __shfl_xor(mx, 32));
;         float den = 0.f;
; #pragma unroll
;         for (int cc = 0; cc < 8; ++cc)
; #pragma unroll
;             for (int tt = 0; tt < 2; ++tt)
; #pragma unroll
;                 for (int e = 0; e < 4; ++e) { const float pe = __expf(S[cc][tt][e] - mx); S[cc][tt][e] = pe; den += pe; }
;         den += __shfl_xor(den, 16); den += __shfl_xor(den, 32);
;         const float rden = 1.f / den;
;         bf16x8 pf[8];
; #pragma unroll
;         for (int cc = 0; cc < 8; ++cc) { float t8[8];
; #pragma unroll
;             for (int e = 0; e < 4; ++e) { t8[e] = S[cc][0][e]; t8[4 + e] = S[cc][1][e]; }
;             pf[cc] = pack8(t8); }
	v_max_f32_e32 v57, v57, v57
	v_max_f32_e32 v56, v56, v57
	v_sub_f32_e32 v52, v52, v56
	v_sub_f32_e32 v53, v53, v56
	v_mul_f32_e32 v52, 0x3fb8aa3b, v52
	v_sub_f32_e32 v54, v54, v56
	v_sub_f32_e32 v57, v72, v56
	v_sub_f32_e32 v58, v73, v56
	v_sub_f32_e32 v59, v74, v56
	v_sub_f32_e32 v60, v75, v56
	v_sub_f32_e32 v61, v66, v56
	v_sub_f32_e32 v62, v67, v56
	v_sub_f32_e32 v63, v68, v56
	v_sub_f32_e32 v65, v69, v56
	v_mul_f32_e32 v53, 0x3fb8aa3b, v53
	v_exp_f32_e32 v52, v52
	v_sub_f32_e32 v55, v55, v56
	v_sub_f32_e32 v48, v48, v56
	v_sub_f32_e32 v49, v49, v56
	v_sub_f32_e32 v50, v50, v56
	v_sub_f32_e32 v51, v51, v56
	v_sub_f32_e32 v44, v44, v56
	v_sub_f32_e32 v45, v45, v56
	v_sub_f32_e32 v46, v46, v56
	v_sub_f32_e32 v47, v47, v56
	v_sub_f32_e32 v40, v40, v56
	v_sub_f32_e32 v41, v41, v56
	v_sub_f32_e32 v42, v42, v56
	v_sub_f32_e32 v43, v43, v56
	v_sub_f32_e32 v36, v36, v56
	v_sub_f32_e32 v37, v37, v56
	v_sub_f32_e32 v38, v38, v56
	v_sub_f32_e32 v39, v39, v56
	v_sub_f32_e32 v32, v32, v56
	v_sub_f32_e32 v33, v33, v56
	v_sub_f32_e32 v34, v34, v56
	v_sub_f32_e32 v35, v35, v56
	v_sub_f32_e32 v28, v28, v56
	v_sub_f32_e32 v29, v29, v56
	v_sub_f32_e32 v30, v30, v56
	v_sub_f32_e32 v31, v31, v56
	v_sub_f32_e32 v24, v24, v56
	v_sub_f32_e32 v25, v25, v56
	v_sub_f32_e32 v26, v26, v56
	v_sub_f32_e32 v27, v27, v56
	v_sub_f32_e32 v20, v20, v56
	v_sub_f32_e32 v21, v21, v56
	v_sub_f32_e32 v22, v22, v56
	v_sub_f32_e32 v23, v23, v56
	v_sub_f32_e32 v16, v16, v56
	v_sub_f32_e32 v17, v17, v56
	v_sub_f32_e32 v18, v18, v56
	v_sub_f32_e32 v19, v19, v56
	v_sub_f32_e32 v12, v12, v56
	v_sub_f32_e32 v13, v13, v56
	v_sub_f32_e32 v14, v14, v56
	v_sub_f32_e32 v15, v15, v56
	v_sub_f32_e32 v8, v8, v56
	v_sub_f32_e32 v9, v9, v56
	v_sub_f32_e32 v10, v10, v56
	v_sub_f32_e32 v11, v11, v56
	v_sub_f32_e32 v4, v4, v56
	v_sub_f32_e32 v5, v5, v56
	v_sub_f32_e32 v6, v6, v56
	v_sub_f32_e32 v7, v7, v56
	v_sub_f32_e32 v0, v0, v56
	v_sub_f32_e32 v1, v1, v56
	v_sub_f32_e32 v2, v2, v56
	v_sub_f32_e32 v3, v3, v56
	v_mul_f32_e32 v54, 0x3fb8aa3b, v54
	v_mul_f32_e32 v56, 0x3fb8aa3b, v57
	v_mul_f32_e32 v57, 0x3fb8aa3b, v58
	v_mul_f32_e32 v58, 0x3fb8aa3b, v59
	v_mul_f32_e32 v59, 0x3fb8aa3b, v60
	v_mul_f32_e32 v60, 0x3fb8aa3b, v61
	v_mul_f32_e32 v61, 0x3fb8aa3b, v62
	v_mul_f32_e32 v62, 0x3fb8aa3b, v63
	v_mul_f32_e32 v63, 0x3fb8aa3b, v65
	v_exp_f32_e32 v65, v53
	v_mul_f32_e32 v55, 0x3fb8aa3b, v55
	v_exp_f32_e32 v66, v54
	v_mul_f32_e32 v48, 0x3fb8aa3b, v48
	v_exp_f32_e32 v67, v55
	v_mul_f32_e32 v49, 0x3fb8aa3b, v49
	v_mul_f32_e32 v0, 0x3fb8aa3b, v0
	v_exp_f32_e32 v68, v48
	v_add_f32_e32 v147, 0, v52
	v_mul_f32_e32 v50, 0x3fb8aa3b, v50
	v_exp_f32_e32 v69, v49
	v_exp_f32_e32 v143, v0
	v_cvt_pk_bf16_f32 v0, v52, v65
	v_add_f32_e32 v65, v65, v147
	v_mul_f32_e32 v51, 0x3fb8aa3b, v51
	v_exp_f32_e32 v70, v50
	v_add_f32_e32 v65, v66, v65
	v_mul_f32_e32 v44, 0x3fb8aa3b, v44
	v_exp_f32_e32 v71, v51
	v_add_f32_e32 v65, v67, v65
	v_mul_f32_e32 v45, 0x3fb8aa3b, v45
	v_exp_f32_e32 v72, v44
	v_add_f32_e32 v65, v68, v65
	v_mul_f32_e32 v46, 0x3fb8aa3b, v46
	v_exp_f32_e32 v73, v45
	v_add_f32_e32 v65, v69, v65
	v_mul_f32_e32 v47, 0x3fb8aa3b, v47
	v_exp_f32_e32 v74, v46
	v_add_f32_e32 v65, v70, v65
	v_mul_f32_e32 v40, 0x3fb8aa3b, v40
	v_exp_f32_e32 v75, v47
	v_add_f32_e32 v65, v71, v65
	v_mul_f32_e32 v41, 0x3fb8aa3b, v41
	v_mul_f32_e32 v42, 0x3fb8aa3b, v42
	v_mul_f32_e32 v43, 0x3fb8aa3b, v43
	v_mul_f32_e32 v36, 0x3fb8aa3b, v36
	v_mul_f32_e32 v37, 0x3fb8aa3b, v37
	v_mul_f32_e32 v38, 0x3fb8aa3b, v38
	v_mul_f32_e32 v39, 0x3fb8aa3b, v39
	v_mul_f32_e32 v32, 0x3fb8aa3b, v32
	v_mul_f32_e32 v33, 0x3fb8aa3b, v33
	v_mul_f32_e32 v34, 0x3fb8aa3b, v34
	v_mul_f32_e32 v35, 0x3fb8aa3b, v35
	v_mul_f32_e32 v28, 0x3fb8aa3b, v28
	v_mul_f32_e32 v29, 0x3fb8aa3b, v29
	v_mul_f32_e32 v30, 0x3fb8aa3b, v30
	v_mul_f32_e32 v31, 0x3fb8aa3b, v31
	v_mul_f32_e32 v24, 0x3fb8aa3b, v24
	v_mul_f32_e32 v25, 0x3fb8aa3b, v25
	v_mul_f32_e32 v26, 0x3fb8aa3b, v26
	v_mul_f32_e32 v27, 0x3fb8aa3b, v27
	v_mul_f32_e32 v20, 0x3fb8aa3b, v20
	v_mul_f32_e32 v21, 0x3fb8aa3b, v21
	v_mul_f32_e32 v22, 0x3fb8aa3b, v22
	v_mul_f32_e32 v23, 0x3fb8aa3b, v23
	v_mul_f32_e32 v16, 0x3fb8aa3b, v16
	v_mul_f32_e32 v17, 0x3fb8aa3b, v17
	v_mul_f32_e32 v18, 0x3fb8aa3b, v18
	v_mul_f32_e32 v19, 0x3fb8aa3b, v19
	v_mul_f32_e32 v12, 0x3fb8aa3b, v12
	v_mul_f32_e32 v13, 0x3fb8aa3b, v13
	v_mul_f32_e32 v14, 0x3fb8aa3b, v14
	v_mul_f32_e32 v15, 0x3fb8aa3b, v15
	v_mul_f32_e32 v8, 0x3fb8aa3b, v8
	v_mul_f32_e32 v9, 0x3fb8aa3b, v9
	v_mul_f32_e32 v10, 0x3fb8aa3b, v10
	v_mul_f32_e32 v11, 0x3fb8aa3b, v11
	v_mul_f32_e32 v4, 0x3fb8aa3b, v4
	v_mul_f32_e32 v5, 0x3fb8aa3b, v5
	v_mul_f32_e32 v6, 0x3fb8aa3b, v6
	v_mul_f32_e32 v7, 0x3fb8aa3b, v7
	v_mul_f32_e32 v1, 0x3fb8aa3b, v1
	v_mul_f32_e32 v2, 0x3fb8aa3b, v2
	v_mul_f32_e32 v3, 0x3fb8aa3b, v3
	v_exp_f32_e32 v76, v40
	v_add_f32_e32 v65, v72, v65
	v_exp_f32_e32 v77, v41
	v_exp_f32_e32 v78, v42
	v_exp_f32_e32 v79, v43
	v_exp_f32_e32 v90, v36
	v_exp_f32_e32 v91, v37
	v_exp_f32_e32 v101, v38
	v_exp_f32_e32 v102, v39
	v_exp_f32_e32 v103, v32
	v_exp_f32_e32 v104, v33
	v_exp_f32_e32 v105, v34
	v_exp_f32_e32 v106, v35
	v_exp_f32_e32 v107, v28
	v_exp_f32_e32 v108, v29
	v_exp_f32_e32 v109, v30
	v_exp_f32_e32 v110, v31
	v_exp_f32_e32 v111, v24
	v_exp_f32_e32 v112, v25
	v_exp_f32_e32 v113, v26
	v_exp_f32_e32 v114, v27
	v_exp_f32_e32 v115, v20
	v_exp_f32_e32 v116, v21
	v_exp_f32_e32 v117, v22
	v_exp_f32_e32 v118, v23
	v_exp_f32_e32 v119, v16
	v_exp_f32_e32 v120, v17
	v_exp_f32_e32 v121, v18
	v_exp_f32_e32 v122, v19
	v_exp_f32_e32 v123, v12
	v_exp_f32_e32 v124, v13
	v_exp_f32_e32 v125, v14
	v_exp_f32_e32 v126, v15
	v_exp_f32_e32 v127, v8
	v_exp_f32_e32 v128, v9
	v_exp_f32_e32 v129, v10
; #define LAS __attribute__((address_space(3)))
; __device__ __forceinline__ unsigned pk2(float lo, float hi) { return pg8::cvt_pk_bf16(lo, hi); }
; __device__ __forceinline__ bf16x8 pack8(const float (&o)[8]) { v4u w; w.x = pk2(o[0], o[1]); w.y = pk2(o[2], o[3]); w.z = pk2(o[4], o[5]); w.w = pk2(o[6], o[7]); return __builtin_bit_cast(bf16x8, w); }
; __device__ __forceinline__ v2u vtr(const LAS bf16* p) { return __builtin_bit_cast(v2u, __builtin_amdgcn_ds_read_tr16_b64_v4i16((LAS v4i16_t*)p)); }
; template <bool SAMPLE>
; __device__ __forceinline__ void mem_unit(const Params& p, int l, LAS unsigned char* lds, int unit, int tid, int wave, int lane) {
;     ...
;                 for (int e = 0; e < 4; ++e) { const float pe = __expf(S[cc][tt][e] - mx); S[cc][tt][e] = pe; den += pe; }
;         den += __shfl_xor(den, 16); den += __shfl_xor(den, 32);
;         const float rden = 1.f / den;
;         bf16x8 pf[8];
; #pragma unroll
;         for (int cc = 0; cc < 8; ++cc) { float t8[8];
; #pragma unroll
;             for (int e = 0; e < 4; ++e) { t8[e] = S[cc][0][e]; t8[4 + e] = S[cc][1][e]; }
;             pf[cc] = pack8(t8); }
; #pragma unroll
;         for (int dt = 0; dt < 8; ++dt) { f32x4 o = (f32x4){0.f, 0.f, 0.f, 0.f};
; #pragma unroll
;             for (int cc = 0; cc < 8; ++cc) { const LAS bf16* vp = Vt + (32 * cc + 4 * kq + (q16 >> 2)) * MEM_VS + 16 * dt + 4 * (q16 & 3);
;                 const v2u lo = vtr(vp), hi = vtr(vp + 16 * MEM_VS);
;                 v4u av; av.x = lo.x; av.y = lo.y; av.z = hi.x; av.w = hi.y;
;                 o = __builtin_amdgcn_mfma_f32_16x16x32_bf16(__builtin_bit_cast(bf16x8, av), pf[cc], o, 0, 0, 0); }
;             if (st) { v2u w; w.x = pk2(o[0] * rden, o[1] * rden); w.y = pk2(o[2] * rden, o[3] * rden);
;                 *(v2u*)(MO + row * 512 + h * 128 + 16 * dt + 4 * kq) = w; } }
	v_exp_f32_e32 v130, v11
	v_exp_f32_e32 v131, v4
	v_exp_f32_e32 v132, v5
	v_exp_f32_e32 v133, v6
	v_exp_f32_e32 v134, v7
	v_exp_f32_e32 v135, v56
	v_exp_f32_e32 v136, v57
	v_exp_f32_e32 v137, v58
	v_exp_f32_e32 v138, v59
	v_exp_f32_e32 v139, v60
	v_exp_f32_e32 v140, v61
	v_exp_f32_e32 v141, v62
	v_exp_f32_e32 v142, v63
	v_exp_f32_e32 v144, v1
	v_exp_f32_e32 v145, v2
	v_exp_f32_e32 v146, v3
	v_cvt_pk_bf16_f32 v1, v66, v67
	v_cvt_pk_bf16_f32 v2, v68, v69
	v_cvt_pk_bf16_f32 v3, v70, v71
	v_cvt_pk_bf16_f32 v4, v72, v73
	v_cvt_pk_bf16_f32 v5, v74, v75
	v_cvt_pk_bf16_f32 v6, v76, v77
	v_cvt_pk_bf16_f32 v7, v78, v79
	v_cvt_pk_bf16_f32 v8, v90, v91
	v_cvt_pk_bf16_f32 v9, v101, v102
	v_cvt_pk_bf16_f32 v10, v103, v104
	v_cvt_pk_bf16_f32 v11, v105, v106
	v_cvt_pk_bf16_f32 v12, v107, v108
	v_cvt_pk_bf16_f32 v13, v109, v110
	v_cvt_pk_bf16_f32 v14, v111, v112
	v_cvt_pk_bf16_f32 v15, v113, v114
	v_cvt_pk_bf16_f32 v16, v115, v116
	v_cvt_pk_bf16_f32 v17, v117, v118
	v_cvt_pk_bf16_f32 v18, v119, v120
	v_cvt_pk_bf16_f32 v19, v121, v122
	v_cvt_pk_bf16_f32 v24, v123, v124
	v_cvt_pk_bf16_f32 v25, v125, v126
	v_cvt_pk_bf16_f32 v26, v127, v128
	v_cvt_pk_bf16_f32 v27, v129, v130
	v_cvt_pk_bf16_f32 v28, v131, v132
	v_cvt_pk_bf16_f32 v29, v133, v134
	v_cvt_pk_bf16_f32 v30, v135, v136
	v_cvt_pk_bf16_f32 v31, v137, v138
	v_cvt_pk_bf16_f32 v20, v139, v140
	v_cvt_pk_bf16_f32 v21, v141, v142
	v_cvt_pk_bf16_f32 v22, v143, v144
	v_cvt_pk_bf16_f32 v23, v145, v146
	s_nop 7
	s_nop 1
	ds_read_b64_tr_b16 v[52:53], v64 offset:43520
	ds_read_b64_tr_b16 v[54:55], v64 offset:47872
	ds_read_b64_tr_b16 v[56:57], v64 offset:52224
	ds_read_b64_tr_b16 v[58:59], v64 offset:56576
	ds_read_b64_tr_b16 v[60:61], v64 offset:60928
	ds_read_b64_tr_b16 v[62:63], v64 offset:65280
	v_add_f32_e32 v65, v73, v65
	s_nop 0
	v_mfma_f32_16x16x32_bf16 v[32:35], v[226:229], v[0:3], 0
	v_add_f32_e32 v65, v74, v65
	v_add_f32_e32 v65, v75, v65
	v_add_f32_e32 v65, v76, v65
	v_add_f32_e32 v65, v77, v65
	s_nop 0
	ds_read_b64_tr_b16 v[206:207], v64 offset:8736
	ds_read_b64_tr_b16 v[208:209], v64 offset:13088
	ds_read_b64_tr_b16 v[210:211], v64 offset:17440
	ds_read_b64_tr_b16 v[212:213], v64 offset:21792
	ds_read_b64_tr_b16 v[218:219], v64 offset:26144
	ds_read_b64_tr_b16 v[220:221], v64 offset:30496
	ds_read_b64_tr_b16 v[222:223], v64 offset:34848
	ds_read_b64_tr_b16 v[224:225], v64 offset:39200
	ds_read_b64_tr_b16 v[226:227], v64 offset:43552
	ds_read_b64_tr_b16 v[228:229], v64 offset:47904
	v_mfma_f32_16x16x32_bf16 v[32:35], v[186:189], v[4:7], v[32:35]
	v_add_f32_e32 v36, v78, v65
	v_add_f32_e32 v36, v79, v36
	v_add_f32_e32 v36, v90, v36
	v_add_f32_e32 v36, v91, v36
	s_nop 0
	v_mfma_f32_16x16x32_bf16 v[32:35], v[190:193], v[8:11], v[32:35]
	v_add_f32_e32 v36, v101, v36
	v_add_f32_e32 v36, v102, v36
	v_add_f32_e32 v36, v103, v36
	v_add_f32_e32 v36, v104, v36
	s_nop 0
	v_mfma_f32_16x16x32_bf16 v[32:35], v[194:197], v[12:15], v[32:35]
	v_add_f32_e32 v36, v105, v36
	v_add_f32_e32 v36, v106, v36
	v_add_f32_e32 v36, v107, v36
	v_add_f32_e32 v36, v108, v36
	s_nop 0
	v_mfma_f32_16x16x32_bf16 v[32:35], v[198:201], v[16:19], v[32:35]
	v_add_f32_e32 v36, v109, v36
	v_add_f32_e32 v36, v110, v36
	v_add_f32_e32 v36, v111, v36
	v_add_f32_e32 v36, v112, v36
	s_waitcnt lgkmcnt(14)
	v_mfma_f32_16x16x32_bf16 v[32:35], v[52:55], v[24:27], v[32:35]
	v_add_f32_e32 v36, v113, v36
	v_add_f32_e32 v36, v114, v36
	v_add_f32_e32 v36, v115, v36
	v_add_f32_e32 v36, v116, v36
	s_waitcnt lgkmcnt(12)
	v_mfma_f32_16x16x32_bf16 v[32:35], v[56:59], v[28:31], v[32:35]
	v_add_f32_e32 v36, v117, v36
	v_add_f32_e32 v36, v118, v36
	v_add_f32_e32 v36, v119, v36
	v_add_f32_e32 v40, v120, v36
	s_waitcnt lgkmcnt(10)
	v_mfma_f32_16x16x32_bf16 v[36:39], v[60:63], v[20:23], v[32:35]
	s_nop 2
	v_add_f32_e32 v32, v121, v40
	v_add_f32_e32 v32, v122, v32
	v_add_f32_e32 v32, v123, v32
	v_add_f32_e32 v32, v124, v32
	v_add_f32_e32 v32, v125, v32
	v_add_f32_e32 v32, v126, v32
	v_add_f32_e32 v32, v127, v32
	v_add_f32_e32 v32, v128, v32
	v_add_f32_e32 v32, v129, v32
	v_add_f32_e32 v32, v130, v32
	v_add_f32_e32 v32, v131, v32
	v_add_f32_e32 v32, v132, v32
	v_add_f32_e32 v32, v133, v32
	v_add_f32_e32 v32, v134, v32
	v_add_f32_e32 v32, v135, v32
	v_add_f32_e32 v32, v136, v32
	v_add_f32_e32 v32, v137, v32
	v_add_f32_e32 v32, v138, v32
	v_add_f32_e32 v32, v139, v32
	v_add_f32_e32 v32, v140, v32
	v_add_f32_e32 v32, v141, v32
	v_add_f32_e32 v32, v142, v32
	v_add_f32_e32 v32, v143, v32
	v_add_f32_e32 v32, v144, v32
	v_add_f32_e32 v32, v145, v32
	v_add_f32_e32 v32, v146, v32
	ds_bpermute_b32 v33, v82, v32
	s_waitcnt lgkmcnt(0)
	v_add_f32_e32 v32, v32, v33
	ds_bpermute_b32 v33, v100, v32
	s_waitcnt lgkmcnt(0)
	v_add_f32_e32 v32, v32, v33
	v_div_scale_f32 v33, s[16:17], v32, v32, 1.0
	v_rcp_f32_e32 v35, v33
	v_div_scale_f32 v34, vcc, 1.0, v32, 1.0
	v_fma_f32 v40, -v33, v35, 1.0
	v_fmac_f32_e32 v35, v40, v35
	v_mul_f32_e32 v40, v34, v35
	v_fma_f32 v41, -v33, v40, v34
	v_fmac_f32_e32 v40, v41, v35
	v_fma_f32 v33, -v33, v40, v34
	v_div_fmas_f32 v33, v33, v35, v40
	v_div_fixup_f32 v34, v33, v32, 1.0
	v_mul_f32_e32 v32, v36, v34
	v_mul_f32_e32 v36, v39, v34
	v_mul_f32_e32 v33, v37, v34
	v_mul_f32_e32 v35, v38, v34
	v_cvt_pk_bf16_f32 v52, v32, v33
	v_cvt_pk_bf16_f32 v53, v35, v36
	s_nop 5
	v_mfma_f32_16x16x32_bf16 v[36:39], v[202:205], v[0:3], 0
	s_nop 1
	v_lshl_add_u64 v[32:33], s[2:3], 0, v[88:89]
	v_lshl_add_u64 v[32:33], v[92:93], 1, v[32:33]
	s_nop 0
	ds_read_b64_tr_b16 v[186:187], v64 offset:52256
	ds_read_b64_tr_b16 v[188:189], v64 offset:56608
	ds_read_b64_tr_b16 v[190:191], v64 offset:60960
	ds_read_b64_tr_b16 v[192:193], v64 offset:65312
	ds_read_b64_tr_b16 v[194:195], v64 offset:64
	ds_read_b64_tr_b16 v[196:197], v64 offset:4416
	ds_read_b64_tr_b16 v[198:199], v64 offset:8768
	ds_read_b64_tr_b16 v[200:201], v64 offset:13120
	ds_read_b64_tr_b16 v[202:203], v64 offset:17472
	ds_read_b64_tr_b16 v[204:205], v64 offset:21824
	v_mfma_f32_16x16x32_bf16 v[36:39], v[206:209], v[4:7], v[36:39]
	s_nop 2
	v_mfma_f32_16x16x32_bf16 v[36:39], v[210:213], v[8:11], v[36:39]
	s_nop 2
	v_mfma_f32_16x16x32_bf16 v[36:39], v[218:221], v[12:15], v[36:39]
	s_nop 2
	v_mfma_f32_16x16x32_bf16 v[36:39], v[222:225], v[16:19], v[36:39]
	s_nop 2
	global_store_dwordx2 v[32:33], v[52:53], off
	s_nop 0
	v_mfma_f32_16x16x32_bf16 v[36:39], v[226:229], v[24:27], v[36:39]
	s_waitcnt lgkmcnt(8)
; #define LAS __attribute__((address_space(3)))
; __device__ __forceinline__ unsigned pk2(float lo, float hi) { return pg8::cvt_pk_bf16(lo, hi); }
; __device__ __forceinline__ v2u vtr(const LAS bf16* p) { return __builtin_bit_cast(v2u, __builtin_amdgcn_ds_read_tr16_b64_v4i16((LAS v4i16_t*)p)); }
; template <bool SAMPLE>
; __device__ __forceinline__ void mem_unit(const Params& p, int l, LAS unsigned char* lds, int unit, int tid, int wave, int lane) {
;     ...
; #pragma unroll
;         for (int dt = 0; dt < 8; ++dt) { f32x4 o = (f32x4){0.f, 0.f, 0.f, 0.f};
; #pragma unroll
;             for (int cc = 0; cc < 8; ++cc) { const LAS bf16* vp = Vt + (32 * cc + 4 * kq + (q16 >> 2)) * MEM_VS + 16 * dt + 4 * (q16 & 3);
;                 const v2u lo = vtr(vp), hi = vtr(vp + 16 * MEM_VS);
;                 v4u av; av.x = lo.x; av.y = lo.y; av.z = hi.x; av.w = hi.y;
;                 o = __builtin_amdgcn_mfma_f32_16x16x32_bf16(__builtin_bit_cast(bf16x8, av), pf[cc], o, 0, 0, 0); }
;             if (st) { v2u w; w.x = pk2(o[0] * rden, o[1] * rden); w.y = pk2(o[2] * rden, o[3] * rden);
;                 *(v2u*)(MO + row * 512 + h * 128 + 16 * dt + 4 * kq) = w; } }
	ds_read_b64_tr_b16 v[206:207], v64 offset:26176
	ds_read_b64_tr_b16 v[208:209], v64 offset:30528
	ds_read_b64_tr_b16 v[210:211], v64 offset:34880
	ds_read_b64_tr_b16 v[212:213], v64 offset:39232
	ds_read_b64_tr_b16 v[218:219], v64 offset:43584
	ds_read_b64_tr_b16 v[220:221], v64 offset:47936
	ds_read_b64_tr_b16 v[222:223], v64 offset:52288
	ds_read_b64_tr_b16 v[224:225], v64 offset:56640
	ds_read_b64_tr_b16 v[226:227], v64 offset:60992
	ds_read_b64_tr_b16 v[228:229], v64 offset:65344
	v_mfma_f32_16x16x32_bf16 v[36:39], v[186:189], v[28:31], v[36:39]
	s_waitcnt lgkmcnt(15)
	v_mfma_f32_16x16x32_bf16 v[36:39], v[190:193], v[20:23], v[36:39]
	s_nop 7
	v_mul_f32_e32 v35, v34, v36
	v_mul_f32_e32 v36, v34, v37
	v_mul_f32_e32 v37, v34, v38
	v_mul_f32_e32 v38, v34, v39
	v_cvt_pk_bf16_f32 v52, v35, v36
	v_cvt_pk_bf16_f32 v53, v37, v38
	s_nop 4
	s_waitcnt lgkmcnt(14)
	v_mfma_f32_16x16x32_bf16 v[36:39], v[194:197], v[0:3], 0
	s_nop 1
	s_waitcnt lgkmcnt(12)
	v_mfma_f32_16x16x32_bf16 v[36:39], v[198:201], v[4:7], v[36:39]
	s_nop 1
	s_waitcnt lgkmcnt(10)
	v_mfma_f32_16x16x32_bf16 v[36:39], v[202:205], v[8:11], v[36:39]
	s_nop 1
	s_waitcnt lgkmcnt(8)
	ds_read_b64_tr_b16 v[186:187], v64 offset:96
	ds_read_b64_tr_b16 v[188:189], v64 offset:4448
	ds_read_b64_tr_b16 v[190:191], v64 offset:8800
	ds_read_b64_tr_b16 v[192:193], v64 offset:13152
	ds_read_b64_tr_b16 v[194:195], v64 offset:17504
	ds_read_b64_tr_b16 v[196:197], v64 offset:21856
	ds_read_b64_tr_b16 v[198:199], v64 offset:26208
	ds_read_b64_tr_b16 v[200:201], v64 offset:30560
	ds_read_b64_tr_b16 v[202:203], v64 offset:34912
	ds_read_b64_tr_b16 v[204:205], v64 offset:39264
	v_mfma_f32_16x16x32_bf16 v[36:39], v[206:209], v[12:15], v[36:39]
	s_nop 1
	s_waitcnt lgkmcnt(15)
	v_mfma_f32_16x16x32_bf16 v[36:39], v[210:213], v[16:19], v[36:39]
	s_nop 2
	global_store_dwordx2 v[32:33], v[52:53], off offset:32
	s_waitcnt lgkmcnt(14)
	v_mfma_f32_16x16x32_bf16 v[36:39], v[218:221], v[24:27], v[36:39]
	s_waitcnt lgkmcnt(12)
	v_mfma_f32_16x16x32_bf16 v[36:39], v[222:225], v[28:31], v[36:39]
	s_waitcnt lgkmcnt(10)
	v_mfma_f32_16x16x32_bf16 v[36:39], v[226:229], v[20:23], v[36:39]
	s_nop 7
	v_mul_f32_e32 v35, v34, v36
	v_mul_f32_e32 v36, v34, v37
	v_mul_f32_e32 v37, v34, v38
	v_mul_f32_e32 v38, v34, v39
	v_cvt_pk_bf16_f32 v52, v35, v36
	v_cvt_pk_bf16_f32 v53, v37, v38
	s_nop 4
	s_waitcnt lgkmcnt(8)
	ds_read_b64_tr_b16 v[206:207], v64 offset:43616
	ds_read_b64_tr_b16 v[208:209], v64 offset:47968
	ds_read_b64_tr_b16 v[210:211], v64 offset:52320
	ds_read_b64_tr_b16 v[212:213], v64 offset:56672
	ds_read_b64_tr_b16 v[218:219], v64 offset:61024
	ds_read_b64_tr_b16 v[220:221], v64 offset:65376
	ds_read_b64_tr_b16 v[222:223], v64 offset:128
	ds_read_b64_tr_b16 v[224:225], v64 offset:4480
	ds_read_b64_tr_b16 v[226:227], v64 offset:8832
	ds_read_b64_tr_b16 v[228:229], v64 offset:13184
	v_mfma_f32_16x16x32_bf16 v[36:39], v[186:189], v[0:3], 0
	s_nop 1
	s_waitcnt lgkmcnt(15)
	v_mfma_f32_16x16x32_bf16 v[36:39], v[190:193], v[4:7], v[36:39]
	s_nop 1
	s_waitcnt lgkmcnt(14)
	v_mfma_f32_16x16x32_bf16 v[36:39], v[194:197], v[8:11], v[36:39]
	s_nop 1
	s_waitcnt lgkmcnt(12)
	v_mfma_f32_16x16x32_bf16 v[36:39], v[198:201], v[12:15], v[36:39]
	s_nop 1
	s_waitcnt lgkmcnt(10)
	v_mfma_f32_16x16x32_bf16 v[36:39], v[202:205], v[16:19], v[36:39]
	s_nop 2
	global_store_dwordx2 v[32:33], v[52:53], off offset:64
	s_waitcnt lgkmcnt(8)
	ds_read_b64_tr_b16 v[186:187], v64 offset:17536
	ds_read_b64_tr_b16 v[188:189], v64 offset:21888
	ds_read_b64_tr_b16 v[190:191], v64 offset:26240
	ds_read_b64_tr_b16 v[192:193], v64 offset:30592
	ds_read_b64_tr_b16 v[194:195], v64 offset:34944
	ds_read_b64_tr_b16 v[196:197], v64 offset:39296
	ds_read_b64_tr_b16 v[198:199], v64 offset:43648
	ds_read_b64_tr_b16 v[200:201], v64 offset:48000
	ds_read_b64_tr_b16 v[202:203], v64 offset:52352
	ds_read_b64_tr_b16 v[204:205], v64 offset:56704
	v_mfma_f32_16x16x32_bf16 v[36:39], v[206:209], v[24:27], v[36:39]
	s_waitcnt lgkmcnt(15)
	v_mfma_f32_16x16x32_bf16 v[36:39], v[210:213], v[28:31], v[36:39]
	s_waitcnt lgkmcnt(14)
	v_mfma_f32_16x16x32_bf16 v[36:39], v[218:221], v[20:23], v[36:39]
	s_nop 7
	v_mul_f32_e32 v35, v34, v36
	v_mul_f32_e32 v36, v34, v37
	v_mul_f32_e32 v37, v34, v38
	v_mul_f32_e32 v38, v34, v39
	v_cvt_pk_bf16_f32 v52, v35, v36
	v_cvt_pk_bf16_f32 v53, v37, v38
	s_nop 4
	s_waitcnt lgkmcnt(12)
	v_mfma_f32_16x16x32_bf16 v[36:39], v[222:225], v[0:3], 0
	s_nop 1
	s_waitcnt lgkmcnt(10)
	v_mfma_f32_16x16x32_bf16 v[36:39], v[226:229], v[4:7], v[36:39]
	s_nop 1
	s_waitcnt lgkmcnt(8)
	ds_read_b64_tr_b16 v[206:207], v64 offset:61056
	ds_read_b64_tr_b16 v[208:209], v64 offset:65408
	ds_read_b64_tr_b16 v[210:211], v64 offset:160
	ds_read_b64_tr_b16 v[212:213], v64 offset:4512
	ds_read_b64_tr_b16 v[218:219], v64 offset:8864
	ds_read_b64_tr_b16 v[220:221], v64 offset:13216
	ds_read_b64_tr_b16 v[222:223], v64 offset:17568
	ds_read_b64_tr_b16 v[224:225], v64 offset:21920
	ds_read_b64_tr_b16 v[226:227], v64 offset:26272
	ds_read_b64_tr_b16 v[228:229], v64 offset:30624
	v_mfma_f32_16x16x32_bf16 v[36:39], v[186:189], v[8:11], v[36:39]
	s_nop 1
	s_waitcnt lgkmcnt(15)
	v_mfma_f32_16x16x32_bf16 v[36:39], v[190:193], v[12:15], v[36:39]
	s_nop 1
	s_waitcnt lgkmcnt(14)
	v_mfma_f32_16x16x32_bf16 v[36:39], v[194:197], v[16:19], v[36:39]
	s_nop 2
	global_store_dwordx2 v[32:33], v[52:53], off offset:96
	s_waitcnt lgkmcnt(12)
; #define LAS __attribute__((address_space(3)))
; __device__ __forceinline__ unsigned pk2(float lo, float hi) { return pg8::cvt_pk_bf16(lo, hi); }
; __device__ __forceinline__ v2u vtr(const LAS bf16* p) { return __builtin_bit_cast(v2u, __builtin_amdgcn_ds_read_tr16_b64_v4i16((LAS v4i16_t*)p)); }
; template <bool SAMPLE>
; __device__ __forceinline__ void mem_unit(const Params& p, int l, LAS unsigned char* lds, int unit, int tid, int wave, int lane) {
;     ...
; #pragma unroll
;         for (int dt = 0; dt < 8; ++dt) { f32x4 o = (f32x4){0.f, 0.f, 0.f, 0.f};
; #pragma unroll
;             for (int cc = 0; cc < 8; ++cc) { const LAS bf16* vp = Vt + (32 * cc + 4 * kq + (q16 >> 2)) * MEM_VS + 16 * dt + 4 * (q16 & 3);
;                 const v2u lo = vtr(vp), hi = vtr(vp + 16 * MEM_VS);
;                 v4u av; av.x = lo.x; av.y = lo.y; av.z = hi.x; av.w = hi.y;
;                 o = __builtin_amdgcn_mfma_f32_16x16x32_bf16(__builtin_bit_cast(bf16x8, av), pf[cc], o, 0, 0, 0); }
;             if (st) { v2u w; w.x = pk2(o[0] * rden, o[1] * rden); w.y = pk2(o[2] * rden, o[3] * rden);
;                 *(v2u*)(MO + row * 512 + h * 128 + 16 * dt + 4 * kq) = w; } }
;       }
;     }
;     __syncthreads();
	v_mfma_f32_16x16x32_bf16 v[36:39], v[198:201], v[24:27], v[36:39]
	s_waitcnt lgkmcnt(10)
	v_mfma_f32_16x16x32_bf16 v[36:39], v[202:205], v[28:31], v[36:39]
	s_waitcnt lgkmcnt(8)
	ds_read_b64_tr_b16 v[186:187], v64 offset:34976
	ds_read_b64_tr_b16 v[188:189], v64 offset:39328
	ds_read_b64_tr_b16 v[190:191], v64 offset:43680
	ds_read_b64_tr_b16 v[192:193], v64 offset:48032
	ds_read_b64_tr_b16 v[194:195], v64 offset:52384
	ds_read_b64_tr_b16 v[196:197], v64 offset:56736
	ds_read_b64_tr_b16 v[198:199], v64 offset:61088
	ds_read_b64_tr_b16 v[200:201], v64 offset:65440
	ds_read_b64_tr_b16 v[202:203], v64 offset:192
	ds_read_b64_tr_b16 v[204:205], v64 offset:4544
	v_mfma_f32_16x16x32_bf16 v[36:39], v[206:209], v[20:23], v[36:39]
	s_nop 7
	v_mul_f32_e32 v35, v34, v36
	v_mul_f32_e32 v36, v34, v37
	v_mul_f32_e32 v37, v34, v38
	v_mul_f32_e32 v38, v34, v39
	v_cvt_pk_bf16_f32 v52, v35, v36
	v_cvt_pk_bf16_f32 v53, v37, v38
	s_nop 4
	s_waitcnt lgkmcnt(15)
	v_mfma_f32_16x16x32_bf16 v[36:39], v[210:213], v[0:3], 0
	s_nop 1
	s_waitcnt lgkmcnt(14)
	v_mfma_f32_16x16x32_bf16 v[36:39], v[218:221], v[4:7], v[36:39]
	s_nop 1
	s_waitcnt lgkmcnt(12)
	v_mfma_f32_16x16x32_bf16 v[36:39], v[222:225], v[8:11], v[36:39]
	s_nop 1
	s_waitcnt lgkmcnt(10)
	v_mfma_f32_16x16x32_bf16 v[36:39], v[226:229], v[12:15], v[36:39]
	s_nop 1
	s_waitcnt lgkmcnt(8)
	ds_read_b64_tr_b16 v[206:207], v64 offset:8896
	ds_read_b64_tr_b16 v[208:209], v64 offset:13248
	ds_read_b64_tr_b16 v[210:211], v64 offset:17600
	ds_read_b64_tr_b16 v[212:213], v64 offset:21952
	ds_read_b64_tr_b16 v[218:219], v64 offset:26304
	ds_read_b64_tr_b16 v[220:221], v64 offset:30656
	ds_read_b64_tr_b16 v[222:223], v64 offset:35008
	ds_read_b64_tr_b16 v[224:225], v64 offset:39360
	ds_read_b64_tr_b16 v[226:227], v64 offset:43712
	ds_read_b64_tr_b16 v[228:229], v64 offset:48064
	v_mfma_f32_16x16x32_bf16 v[36:39], v[186:189], v[16:19], v[36:39]
	s_nop 2
	global_store_dwordx2 v[32:33], v[52:53], off offset:128
	s_waitcnt lgkmcnt(15)
	v_mfma_f32_16x16x32_bf16 v[36:39], v[190:193], v[24:27], v[36:39]
	s_waitcnt lgkmcnt(14)
	v_mfma_f32_16x16x32_bf16 v[36:39], v[194:197], v[28:31], v[36:39]
	s_waitcnt lgkmcnt(12)
	v_mfma_f32_16x16x32_bf16 v[36:39], v[198:201], v[20:23], v[36:39]
	s_nop 7
	v_mul_f32_e32 v35, v34, v36
	v_mul_f32_e32 v36, v34, v37
	v_mul_f32_e32 v37, v34, v38
	v_mul_f32_e32 v38, v34, v39
	v_cvt_pk_bf16_f32 v52, v35, v36
	v_cvt_pk_bf16_f32 v53, v37, v38
	s_nop 4
	s_waitcnt lgkmcnt(10)
	v_mfma_f32_16x16x32_bf16 v[36:39], v[202:205], v[0:3], 0
	s_nop 1
	s_waitcnt lgkmcnt(8)
	ds_read_b64_tr_b16 v[186:187], v64 offset:61120
	ds_read_b64_tr_b16 v[188:189], v64 offset:65472
	ds_read_b64_tr_b16 v[190:191], v64 offset:224
	ds_read_b64_tr_b16 v[192:193], v64 offset:4576
	ds_read_b64_tr_b16 v[194:195], v64 offset:35040
	ds_read_b64_tr_b16 v[196:197], v64 offset:39392
	v_mfma_f32_16x16x32_bf16 v[36:39], v[206:209], v[4:7], v[36:39]
	s_nop 1
	s_waitcnt lgkmcnt(12)
	v_mfma_f32_16x16x32_bf16 v[36:39], v[210:213], v[8:11], v[36:39]
	s_nop 1
	s_waitcnt lgkmcnt(10)
	v_mfma_f32_16x16x32_bf16 v[36:39], v[218:221], v[12:15], v[36:39]
	s_nop 0
	ds_read_b64_tr_b16 v[48:49], v64 offset:52416
	s_waitcnt lgkmcnt(9)
	v_mfma_f32_16x16x32_bf16 v[36:39], v[222:225], v[16:19], v[36:39]
	ds_read_b64_tr_b16 v[50:51], v64 offset:56768
	s_nop 1
	global_store_dwordx2 v[32:33], v[52:53], off offset:160
	s_waitcnt lgkmcnt(8)
	v_mfma_f32_16x16x32_bf16 v[36:39], v[226:229], v[24:27], v[36:39]
	s_waitcnt lgkmcnt(0)
	v_mfma_f32_16x16x32_bf16 v[36:39], v[48:51], v[28:31], v[36:39]
	s_nop 0
	v_mfma_f32_16x16x32_bf16 v[36:39], v[186:189], v[20:23], v[36:39]
	s_nop 7
	v_mul_f32_e32 v35, v34, v36
	v_mul_f32_e32 v36, v34, v37
	v_mul_f32_e32 v37, v34, v38
	v_mul_f32_e32 v38, v34, v39
	v_cvt_pk_bf16_f32 v48, v35, v36
	v_cvt_pk_bf16_f32 v49, v37, v38
	s_nop 1
	ds_read_b64_tr_b16 v[40:41], v64 offset:8928
	ds_read_b64_tr_b16 v[42:43], v64 offset:13280
	ds_read_b64_tr_b16 v[44:45], v64 offset:17632
	s_nop 0
	v_mfma_f32_16x16x32_bf16 v[0:3], v[190:193], v[0:3], 0
	ds_read_b64_tr_b16 v[46:47], v64 offset:21984
	ds_read_b64_tr_b16 v[36:37], v64 offset:26336
	s_waitcnt lgkmcnt(3)
	v_mfma_f32_16x16x32_bf16 v[0:3], v[40:43], v[4:7], v[0:3]
	ds_read_b64_tr_b16 v[38:39], v64 offset:30688
	s_nop 0
	s_waitcnt lgkmcnt(2)
	v_mfma_f32_16x16x32_bf16 v[0:3], v[44:47], v[8:11], v[0:3]
	s_nop 0
	ds_read_b64_tr_b16 v[8:9], v64 offset:43744
	s_waitcnt lgkmcnt(1)
	v_mfma_f32_16x16x32_bf16 v[0:3], v[36:39], v[12:15], v[0:3]
	ds_read_b64_tr_b16 v[10:11], v64 offset:48096
	ds_read_b64_tr_b16 v[12:13], v64 offset:52448
	s_nop 0
	v_mfma_f32_16x16x32_bf16 v[0:3], v[194:197], v[16:19], v[0:3]
	ds_read_b64_tr_b16 v[14:15], v64 offset:56800
	ds_read_b64_tr_b16 v[4:5], v64 offset:61152
	ds_read_b64_tr_b16 v[6:7], v64 offset:65504
	global_store_dwordx2 v[32:33], v[48:49], off offset:192
	s_waitcnt lgkmcnt(4)
	v_mfma_f32_16x16x32_bf16 v[0:3], v[8:11], v[24:27], v[0:3]
	s_waitcnt lgkmcnt(2)
	v_mfma_f32_16x16x32_bf16 v[0:3], v[12:15], v[28:31], v[0:3]
	s_waitcnt lgkmcnt(0)
	v_mfma_f32_16x16x32_bf16 v[0:3], v[4:7], v[20:23], v[0:3]
	s_nop 7
	v_mul_f32_e32 v0, v34, v0
	v_mul_f32_e32 v1, v34, v1
	v_mul_f32_e32 v2, v34, v2
	v_mul_f32_e32 v3, v34, v3
	v_cvt_pk_bf16_f32 v0, v0, v1
	v_cvt_pk_bf16_f32 v1, v2, v3
	global_store_dwordx2 v[32:33], v[0:1], off offset:224
	s_cbranch_scc1 .LBB0_631
	s_nop 0
	s_nop 0
	s_nop 0
	s_nop 0
	s_nop 0
	s_nop 0
	s_nop 0
	s_nop 0
	s_nop 0
	s_nop 0
	s_nop 0
	s_barrier
	s_branch .LBB0_596

; #define LAS __attribute__((address_space(3)))
; template <bool SAMPLE>
; __device__ __forceinline__ void mem_unit(const Params& p, int l, LAS unsigned char* lds, int unit, int tid, int wave, int lane) {
;     ...
;         for (int hb = 0; hb < 2; ++hb) {
;             float kk[4][8], vv[4][8];
; #pragma unroll
;             for (int it = 0; it < 4; ++it) { const int s = (tid >> 4) + 32 * (4 * hb + it);
;                 const float* kp; const float* vp;
;                 if (!SAMPLE) { kp = (const float*)(p.ws + W_MKV) + ((size_t)l * 1024 + b * 256 + s) * 1024 + h * 128 + sub * 8; vp = kp + 512; }
;                 else { const size_t o = ((((size_t)l * 128 + b) * 256 + s) * 4 + h) * 128 + sub * 8; kp = p.in[I_CMK] + o; vp = p.in[I_CMV] + o; }
;                 if (SAMPLE) { pg8::ld8f_nt(kp, kk[it]); pg8::ld8f_nt(vp, vv[it]); } else { pg8::ld8f(kp, kk[it]); pg8::ld8f(vp, vv[it]); } }
; #pragma unroll
;             for (int it = 0; it < 4; ++it) { const int s = (tid >> 4) + 32 * (4 * hb + it);
;                 float (&k)[8] = kk[it]; float (&v)[8] = vv[it];
;                 if (!SAMPLE) { float ss = 0.f;
; #pragma unroll
;                     for (int e = 0; e < 8; ++e) ss += k[e] * k[e];
;                     ss += __shfl_xor(ss, 1); ss += __shfl_xor(ss, 2); ss += __shfl_xor(ss, 4); ss += __shfl_xor(ss, 8);
;                     const float rs = rsqrtf(ss * (1.f / 128.f) + EPS);
; #pragma unroll
;                     for (int e = 0; e < 8; ++e) k[e] *= rs * kg[e];
;                     if (qt == 0) { const size_t o = ((((size_t)l * 4 + b) * 256 + s) * 4 + h) * 128 + sub * 8;
;                         *(f32x4*)(p.out + O_MKP + o) = (f32x4){k[0], k[1], k[2], k[3]}; *(f32x4*)(p.out + O_MKP + o + 4) = (f32x4){k[4], k[5], k[6], k[7]};
;                         *(f32x4*)(p.out + O_MVP + o) = (f32x4){v[0], v[1], v[2], v[3]}; *(f32x4*)(p.out + O_MVP + o + 4) = (f32x4){v[4], v[5], v[6], v[7]}; }
;                 }
;                 *(LAS bf16x8*)(Kl + s * MEM_KS + sub * 8) = pack8(k);
;                 *(LAS bf16x8*)(Vt + s * MEM_VS + sub * 8) = pack8(v);
;     ...
;     if (!SAMPLE || wave == 0) {
; #pragma unroll 1
;       for (int qq = 0; qq < (SAMPLE ? 1 : 4); ++qq) {
;         int q16 = lane & 15, kq = lane >> 4; asm volatile("" : "+v"(q16), "+v"(kq));
;         size_t row; bool st;
.LBB0_2730:
	v_add_u32_e32 v66, s8, v81
	v_ashrrev_i32_e32 v67, 31, v66
	v_add_u32_e32 v6, 0x60, v66
	v_lshl_add_u64 v[8:9], v[66:67], 0, s[10:11]
	v_add_u32_e32 v2, 32, v66
	v_add_u32_e32 v4, 64, v66
	v_ashrrev_i32_e32 v7, 31, v6
	v_lshlrev_b64 v[8:9], 11, v[8:9]
	v_ashrrev_i32_e32 v3, 31, v2
	v_ashrrev_i32_e32 v5, 31, v4
	v_lshl_add_u64 v[6:7], v[6:7], 0, s[10:11]
	v_or_b32_e32 v8, v8, v0
	v_lshl_add_u64 v[2:3], v[2:3], 0, s[10:11]
	v_lshl_add_u64 v[4:5], v[4:5], 0, s[10:11]
	v_lshlrev_b64 v[22:23], 11, v[6:7]
	v_lshl_add_u64 v[6:7], s[78:79], 0, v[8:9]
	v_lshl_add_u64 v[14:15], s[80:81], 0, v[8:9]
	v_lshlrev_b64 v[18:19], 11, v[2:3]
	v_lshlrev_b64 v[20:21], 11, v[4:5]
	global_load_dwordx4 v[2:5], v[6:7], off nt
	s_nop 0
	global_load_dwordx4 v[6:9], v[6:7], off offset:16 nt
	s_nop 0
	global_load_dwordx4 v[10:13], v[14:15], off offset:16 nt
	s_nop 0
	global_load_dwordx4 v[14:17], v[14:15], off nt
	v_or_b32_e32 v18, v18, v0
	v_or_b32_e32 v20, v20, v0
	v_or_b32_e32 v22, v22, v0
	v_lshl_add_u64 v[24:25], s[78:79], 0, v[18:19]
	v_lshl_add_u64 v[30:31], s[80:81], 0, v[18:19]
	v_lshl_add_u64 v[38:39], s[78:79], 0, v[20:21]
	v_lshl_add_u64 v[46:47], s[80:81], 0, v[20:21]
	v_lshl_add_u64 v[54:55], s[78:79], 0, v[22:23]
	v_lshl_add_u64 v[62:63], s[80:81], 0, v[22:23]
	global_load_dwordx4 v[18:21], v[24:25], off nt
	s_nop 0
	global_load_dwordx4 v[22:25], v[24:25], off offset:16 nt
	s_nop 0
	global_load_dwordx4 v[26:29], v[30:31], off nt
	s_nop 0
	global_load_dwordx4 v[30:33], v[30:31], off offset:16 nt
	s_nop 0
	global_load_dwordx4 v[34:37], v[38:39], off nt
	s_nop 0
	global_load_dwordx4 v[38:41], v[38:39], off offset:16 nt
	s_nop 0
	global_load_dwordx4 v[42:45], v[46:47], off nt
	s_nop 0
	global_load_dwordx4 v[46:49], v[46:47], off offset:16 nt
	s_nop 0
	global_load_dwordx4 v[50:53], v[54:55], off nt
	s_nop 0
	global_load_dwordx4 v[54:57], v[54:55], off offset:16 nt
	s_nop 0
	global_load_dwordx4 v[58:61], v[62:63], off nt
	s_nop 0
	global_load_dwordx4 v[62:65], v[62:63], off offset:16 nt
	v_cndmask_b32_e64 v1, 0, 1, s[0:1]
	v_cmp_ne_u32_e32 vcc, 1, v1
	v_mul_lo_u32 v1, v66, s22
	v_add_u32_e32 v66, v96, v1
	v_add_u32_e32 v1, v97, v1
	s_movk_i32 s8, 0x80
	s_mov_b64 s[0:1], 0
	s_and_b64 vcc, exec, vcc
	s_waitcnt vmcnt(15)
	v_cvt_pk_bf16_f32 v2, v2, v3
	v_cvt_pk_bf16_f32 v3, v4, v5
	s_waitcnt vmcnt(14)
	v_cvt_pk_bf16_f32 v4, v6, v7
	v_cvt_pk_bf16_f32 v5, v8, v9
	ds_write_b128 v66, v[2:5]
	s_waitcnt vmcnt(12)
	v_cvt_pk_bf16_f32 v2, v14, v15
	v_cvt_pk_bf16_f32 v3, v16, v17
	v_cvt_pk_bf16_f32 v4, v10, v11
	v_cvt_pk_bf16_f32 v5, v12, v13
	ds_write_b128 v1, v[2:5]
	s_waitcnt vmcnt(11)
	v_cvt_pk_bf16_f32 v2, v18, v19
	v_cvt_pk_bf16_f32 v3, v20, v21
	s_waitcnt vmcnt(10)
	v_cvt_pk_bf16_f32 v4, v22, v23
	v_cvt_pk_bf16_f32 v5, v24, v25
	ds_write_b128 v66, v[2:5] offset:8704
	s_waitcnt vmcnt(9)
	v_cvt_pk_bf16_f32 v2, v26, v27
	v_cvt_pk_bf16_f32 v3, v28, v29
	s_waitcnt vmcnt(8)
	v_cvt_pk_bf16_f32 v4, v30, v31
	v_cvt_pk_bf16_f32 v5, v32, v33
	ds_write_b128 v1, v[2:5] offset:8704
	s_waitcnt vmcnt(7)
	v_cvt_pk_bf16_f32 v2, v34, v35
	v_cvt_pk_bf16_f32 v3, v36, v37
	s_waitcnt vmcnt(6)
	v_cvt_pk_bf16_f32 v4, v38, v39
	v_cvt_pk_bf16_f32 v5, v40, v41
	ds_write_b128 v66, v[2:5] offset:17408
	s_waitcnt vmcnt(5)
	v_cvt_pk_bf16_f32 v2, v42, v43
	v_cvt_pk_bf16_f32 v3, v44, v45
	s_waitcnt vmcnt(4)
	v_cvt_pk_bf16_f32 v4, v46, v47
	v_cvt_pk_bf16_f32 v5, v48, v49
	ds_write_b128 v1, v[2:5] offset:17408
	s_waitcnt vmcnt(3)
	v_cvt_pk_bf16_f32 v2, v50, v51
	v_cvt_pk_bf16_f32 v3, v52, v53
	s_waitcnt vmcnt(2)
	v_cvt_pk_bf16_f32 v4, v54, v55
	v_cvt_pk_bf16_f32 v5, v56, v57
	ds_write_b128 v66, v[2:5] offset:26112
	s_waitcnt vmcnt(1)
	v_cvt_pk_bf16_f32 v2, v58, v59
	v_cvt_pk_bf16_f32 v3, v60, v61
	s_waitcnt vmcnt(0)
	v_cvt_pk_bf16_f32 v4, v62, v63
	v_cvt_pk_bf16_f32 v5, v64, v65
	ds_write_b128 v1, v[2:5] offset:26112
	s_cbranch_vccz .LBB0_2730
	s_andn2_b64 vcc, exec, s[6:7]
	s_waitcnt lgkmcnt(0)
	s_barrier
	s_cbranch_vccnz .LBB0_2749
	s_lshl_b32 s0, s2, 3
	s_add_i32 s1, s0, 0x8000
	s_lshl_b32 s0, s3, 1
	v_mov_b32_e32 v37, v95
	v_mov_b32_e32 v36, v94
	s_add_u32 s2, s64, s0
	s_addc_u32 s3, s65, 0
	v_and_or_b32 v0, v36, 7, s1
	v_lshlrev_b32_e32 v82, 10, v0
	v_lshlrev_b32_e32 v16, 3, v37
	v_lshl_add_u64 v[0:1], s[2:3], 0, v[82:83]
	v_ashrrev_i32_e32 v17, 31, v16
	v_lshl_add_u64 v[12:13], v[16:17], 1, v[0:1]
	global_load_dwordx4 v[0:3], v[12:13], off
	global_load_dwordx4 v[4:7], v[12:13], off offset:64
	global_load_dwordx4 v[8:11], v[12:13], off offset:128
	s_nop 0
	global_load_dwordx4 v[12:15], v[12:13], off offset:192
	v_and_b32_e32 v19, 64, v99
	v_xor_b32_e32 v18, 16, v99
	v_add_u32_e32 v34, 64, v19
	v_cmp_lt_i32_e32 vcc, v18, v34
	v_lshl_add_u64 v[24:25], v[16:17], 2, s[46:47]
	s_waitcnt vmcnt(3)
	v_and_b32_e32 v40, 0xffff0000, v0
	v_cndmask_b32_e32 v18, v99, v18, vcc
	v_lshlrev_b32_e32 v38, 2, v18
	global_load_dwordx4 v[16:19], v[24:25], off offset:528
	global_load_dwordx4 v[20:23], v[24:25], off offset:512
	v_lshlrev_b32_e32 v35, 16, v0
	s_waitcnt vmcnt(3)
; __device__ __forceinline__ void unpack8(const v4u w, float (&o)[8]) { o[0] = bflo(w.x); o[1] = bfhi(w.x); o[2] = bflo(w.y); o[3] = bfhi(w.y); o[4] = bflo(w.z); o[5] = bfhi(w.z); o[6] = bflo(w.w); o[7] = bfhi(w.w); }
; __device__ __forceinline__ bf16x8 pack8(const float (&o)[8]) { v4u w; w.x = pk2(o[0], o[1]); w.y = pk2(o[2], o[3]); w.z = pk2(o[4], o[5]); w.w = pk2(o[6], o[7]); return __builtin_bit_cast(bf16x8, w); }
; template <bool SAMPLE>
; __device__ __forceinline__ void mem_unit(const Params& p, int l, LAS unsigned char* lds, int unit, int tid, int wave, int lane) {
;     ...
;             float qv[4][8]; float ss = 0.f;
; #pragma unroll
;             for (int dc = 0; dc < 4; ++dc) { unpack8(*(const v4u*)(MQ + row * 512 + h * 128 + 32 * dc + 8 * kq), qv[dc]);
; #pragma unroll
;                 for (int e = 0; e < 8; ++e) ss += qv[dc][e] * qv[dc][e]; }
;             ss += __shfl_xor(ss, 16); ss += __shfl_xor(ss, 32);
;             const float rs = rsqrtf(ss * (1.f / 128.f) + EPS) * 0.08838834764831845f;
; #pragma unroll
;             for (int dc = 0; dc < 4; ++dc) { float qg[8]; pg8::ld8f(p.in[I_MQG] + l * 128 + 32 * dc + 8 * kq, qg);
; #pragma unroll
;                 for (int e = 0; e < 8; ++e) qv[dc][e] *= rs * qg[e];
;                 qf[dc] = pack8(qv[dc]); }
	v_lshlrev_b32_e32 v55, 16, v8
	v_and_b32_e32 v56, 0xffff0000, v8
	v_mul_f32_e32 v8, v40, v40
	v_lshlrev_b32_e32 v41, 16, v1
	v_fmac_f32_e32 v8, v35, v35
	v_and_b32_e32 v42, 0xffff0000, v1
	v_fmac_f32_e32 v8, v41, v41
	v_lshlrev_b32_e32 v43, 16, v2
	v_fmac_f32_e32 v8, v42, v42
	v_and_b32_e32 v44, 0xffff0000, v2
	v_fmac_f32_e32 v8, v43, v43
	v_lshlrev_b32_e32 v45, 16, v3
	v_fmac_f32_e32 v8, v44, v44
	v_and_b32_e32 v46, 0xffff0000, v3
	v_fmac_f32_e32 v8, v45, v45
	v_lshlrev_b32_e32 v47, 16, v4
	v_fmac_f32_e32 v8, v46, v46
	v_and_b32_e32 v48, 0xffff0000, v4
	v_fmac_f32_e32 v8, v47, v47
	v_lshlrev_b32_e32 v49, 16, v5
	v_fmac_f32_e32 v8, v48, v48
	v_and_b32_e32 v50, 0xffff0000, v5
	v_fmac_f32_e32 v8, v49, v49
	v_lshlrev_b32_e32 v51, 16, v6
	v_fmac_f32_e32 v8, v50, v50
	v_and_b32_e32 v52, 0xffff0000, v6
	v_fmac_f32_e32 v8, v51, v51
	v_lshlrev_b32_e32 v53, 16, v7
	v_fmac_f32_e32 v8, v52, v52
	v_and_b32_e32 v54, 0xffff0000, v7
	v_fmac_f32_e32 v8, v53, v53
	v_fmac_f32_e32 v8, v54, v54
	v_fmac_f32_e32 v8, v55, v55
	v_lshlrev_b32_e32 v57, 16, v9
	v_fmac_f32_e32 v8, v56, v56
	v_and_b32_e32 v58, 0xffff0000, v9
	v_fmac_f32_e32 v8, v57, v57
	v_lshlrev_b32_e32 v59, 16, v10
	v_fmac_f32_e32 v8, v58, v58
	v_and_b32_e32 v60, 0xffff0000, v10
	v_fmac_f32_e32 v8, v59, v59
	v_lshlrev_b32_e32 v61, 16, v11
	v_fmac_f32_e32 v8, v60, v60
	v_and_b32_e32 v62, 0xffff0000, v11
	s_waitcnt vmcnt(2)
	v_and_b32_e32 v26, 0xffff0000, v12
	v_lshlrev_b32_e32 v27, 16, v12
	v_fmac_f32_e32 v8, v61, v61
	v_pk_mul_f32 v[0:1], v[26:27], v[26:27]
	v_fmac_f32_e32 v8, v62, v62
	v_and_b32_e32 v28, 0xffff0000, v13
	v_lshlrev_b32_e32 v29, 16, v13
	v_add_f32_e32 v1, v1, v8
	v_pk_mul_f32 v[2:3], v[28:29], v[28:29]
	v_add_f32_e32 v0, v0, v1
	v_and_b32_e32 v30, 0xffff0000, v14
	v_lshlrev_b32_e32 v31, 16, v14
	v_add_f32_e32 v0, v3, v0
	v_pk_mul_f32 v[4:5], v[30:31], v[30:31]
	v_add_f32_e32 v0, v2, v0
	v_and_b32_e32 v32, 0xffff0000, v15
	v_lshlrev_b32_e32 v33, 16, v15
	v_add_f32_e32 v0, v5, v0
	v_pk_mul_f32 v[6:7], v[32:33], v[32:33]
	v_add_f32_e32 v0, v4, v0
	v_add_f32_e32 v0, v7, v0
	v_add_f32_e32 v0, v6, v0
	ds_bpermute_b32 v1, v38, v0
	v_xor_b32_e32 v2, 32, v99
	v_cmp_lt_i32_e32 vcc, v2, v34
	s_waitcnt lgkmcnt(0)
	v_add_f32_e32 v0, v0, v1
	v_cndmask_b32_e32 v2, v99, v2, vcc
	v_lshlrev_b32_e32 v39, 2, v2
	ds_bpermute_b32 v1, v39, v0
	s_waitcnt lgkmcnt(0)
	v_add_f32_e32 v0, v0, v1
	v_fmamk_f32 v0, v0, 0x3c000000, v98
	v_mul_f32_e32 v1, 0x4b800000, v0
	v_cmp_gt_f32_e32 vcc, s23, v0
	s_nop 1
	v_cndmask_b32_e32 v0, v0, v1, vcc
	v_rsq_f32_e32 v0, v0
	s_nop 0
	v_mul_f32_e32 v1, 0x45800000, v0
	v_cndmask_b32_e32 v0, v0, v1, vcc
	v_mul_f32_e32 v34, 0x3db504f3, v0
	s_waitcnt vmcnt(0)
	v_mul_f32_e32 v0, v20, v34
	v_mul_f32_e32 v1, v21, v34
	v_mul_f32_e32 v2, v22, v34
	v_mul_f32_e32 v3, v23, v34
	v_mul_f32_e32 v4, v16, v34
	v_mul_f32_e32 v5, v17, v34
	v_mul_f32_e32 v6, v18, v34
	v_mul_f32_e32 v7, v19, v34
	v_mul_f32_e32 v0, v0, v35
	v_mul_f32_e32 v1, v1, v40
	v_mul_f32_e32 v2, v2, v41
	v_mul_f32_e32 v3, v3, v42
	v_mul_f32_e32 v4, v4, v43
	v_mul_f32_e32 v5, v5, v44
	v_mul_f32_e32 v6, v6, v45
	v_mul_f32_e32 v7, v7, v46
	v_cvt_pk_bf16_f32 v0, v0, v1
	v_cvt_pk_bf16_f32 v1, v2, v3
	v_cvt_pk_bf16_f32 v2, v4, v5
	v_cvt_pk_bf16_f32 v3, v6, v7
	global_load_dwordx4 v[4:7], v[24:25], off offset:640
	global_load_dwordx4 v[8:11], v[24:25], off offset:656
	v_lshlrev_b32_e32 v20, 4, v37
	v_mul_lo_u32 v21, v36, s22
	v_add3_u32 v92, 0, v20, v21
	s_waitcnt vmcnt(1)
	v_mul_f32_e32 v4, v4, v34
	v_mul_f32_e32 v5, v5, v34
	v_mul_f32_e32 v6, v6, v34
	v_mul_f32_e32 v7, v7, v34
	s_waitcnt vmcnt(0)
	v_mul_f32_e32 v8, v8, v34
	v_mul_f32_e32 v9, v9, v34
	v_mul_f32_e32 v10, v10, v34
	v_mul_f32_e32 v11, v11, v34
	v_mul_f32_e32 v4, v4, v47
	v_mul_f32_e32 v5, v5, v48
	v_mul_f32_e32 v6, v6, v49
	v_mul_f32_e32 v7, v7, v50
	v_mul_f32_e32 v12, v8, v51
	v_mul_f32_e32 v13, v9, v52
	v_mul_f32_e32 v14, v10, v53
	v_mul_f32_e32 v11, v11, v54
	v_cvt_pk_bf16_f32 v8, v4, v5
	v_cvt_pk_bf16_f32 v9, v6, v7
	v_cvt_pk_bf16_f32 v10, v12, v13
	v_cvt_pk_bf16_f32 v11, v14, v11
	global_load_dwordx4 v[4:7], v[24:25], off offset:768
	global_load_dwordx4 v[12:15], v[24:25], off offset:784
	s_waitcnt vmcnt(1)
	v_mul_f32_e32 v4, v4, v34
	v_mul_f32_e32 v5, v5, v34
	v_mul_f32_e32 v6, v6, v34
	v_mul_f32_e32 v7, v7, v34
	s_waitcnt vmcnt(0)
	v_mul_f32_e32 v12, v12, v34
	v_mul_f32_e32 v13, v13, v34
	v_mul_f32_e32 v14, v14, v34
	v_mul_f32_e32 v15, v15, v34
	v_mul_f32_e32 v4, v4, v55
	v_mul_f32_e32 v5, v5, v56
	v_mul_f32_e32 v6, v6, v57
	v_mul_f32_e32 v7, v7, v58
	v_mul_f32_e32 v12, v12, v59
	v_mul_f32_e32 v13, v13, v60
	v_mul_f32_e32 v14, v14, v61
	v_mul_f32_e32 v15, v15, v62
	v_cvt_pk_bf16_f32 v4, v4, v5
	v_cvt_pk_bf16_f32 v5, v6, v7
	v_cvt_pk_bf16_f32 v6, v12, v13
	v_cvt_pk_bf16_f32 v7, v14, v15
	global_load_dwordx4 v[12:15], v[24:25], off offset:896
	global_load_dwordx4 v[16:19], v[24:25], off offset:912
	s_waitcnt vmcnt(1)
	v_mul_f32_e32 v12, v12, v34
	v_mul_f32_e32 v13, v13, v34
	v_mul_f32_e32 v14, v14, v34
	v_mul_f32_e32 v15, v15, v34
	s_waitcnt vmcnt(0)
; #define LAS __attribute__((address_space(3)))
; template <bool SAMPLE>
; __device__ __forceinline__ void mem_unit(const Params& p, int l, LAS unsigned char* lds, int unit, int tid, int wave, int lane) {
;     ...
;         f32x4 S[8][2]; float mx = -INFINITY;
; #pragma unroll
;         for (int cc = 0; cc < 8; ++cc)
; #pragma unroll
;             for (int tt = 0; tt < 2; ++tt) { const int kb = 32 * cc + 16 * tt; f32x4 a = (f32x4){0.f, 0.f, 0.f, 0.f};
; #pragma unroll
;                 for (int dc = 0; dc < 4; ++dc) { const bf16x8 kf = *(const LAS bf16x8*)(Kl + (kb + q16) * MEM_KS + 32 * dc + 8 * kq);
;                     a = __builtin_amdgcn_mfma_f32_16x16x32_bf16(kf, qf[dc], a, 0, 0, 0); }
; #pragma unroll
;                 for (int e = 0; e < 4; ++e) mx = fmaxf(mx, a[e]);
;                 S[cc][tt] = a; }
	v_mul_f32_e32 v16, v16, v34
	v_mul_f32_e32 v17, v17, v34
	v_mul_f32_e32 v18, v18, v34
	v_mul_f32_e32 v19, v19, v34
	v_mul_f32_e32 v12, v12, v27
	v_mul_f32_e32 v13, v13, v26
	v_mul_f32_e32 v14, v14, v29
	v_mul_f32_e32 v15, v15, v28
	v_mul_f32_e32 v16, v16, v31
	v_mul_f32_e32 v17, v17, v30
	v_mul_f32_e32 v18, v18, v33
	v_mul_f32_e32 v19, v19, v32
	v_cvt_pk_bf16_f32 v32, v12, v13
	v_cvt_pk_bf16_f32 v33, v14, v15
	v_cvt_pk_bf16_f32 v34, v16, v17
	v_cvt_pk_bf16_f32 v35, v18, v19
	ds_read_b128 v[186:189], v92
	ds_read_b128 v[190:193], v92 offset:4352
	ds_read_b128 v[194:197], v92 offset:8704
	ds_read_b128 v[198:201], v92 offset:13056
	ds_read_b128 v[202:205], v92 offset:17408
	s_nop 0
	ds_read_b128 v[16:19], v92 offset:64
	s_nop 0
	ds_read_b128 v[24:27], v92 offset:4416
	s_nop 0
	ds_read_b128 v[40:43], v92 offset:8768
	s_nop 0
	ds_read_b128 v[48:51], v92 offset:13120
	s_nop 0
	ds_read_b128 v[56:59], v92 offset:17472
	ds_read_b128 v[60:63], v92 offset:21760
	ds_read_b128 v[64:67], v92 offset:21824
	ds_read_b128 v[68:71], v92 offset:26112
	ds_read_b128 v[72:75], v92 offset:26176
	ds_read_b128 v[76:79], v92 offset:30464
	ds_read_b128 v[88:91], v92 offset:30528
	ds_read_b128 v[100:103], v92 offset:34816
	ds_read_b128 v[104:107], v92 offset:34880
	ds_read_b128 v[108:111], v92 offset:39168
	ds_read_b128 v[112:115], v92 offset:39232
	ds_read_b128 v[116:119], v92 offset:43520
	ds_read_b128 v[120:123], v92 offset:43584
	ds_read_b128 v[124:127], v92 offset:47872
	ds_read_b128 v[128:131], v92 offset:47936
	ds_read_b128 v[132:135], v92 offset:52224
	ds_read_b128 v[136:139], v92 offset:52288
	ds_read_b128 v[140:143], v92 offset:56576
	ds_read_b128 v[144:147], v92 offset:56640
	ds_read_b128 v[148:151], v92 offset:60928
	ds_read_b128 v[152:155], v92 offset:60992
	ds_read_b128 v[156:159], v92 offset:65280
	ds_read_b128 v[160:163], v92 offset:65344
	s_waitcnt lgkmcnt(14)
	v_mfma_f32_16x16x32_bf16 v[12:15], v[186:189], v[0:3], 0
	v_mfma_f32_16x16x32_bf16 v[20:23], v[190:193], v[0:3], 0
	v_mfma_f32_16x16x32_bf16 v[28:31], v[194:197], v[0:3], 0
	v_mfma_f32_16x16x32_bf16 v[44:47], v[198:201], v[0:3], 0
	v_mfma_f32_16x16x32_bf16 v[52:55], v[202:205], v[0:3], 0
	v_mfma_f32_16x16x32_bf16 v[60:63], v[60:63], v[0:3], 0
	v_mfma_f32_16x16x32_bf16 v[68:71], v[68:71], v[0:3], 0
	v_mfma_f32_16x16x32_bf16 v[76:79], v[76:79], v[0:3], 0
	v_mfma_f32_16x16x32_bf16 v[100:103], v[100:103], v[0:3], 0
	s_waitcnt lgkmcnt(13)
	v_mfma_f32_16x16x32_bf16 v[108:111], v[108:111], v[0:3], 0
	s_waitcnt lgkmcnt(11)
	v_mfma_f32_16x16x32_bf16 v[116:119], v[116:119], v[0:3], 0
	s_waitcnt lgkmcnt(9)
	v_mfma_f32_16x16x32_bf16 v[124:127], v[124:127], v[0:3], 0
	s_waitcnt lgkmcnt(7)
	v_mfma_f32_16x16x32_bf16 v[132:135], v[132:135], v[0:3], 0
	s_waitcnt lgkmcnt(5)
	v_mfma_f32_16x16x32_bf16 v[140:143], v[140:143], v[0:3], 0
	s_waitcnt lgkmcnt(3)
	v_mfma_f32_16x16x32_bf16 v[148:151], v[148:151], v[0:3], 0
	s_waitcnt lgkmcnt(1)
	v_mfma_f32_16x16x32_bf16 v[0:3], v[156:159], v[0:3], 0
	v_mfma_f32_16x16x32_bf16 v[12:15], v[16:19], v[8:11], v[12:15]
	v_mfma_f32_16x16x32_bf16 v[16:19], v[24:27], v[8:11], v[20:23]
	v_mfma_f32_16x16x32_bf16 v[20:23], v[40:43], v[8:11], v[28:31]
	v_mfma_f32_16x16x32_bf16 v[24:27], v[48:51], v[8:11], v[44:47]
	v_mfma_f32_16x16x32_bf16 v[28:31], v[56:59], v[8:11], v[52:55]
	v_mfma_f32_16x16x32_bf16 v[40:43], v[64:67], v[8:11], v[60:63]
	v_mfma_f32_16x16x32_bf16 v[44:47], v[72:75], v[8:11], v[68:71]
	v_mfma_f32_16x16x32_bf16 v[48:51], v[88:91], v[8:11], v[76:79]
	v_mfma_f32_16x16x32_bf16 v[52:55], v[104:107], v[8:11], v[100:103]
	ds_read_b128 v[190:193], v92 offset:128
	ds_read_b128 v[194:197], v92 offset:4480
	ds_read_b128 v[198:201], v92 offset:8832
	ds_read_b128 v[202:205], v92 offset:13184
	v_mfma_f32_16x16x32_bf16 v[56:59], v[112:115], v[8:11], v[108:111]
	v_mfma_f32_16x16x32_bf16 v[60:63], v[120:123], v[8:11], v[116:119]
	v_mfma_f32_16x16x32_bf16 v[64:67], v[128:131], v[8:11], v[124:127]
	v_mfma_f32_16x16x32_bf16 v[68:71], v[136:139], v[8:11], v[132:135]
	v_mfma_f32_16x16x32_bf16 v[72:75], v[144:147], v[8:11], v[140:143]
	ds_read_b128 v[206:209], v92 offset:17536
	ds_read_b128 v[210:213], v92 offset:21888
	ds_read_b128 v[218:221], v92 offset:26240
	ds_read_b128 v[222:225], v92 offset:30592
	ds_read_b128 v[226:229], v92 offset:34944
	v_mfma_f32_16x16x32_bf16 v[76:79], v[152:155], v[8:11], v[148:151]
	s_waitcnt lgkmcnt(9)
	v_mfma_f32_16x16x32_bf16 v[0:3], v[160:163], v[8:11], v[0:3]
	s_nop 0
	ds_read_b128 v[88:91], v92 offset:192
	s_waitcnt lgkmcnt(9)
	v_mfma_f32_16x16x32_bf16 v[8:11], v[190:193], v[4:7], v[12:15]
	s_nop 2
	s_nop 0
	ds_read_b128 v[100:103], v92 offset:4544
	s_waitcnt lgkmcnt(9)
	v_mfma_f32_16x16x32_bf16 v[12:15], v[194:197], v[4:7], v[16:19]
	s_nop 2
	s_nop 0
	ds_read_b128 v[104:107], v92 offset:8896
	s_waitcnt lgkmcnt(9)
	v_mfma_f32_16x16x32_bf16 v[16:19], v[198:201], v[4:7], v[20:23]
	s_nop 2
	s_nop 0
	ds_read_b128 v[108:111], v92 offset:13248
	s_waitcnt lgkmcnt(9)
	v_mfma_f32_16x16x32_bf16 v[20:23], v[202:205], v[4:7], v[24:27]
	s_nop 2
	s_nop 0
	ds_read_b128 v[112:115], v92 offset:17600
	s_waitcnt lgkmcnt(9)
	ds_read_b128 v[186:189], v92 offset:39296
	ds_read_b128 v[190:193], v92 offset:43648
	ds_read_b128 v[194:197], v92 offset:48000
	ds_read_b128 v[198:201], v92 offset:52352
	ds_read_b128 v[202:205], v92 offset:56704
	v_mfma_f32_16x16x32_bf16 v[24:27], v[206:209], v[4:7], v[28:31]
	s_nop 2
	s_nop 0
	ds_read_b128 v[116:119], v92 offset:21952
	s_waitcnt lgkmcnt(14)
	v_mfma_f32_16x16x32_bf16 v[28:31], v[210:213], v[4:7], v[40:43]
	s_nop 2
	s_nop 0
	ds_read_b128 v[120:123], v92 offset:26304
	s_waitcnt lgkmcnt(14)
; #define LAS __attribute__((address_space(3)))
; template <bool SAMPLE>
; __device__ __forceinline__ void mem_unit(const Params& p, int l, LAS unsigned char* lds, int unit, int tid, int wave, int lane) {
;     ...
;         f32x4 S[8][2]; float mx = -INFINITY;
; #pragma unroll
;         for (int cc = 0; cc < 8; ++cc)
; #pragma unroll
;             for (int tt = 0; tt < 2; ++tt) { const int kb = 32 * cc + 16 * tt; f32x4 a = (f32x4){0.f, 0.f, 0.f, 0.f};
; #pragma unroll
;                 for (int dc = 0; dc < 4; ++dc) { const bf16x8 kf = *(const LAS bf16x8*)(Kl + (kb + q16) * MEM_KS + 32 * dc + 8 * kq);
;                     a = __builtin_amdgcn_mfma_f32_16x16x32_bf16(kf, qf[dc], a, 0, 0, 0); }
; #pragma unroll
;                 for (int e = 0; e < 4; ++e) mx = fmaxf(mx, a[e]);
;                 S[cc][tt] = a; }
;         mx = fmaxf(mx, __shfl_xor(mx, 16)); mx = fmaxf(mx, __shfl_xor(mx, 32));
;         float den = 0.f;
; #pragma unroll
;         for (int cc = 0; cc < 8; ++cc)
; #pragma unroll
;             for (int tt = 0; tt < 2; ++tt)
; #pragma unroll
;                 for (int e = 0; e < 4; ++e) { const float pe = __expf(S[cc][tt][e] - mx); S[cc][tt][e] = pe; den += pe; }
	v_mfma_f32_16x16x32_bf16 v[40:43], v[218:221], v[4:7], v[44:47]
	s_nop 2
	s_nop 0
	ds_read_b128 v[124:127], v92 offset:30656
	s_waitcnt lgkmcnt(14)
	v_mfma_f32_16x16x32_bf16 v[44:47], v[222:225], v[4:7], v[48:51]
	s_nop 2
	s_nop 0
	ds_read_b128 v[128:131], v92 offset:35008
	s_waitcnt lgkmcnt(14)
	v_mfma_f32_16x16x32_bf16 v[48:51], v[226:229], v[4:7], v[52:55]
	s_nop 2
	s_nop 0
	ds_read_b128 v[132:135], v92 offset:39360
	s_waitcnt lgkmcnt(9)
	ds_read_b128 v[206:209], v92 offset:61056
	ds_read_b128 v[210:213], v92 offset:65408
	v_mfma_f32_16x16x32_bf16 v[52:55], v[186:189], v[4:7], v[56:59]
	s_nop 2
	s_nop 0
	ds_read_b128 v[136:139], v92 offset:43712
	s_waitcnt lgkmcnt(11)
	v_mfma_f32_16x16x32_bf16 v[56:59], v[190:193], v[4:7], v[60:63]
	s_nop 2
	s_nop 0
	ds_read_b128 v[140:143], v92 offset:48064
	s_waitcnt lgkmcnt(11)
	v_mfma_f32_16x16x32_bf16 v[60:63], v[194:197], v[4:7], v[64:67]
	s_nop 2
	s_nop 0
	ds_read_b128 v[144:147], v92 offset:52416
	s_waitcnt lgkmcnt(11)
	v_mfma_f32_16x16x32_bf16 v[64:67], v[198:201], v[4:7], v[68:71]
	s_nop 2
	s_nop 0
	ds_read_b128 v[148:151], v92 offset:56768
	s_waitcnt lgkmcnt(11)
	v_mfma_f32_16x16x32_bf16 v[68:71], v[202:205], v[4:7], v[72:75]
	s_nop 2
	s_nop 0
	ds_read_b128 v[152:155], v92 offset:61120
	s_waitcnt lgkmcnt(6)
	v_mfma_f32_16x16x32_bf16 v[72:75], v[206:209], v[4:7], v[76:79]
	s_nop 2
	s_nop 0
	ds_read_b128 v[156:159], v92 offset:65472
	s_waitcnt lgkmcnt(6)
	v_mfma_f32_16x16x32_bf16 v[0:3], v[210:213], v[4:7], v[0:3]
	v_mfma_f32_16x16x32_bf16 v[76:79], v[88:91], v[32:35], v[8:11]
	v_mfma_f32_16x16x32_bf16 v[88:91], v[100:103], v[32:35], v[12:15]
	v_mfma_f32_16x16x32_bf16 v[100:103], v[104:107], v[32:35], v[16:19]
	v_mfma_f32_16x16x32_bf16 v[104:107], v[108:111], v[32:35], v[20:23]
	v_mfma_f32_16x16x32_bf16 v[108:111], v[112:115], v[32:35], v[24:27]
	v_mfma_f32_16x16x32_bf16 v[112:115], v[116:119], v[32:35], v[28:31]
	v_mfma_f32_16x16x32_bf16 v[40:43], v[120:123], v[32:35], v[40:43]
	v_mfma_f32_16x16x32_bf16 v[44:47], v[124:127], v[32:35], v[44:47]
	v_mfma_f32_16x16x32_bf16 v[28:31], v[128:131], v[32:35], v[48:51]
	v_mfma_f32_16x16x32_bf16 v[24:27], v[132:135], v[32:35], v[52:55]
	v_mfma_f32_16x16x32_bf16 v[20:23], v[136:139], v[32:35], v[56:59]
	v_mfma_f32_16x16x32_bf16 v[16:19], v[140:143], v[32:35], v[60:63]
	v_mfma_f32_16x16x32_bf16 v[12:15], v[144:147], v[32:35], v[64:67]
	v_mfma_f32_16x16x32_bf16 v[8:11], v[148:151], v[32:35], v[68:71]
	v_mfma_f32_16x16x32_bf16 v[4:7], v[152:155], v[32:35], v[72:75]
	s_waitcnt lgkmcnt(0)
	v_mfma_f32_16x16x32_bf16 v[0:3], v[156:159], v[32:35], v[0:3]
	v_max3_f32 v32, v76, s24, v77
	v_max3_f32 v32, v32, v78, v79
	v_max3_f32 v32, v32, v88, v89
	v_max3_f32 v32, v32, v90, v91
	v_max3_f32 v32, v32, v100, v101
	v_max3_f32 v32, v32, v102, v103
	v_max3_f32 v32, v32, v104, v105
	v_max3_f32 v32, v32, v106, v107
	v_max3_f32 v32, v32, v108, v109
	v_max3_f32 v32, v32, v110, v111
	v_max3_f32 v32, v32, v112, v113
	v_max3_f32 v32, v32, v114, v115
	v_max3_f32 v32, v32, v40, v41
	v_max3_f32 v32, v32, v42, v43
	v_max3_f32 v32, v32, v44, v45
	v_max3_f32 v32, v32, v46, v47
	v_max3_f32 v32, v32, v28, v29
	v_max3_f32 v32, v32, v30, v31
	v_max3_f32 v32, v32, v24, v25
	v_max3_f32 v32, v32, v26, v27
	v_max3_f32 v32, v32, v20, v21
	v_max3_f32 v32, v32, v22, v23
	v_max3_f32 v32, v32, v16, v17
	v_max3_f32 v32, v32, v18, v19
	v_max3_f32 v32, v32, v12, v13
	v_max3_f32 v32, v32, v14, v15
	v_max3_f32 v32, v32, v8, v9
	v_max3_f32 v32, v32, v10, v11
	v_max3_f32 v32, v32, v4, v5
	v_max3_f32 v32, v32, v6, v7
	v_max3_f32 v32, v32, v0, v1
	v_max3_f32 v32, v32, v2, v3
	ds_bpermute_b32 v33, v38, v32
	s_waitcnt lgkmcnt(0)
	v_max_f32_e32 v33, v33, v33
	v_max_f32_e32 v32, v32, v33
	ds_bpermute_b32 v33, v39, v32
	s_waitcnt lgkmcnt(0)
	v_max_f32_e32 v33, v33, v33
	v_max_f32_e32 v32, v32, v33
	v_sub_f32_e32 v33, v76, v32
	v_sub_f32_e32 v34, v77, v32
	v_mul_f32_e32 v33, 0x3fb8aa3b, v33
	v_sub_f32_e32 v35, v78, v32
	v_mul_f32_e32 v34, 0x3fb8aa3b, v34
	v_exp_f32_e32 v33, v33
	v_sub_f32_e32 v48, v79, v32
	v_mul_f32_e32 v35, 0x3fb8aa3b, v35
	v_exp_f32_e32 v34, v34
	v_sub_f32_e32 v49, v88, v32
	v_mul_f32_e32 v48, 0x3fb8aa3b, v48
	v_exp_f32_e32 v35, v35
	v_sub_f32_e32 v50, v89, v32
	v_mul_f32_e32 v49, 0x3fb8aa3b, v49
	v_exp_f32_e32 v48, v48
	v_sub_f32_e32 v51, v90, v32
	v_mul_f32_e32 v50, 0x3fb8aa3b, v50
	v_exp_f32_e32 v49, v49
	v_add_f32_e32 v69, 0, v33
	v_sub_f32_e32 v52, v91, v32
	v_mul_f32_e32 v51, 0x3fb8aa3b, v51
	v_exp_f32_e32 v50, v50
	v_add_f32_e32 v69, v34, v69
	v_sub_f32_e32 v53, v100, v32
	v_mul_f32_e32 v52, 0x3fb8aa3b, v52
	v_exp_f32_e32 v51, v51
	v_add_f32_e32 v69, v35, v69
	v_sub_f32_e32 v54, v101, v32
	v_mul_f32_e32 v53, 0x3fb8aa3b, v53
	v_exp_f32_e32 v52, v52
	v_add_f32_e32 v69, v48, v69
	v_sub_f32_e32 v55, v102, v32
	v_mul_f32_e32 v54, 0x3fb8aa3b, v54
	v_exp_f32_e32 v53, v53
	v_add_f32_e32 v69, v49, v69
	v_sub_f32_e32 v56, v103, v32
	v_mul_f32_e32 v55, 0x3fb8aa3b, v55
	v_exp_f32_e32 v54, v54
	v_add_f32_e32 v69, v50, v69
	v_sub_f32_e32 v57, v104, v32
	v_mul_f32_e32 v56, 0x3fb8aa3b, v56
	v_exp_f32_e32 v55, v55
	v_add_f32_e32 v69, v51, v69
	v_sub_f32_e32 v58, v105, v32
	v_mul_f32_e32 v57, 0x3fb8aa3b, v57
	v_exp_f32_e32 v56, v56
	v_add_f32_e32 v69, v52, v69
	v_sub_f32_e32 v59, v106, v32
	v_mul_f32_e32 v58, 0x3fb8aa3b, v58
	v_exp_f32_e32 v57, v57
	v_add_f32_e32 v69, v53, v69
	v_sub_f32_e32 v60, v107, v32
	v_mul_f32_e32 v59, 0x3fb8aa3b, v59
	v_exp_f32_e32 v58, v58
	v_add_f32_e32 v69, v54, v69
	v_sub_f32_e32 v61, v108, v32
	v_mul_f32_e32 v60, 0x3fb8aa3b, v60
	v_exp_f32_e32 v59, v59
	v_add_f32_e32 v69, v55, v69
	v_sub_f32_e32 v62, v109, v32
	v_mul_f32_e32 v61, 0x3fb8aa3b, v61
	v_exp_f32_e32 v60, v60
; __device__ __forceinline__ bf16x8 pack8(const float (&o)[8]) { v4u w; w.x = pk2(o[0], o[1]); w.y = pk2(o[2], o[3]); w.z = pk2(o[4], o[5]); w.w = pk2(o[6], o[7]); return __builtin_bit_cast(bf16x8, w); }
; template <bool SAMPLE>
; __device__ __forceinline__ void mem_unit(const Params& p, int l, LAS unsigned char* lds, int unit, int tid, int wave, int lane) {
;     ...
;         mx = fmaxf(mx, __shfl_xor(mx, 16)); mx = fmaxf(mx, __shfl_xor(mx, 32));
;         float den = 0.f;
; #pragma unroll
;         for (int cc = 0; cc < 8; ++cc)
; #pragma unroll
;             for (int tt = 0; tt < 2; ++tt)
; #pragma unroll
;                 for (int e = 0; e < 4; ++e) { const float pe = __expf(S[cc][tt][e] - mx); S[cc][tt][e] = pe; den += pe; }
;         den += __shfl_xor(den, 16); den += __shfl_xor(den, 32);
;         const float rden = 1.f / den;
;         bf16x8 pf[8];
; #pragma unroll
;         for (int cc = 0; cc < 8; ++cc) { float t8[8];
; #pragma unroll
;             for (int e = 0; e < 4; ++e) { t8[e] = S[cc][0][e]; t8[4 + e] = S[cc][1][e]; }
;             pf[cc] = pack8(t8); }
	v_add_f32_e32 v69, v56, v69
	v_sub_f32_e32 v63, v110, v32
	v_mul_f32_e32 v62, 0x3fb8aa3b, v62
	v_exp_f32_e32 v61, v61
	v_add_f32_e32 v69, v57, v69
	v_sub_f32_e32 v64, v111, v32
	v_mul_f32_e32 v63, 0x3fb8aa3b, v63
	v_exp_f32_e32 v62, v62
	v_add_f32_e32 v69, v58, v69
	v_sub_f32_e32 v65, v112, v32
	v_mul_f32_e32 v64, 0x3fb8aa3b, v64
	v_exp_f32_e32 v63, v63
	v_add_f32_e32 v69, v59, v69
	v_sub_f32_e32 v66, v113, v32
	v_mul_f32_e32 v65, 0x3fb8aa3b, v65
	v_exp_f32_e32 v64, v64
	v_add_f32_e32 v69, v60, v69
	v_sub_f32_e32 v67, v114, v32
	v_mul_f32_e32 v66, 0x3fb8aa3b, v66
	v_exp_f32_e32 v65, v65
	v_add_f32_e32 v69, v61, v69
	v_sub_f32_e32 v68, v115, v32
	v_mul_f32_e32 v67, 0x3fb8aa3b, v67
	v_exp_f32_e32 v66, v66
	v_add_f32_e32 v69, v62, v69
	v_sub_f32_e32 v40, v40, v32
	v_mul_f32_e32 v68, 0x3fb8aa3b, v68
	v_exp_f32_e32 v67, v67
	v_add_f32_e32 v69, v63, v69
	v_sub_f32_e32 v41, v41, v32
	v_mul_f32_e32 v40, 0x3fb8aa3b, v40
	v_exp_f32_e32 v68, v68
	v_add_f32_e32 v69, v64, v69
	v_sub_f32_e32 v42, v42, v32
	v_mul_f32_e32 v41, 0x3fb8aa3b, v41
	v_exp_f32_e32 v40, v40
	v_add_f32_e32 v69, v65, v69
	v_sub_f32_e32 v43, v43, v32
	v_mul_f32_e32 v42, 0x3fb8aa3b, v42
	v_exp_f32_e32 v41, v41
	v_add_f32_e32 v69, v66, v69
	v_sub_f32_e32 v44, v44, v32
	v_mul_f32_e32 v43, 0x3fb8aa3b, v43
	v_exp_f32_e32 v42, v42
	v_add_f32_e32 v69, v67, v69
	v_sub_f32_e32 v45, v45, v32
	v_mul_f32_e32 v44, 0x3fb8aa3b, v44
	v_exp_f32_e32 v43, v43
	v_add_f32_e32 v69, v68, v69
	v_sub_f32_e32 v46, v46, v32
	v_mul_f32_e32 v45, 0x3fb8aa3b, v45
	v_exp_f32_e32 v44, v44
	v_add_f32_e32 v69, v40, v69
	v_sub_f32_e32 v47, v47, v32
	v_mul_f32_e32 v46, 0x3fb8aa3b, v46
	v_exp_f32_e32 v45, v45
	v_add_f32_e32 v69, v41, v69
	v_sub_f32_e32 v28, v28, v32
	v_mul_f32_e32 v47, 0x3fb8aa3b, v47
	v_exp_f32_e32 v46, v46
	v_add_f32_e32 v69, v42, v69
	v_sub_f32_e32 v29, v29, v32
	v_mul_f32_e32 v28, 0x3fb8aa3b, v28
	v_exp_f32_e32 v47, v47
	v_add_f32_e32 v69, v43, v69
	v_exp_f32_e32 v28, v28
	v_add_f32_e32 v69, v44, v69
	v_mul_f32_e32 v29, 0x3fb8aa3b, v29
	v_sub_f32_e32 v30, v30, v32
	v_sub_f32_e32 v24, v24, v32
	v_add_f32_e32 v69, v45, v69
	v_exp_f32_e32 v29, v29
	v_mul_f32_e32 v30, 0x3fb8aa3b, v30
	v_sub_f32_e32 v31, v31, v32
	v_mul_f32_e32 v24, 0x3fb8aa3b, v24
	v_add_f32_e32 v69, v46, v69
	v_exp_f32_e32 v30, v30
	v_mul_f32_e32 v31, 0x3fb8aa3b, v31
	v_exp_f32_e32 v70, v24
	v_sub_f32_e32 v24, v25, v32
	v_add_f32_e32 v69, v47, v69
	v_exp_f32_e32 v31, v31
	v_mul_f32_e32 v24, 0x3fb8aa3b, v24
	v_add_f32_e32 v69, v28, v69
	v_exp_f32_e32 v71, v24
	v_sub_f32_e32 v24, v26, v32
	v_add_f32_e32 v69, v29, v69
	v_mul_f32_e32 v24, 0x3fb8aa3b, v24
	v_add_f32_e32 v69, v30, v69
	v_exp_f32_e32 v72, v24
	v_sub_f32_e32 v24, v27, v32
	v_sub_f32_e32 v20, v20, v32
	v_add_f32_e32 v69, v31, v69
	v_mul_f32_e32 v24, 0x3fb8aa3b, v24
	v_mul_f32_e32 v20, 0x3fb8aa3b, v20
	v_exp_f32_e32 v73, v24
	v_add_f32_e32 v24, v70, v69
	v_exp_f32_e32 v69, v20
	v_sub_f32_e32 v20, v21, v32
	v_mul_f32_e32 v20, 0x3fb8aa3b, v20
	v_exp_f32_e32 v74, v20
	v_sub_f32_e32 v20, v22, v32
	v_sub_f32_e32 v16, v16, v32
	v_mul_f32_e32 v20, 0x3fb8aa3b, v20
	v_mul_f32_e32 v16, 0x3fb8aa3b, v16
	v_add_f32_e32 v24, v71, v24
	v_exp_f32_e32 v75, v20
	v_sub_f32_e32 v20, v23, v32
	v_exp_f32_e32 v77, v16
	v_sub_f32_e32 v16, v17, v32
	v_add_f32_e32 v24, v72, v24
	v_mul_f32_e32 v20, 0x3fb8aa3b, v20
	v_mul_f32_e32 v16, 0x3fb8aa3b, v16
	v_add_f32_e32 v24, v73, v24
	v_exp_f32_e32 v76, v20
	v_exp_f32_e32 v78, v16
	v_sub_f32_e32 v16, v18, v32
	v_sub_f32_e32 v12, v12, v32
	v_add_f32_e32 v20, v69, v24
	v_mul_f32_e32 v16, 0x3fb8aa3b, v16
	v_mul_f32_e32 v12, 0x3fb8aa3b, v12
	v_add_f32_e32 v20, v74, v20
	v_exp_f32_e32 v79, v16
	v_sub_f32_e32 v16, v19, v32
	v_exp_f32_e32 v89, v12
	v_sub_f32_e32 v12, v13, v32
	v_add_f32_e32 v20, v75, v20
	v_mul_f32_e32 v16, 0x3fb8aa3b, v16
	v_mul_f32_e32 v12, 0x3fb8aa3b, v12
	v_add_f32_e32 v20, v76, v20
	v_exp_f32_e32 v88, v16
	v_exp_f32_e32 v90, v12
	v_sub_f32_e32 v12, v14, v32
	v_sub_f32_e32 v8, v8, v32
	v_add_f32_e32 v16, v77, v20
	v_mul_f32_e32 v12, 0x3fb8aa3b, v12
	v_mul_f32_e32 v8, 0x3fb8aa3b, v8
	v_add_f32_e32 v16, v78, v16
	v_exp_f32_e32 v91, v12
	v_sub_f32_e32 v12, v15, v32
	v_exp_f32_e32 v93, v8
	v_sub_f32_e32 v8, v9, v32
	v_add_f32_e32 v16, v79, v16
	v_mul_f32_e32 v12, 0x3fb8aa3b, v12
	v_mul_f32_e32 v8, 0x3fb8aa3b, v8
	v_add_f32_e32 v16, v88, v16
	v_exp_f32_e32 v92, v12
	v_exp_f32_e32 v100, v8
	v_sub_f32_e32 v8, v10, v32
	v_sub_f32_e32 v4, v4, v32
	v_add_f32_e32 v12, v89, v16
	v_mul_f32_e32 v8, 0x3fb8aa3b, v8
	v_mul_f32_e32 v4, 0x3fb8aa3b, v4
	v_add_f32_e32 v12, v90, v12
	v_exp_f32_e32 v101, v8
	v_sub_f32_e32 v8, v11, v32
	v_exp_f32_e32 v103, v4
	v_sub_f32_e32 v4, v5, v32
	v_add_f32_e32 v12, v91, v12
	v_mul_f32_e32 v8, 0x3fb8aa3b, v8
	v_mul_f32_e32 v4, 0x3fb8aa3b, v4
	v_add_f32_e32 v12, v92, v12
	v_exp_f32_e32 v102, v8
	v_exp_f32_e32 v104, v4
	v_sub_f32_e32 v4, v6, v32
	v_sub_f32_e32 v0, v0, v32
	v_add_f32_e32 v8, v93, v12
	v_mul_f32_e32 v4, 0x3fb8aa3b, v4
	v_mul_f32_e32 v0, 0x3fb8aa3b, v0
	v_add_f32_e32 v8, v100, v8
	v_exp_f32_e32 v105, v4
	v_sub_f32_e32 v4, v7, v32
	v_exp_f32_e32 v107, v0
	v_sub_f32_e32 v0, v1, v32
	v_add_f32_e32 v8, v101, v8
	v_mul_f32_e32 v4, 0x3fb8aa3b, v4
	v_mul_f32_e32 v0, 0x3fb8aa3b, v0
	v_add_f32_e32 v8, v102, v8
	v_exp_f32_e32 v106, v4
	v_exp_f32_e32 v108, v0
	v_sub_f32_e32 v0, v2, v32
	v_add_f32_e32 v4, v103, v8
	v_mul_f32_e32 v0, 0x3fb8aa3b, v0
	v_add_f32_e32 v4, v104, v4
	v_exp_f32_e32 v109, v0
	v_sub_f32_e32 v0, v3, v32
	v_add_f32_e32 v4, v105, v4
	v_mul_f32_e32 v0, 0x3fb8aa3b, v0
	v_add_f32_e32 v4, v106, v4
	v_exp_f32_e32 v32, v0
	v_add_f32_e32 v0, v107, v4
	v_add_f32_e32 v0, v108, v0
	v_add_f32_e32 v0, v109, v0
	v_add_f32_e32 v0, v32, v0
	ds_bpermute_b32 v1, v38, v0
	v_cvt_pk_bf16_f32 v24, v33, v34
	v_cvt_pk_bf16_f32 v25, v35, v48
	v_cvt_pk_bf16_f32 v26, v49, v50
	v_cvt_pk_bf16_f32 v27, v51, v52
	s_waitcnt lgkmcnt(0)
; #define LAS __attribute__((address_space(3)))
; __device__ __forceinline__ unsigned pk2(float lo, float hi) { return pg8::cvt_pk_bf16(lo, hi); }
; __device__ __forceinline__ bf16x8 pack8(const float (&o)[8]) { v4u w; w.x = pk2(o[0], o[1]); w.y = pk2(o[2], o[3]); w.z = pk2(o[4], o[5]); w.w = pk2(o[6], o[7]); return __builtin_bit_cast(bf16x8, w); }
; __device__ __forceinline__ v2u vtr(const LAS bf16* p) { return __builtin_bit_cast(v2u, __builtin_amdgcn_ds_read_tr16_b64_v4i16((LAS v4i16_t*)p)); }
; template <bool SAMPLE>
; __device__ __forceinline__ void mem_unit(const Params& p, int l, LAS unsigned char* lds, int unit, int tid, int wave, int lane) {
;     ...
;         den += __shfl_xor(den, 16); den += __shfl_xor(den, 32);
;         const float rden = 1.f / den;
;         bf16x8 pf[8];
; #pragma unroll
;         for (int cc = 0; cc < 8; ++cc) { float t8[8];
; #pragma unroll
;             for (int e = 0; e < 4; ++e) { t8[e] = S[cc][0][e]; t8[4 + e] = S[cc][1][e]; }
;             pf[cc] = pack8(t8); }
; #pragma unroll
;         for (int dt = 0; dt < 8; ++dt) { f32x4 o = (f32x4){0.f, 0.f, 0.f, 0.f};
; #pragma unroll
;             for (int cc = 0; cc < 8; ++cc) { const LAS bf16* vp = Vt + (32 * cc + 4 * kq + (q16 >> 2)) * MEM_VS + 16 * dt + 4 * (q16 & 3);
;                 const v2u lo = vtr(vp), hi = vtr(vp + 16 * MEM_VS);
;                 v4u av; av.x = lo.x; av.y = lo.y; av.z = hi.x; av.w = hi.y;
;                 o = __builtin_amdgcn_mfma_f32_16x16x32_bf16(__builtin_bit_cast(bf16x8, av), pf[cc], o, 0, 0, 0); }
;             if (st) { v2u w; w.x = pk2(o[0] * rden, o[1] * rden); w.y = pk2(o[2] * rden, o[3] * rden);
;                 *(v2u*)(MO + row * 512 + h * 128 + 16 * dt + 4 * kq) = w; } }
	v_add_f32_e32 v0, v0, v1
	ds_bpermute_b32 v1, v39, v0
	v_cvt_pk_bf16_f32 v20, v53, v54
	v_cvt_pk_bf16_f32 v21, v55, v56
	v_cvt_pk_bf16_f32 v22, v57, v58
	v_cvt_pk_bf16_f32 v23, v59, v60
	s_waitcnt lgkmcnt(0)
	v_add_f32_e32 v39, v0, v1
	v_cvt_pk_bf16_f32 v16, v61, v62
	v_cvt_pk_bf16_f32 v17, v63, v64
	v_cvt_pk_bf16_f32 v18, v65, v66
	v_cvt_pk_bf16_f32 v19, v67, v68
	v_cvt_pk_bf16_f32 v12, v40, v41
	v_cvt_pk_bf16_f32 v13, v42, v43
	v_cvt_pk_bf16_f32 v14, v44, v45
	v_cvt_pk_bf16_f32 v15, v46, v47
	v_cvt_pk_bf16_f32 v8, v28, v29
	v_cvt_pk_bf16_f32 v9, v30, v31
	v_cvt_pk_bf16_f32 v10, v70, v71
	v_cvt_pk_bf16_f32 v11, v72, v73
	v_cvt_pk_bf16_f32 v4, v69, v74
	v_cvt_pk_bf16_f32 v5, v75, v76
	v_cvt_pk_bf16_f32 v6, v77, v78
	v_cvt_pk_bf16_f32 v7, v79, v88
	v_cvt_pk_bf16_f32 v0, v89, v90
	v_cvt_pk_bf16_f32 v1, v91, v92
	v_cvt_pk_bf16_f32 v2, v93, v100
	v_cvt_pk_bf16_f32 v3, v101, v102
	v_cvt_pk_bf16_f32 v28, v103, v104
	v_cvt_pk_bf16_f32 v29, v105, v106
	v_cvt_pk_bf16_f32 v30, v107, v108
	v_cvt_pk_bf16_f32 v31, v109, v32
	v_lshlrev_b32_e32 v52, 2, v37
	v_lshrrev_b32_e32 v32, 2, v36
	v_add_u32_e32 v32, v32, v52
	v_lshlrev_b32_e32 v33, 3, v36
	v_and_b32_e32 v33, 24, v33
	v_mul_lo_u32 v32, v32, s22
	v_add3_u32 v38, s90, v33, v32
	ds_read_b64_tr_b16 v[194:195], v38
	ds_read_b64_tr_b16 v[196:197], v38 offset:4352
	ds_read_b64_tr_b16 v[198:199], v38 offset:8704
	ds_read_b64_tr_b16 v[200:201], v38 offset:13056
	ds_read_b64_tr_b16 v[202:203], v38 offset:17408
	ds_read_b64_tr_b16 v[204:205], v38 offset:21760
	ds_read_b64_tr_b16 v[206:207], v38 offset:26112
	ds_read_b64_tr_b16 v[208:209], v38 offset:30464
	ds_read_b64_tr_b16 v[210:211], v38 offset:34816
	ds_read_b64_tr_b16 v[212:213], v38 offset:39168
	s_nop 3
	s_waitcnt lgkmcnt(8)
	v_mfma_f32_16x16x32_bf16 v[32:35], v[194:197], v[24:27], 0
	s_nop 3
	v_div_scale_f32 v53, s[2:3], v39, v39, 1.0
	s_waitcnt lgkmcnt(6)
	v_mfma_f32_16x16x32_bf16 v[32:35], v[198:201], v[20:23], v[32:35]
	s_nop 1
	v_rcp_f32_e32 v37, v53
	s_add_u32 s2, s70, s0
	s_waitcnt lgkmcnt(4)
	v_mfma_f32_16x16x32_bf16 v[32:35], v[202:205], v[16:19], v[32:35]
	ds_read_b64_tr_b16 v[44:45], v38 offset:43520
	ds_read_b64_tr_b16 v[46:47], v38 offset:47872
	v_cmp_gt_i32_e64 s[0:1], 8, v36
	v_fma_f32 v36, -v53, v37, 1.0
	s_waitcnt lgkmcnt(4)
	v_mfma_f32_16x16x32_bf16 v[32:35], v[206:209], v[12:15], v[32:35]
	ds_read_b64_tr_b16 v[48:49], v38 offset:52224
	ds_read_b64_tr_b16 v[50:51], v38 offset:56576
	v_fmac_f32_e32 v37, v36, v37
	v_div_scale_f32 v36, vcc, 1.0, v39, 1.0
	s_waitcnt lgkmcnt(4)
	v_mfma_f32_16x16x32_bf16 v[32:35], v[210:213], v[8:11], v[32:35]
	ds_read_b64_tr_b16 v[40:41], v38 offset:60928
	ds_read_b64_tr_b16 v[42:43], v38 offset:65280
	v_mul_f32_e32 v54, v36, v37
	v_fma_f32 v55, -v53, v54, v36
	s_waitcnt lgkmcnt(4)
	v_mfma_f32_16x16x32_bf16 v[32:35], v[44:47], v[4:7], v[32:35]
	v_fmac_f32_e32 v54, v55, v37
	v_fma_f32 v36, -v53, v54, v36
	s_addc_u32 s3, s71, 0
	s_waitcnt lgkmcnt(2)
	v_mfma_f32_16x16x32_bf16 v[32:35], v[48:51], v[0:3], v[32:35]
	v_div_fmas_f32 v36, v36, v37, v54
	v_div_fixup_f32 v39, v36, v39, 1.0
	v_lshl_add_u64 v[36:37], s[2:3], 0, v[82:83]
	s_waitcnt lgkmcnt(0)
	v_mfma_f32_16x16x32_bf16 v[32:35], v[40:43], v[28:31], v[32:35]
	v_ashrrev_i32_e32 v53, 31, v52
	v_lshl_add_u64 v[36:37], v[52:53], 1, v[36:37]
	s_and_saveexec_b64 s[2:3], s[0:1]
	s_cbranch_execz .LBB0_2734
	s_nop 3
	v_mul_f32_e32 v32, v32, v39
	v_mul_f32_e32 v33, v33, v39
	v_cvt_pk_bf16_f32 v32, v32, v33
	v_mul_f32_e32 v33, v34, v39
	v_mul_f32_e32 v34, v35, v39
	v_cvt_pk_bf16_f32 v33, v33, v34
	global_store_dwordx2 v[36:37], v[32:33], off

; __device__ __forceinline__ void unpack8(const v4u w, float (&o)[8]) { o[0] = bflo(w.x); o[1] = bfhi(w.x); o[2] = bflo(w.y); o[3] = bfhi(w.y); o[4] = bflo(w.z); o[5] = bfhi(w.z); o[6] = bflo(w.w); o[7] = bfhi(w.w); }
; template <bool SAMPLE>
; __device__ __forceinline__ void mem_unit(const Params& p, int l, LAS unsigned char* lds, int unit, int tid, int wave, int lane) {
;     ...
;       for (int qq = 0; qq < (SAMPLE ? 1 : 4); ++qq) {
;         int q16 = lane & 15, kq = lane >> 4; asm volatile("" : "+v"(q16), "+v"(kq));
;         size_t row; bool st;
;         if (!SAMPLE) { row = (size_t)b * 8192 + (qt * 4 + qq) * 128 + 16 * wave + q16; st = true; } else { row = (size_t)MP + 8 * b + (q16 & 7); st = q16 < 8; }
;         bf16x8 qf[4];
;         {
;             float qv[4][8]; float ss = 0.f;
; #pragma unroll
;             for (int dc = 0; dc < 4; ++dc) { unpack8(*(const v4u*)(MQ + row * 512 + h * 128 + 32 * dc + 8 * kq), qv[dc]);
.LBB0_2761:
	s_and_b32 s0, s25, 15
	s_lshl_b32 s10, s0, 9
	s_lshl_b64 s[8:9], s[2:3], 13
	s_lshl_b32 s2, s27, 1
	s_add_u32 s0, s64, s2
	s_addc_u32 s1, s65, 0
	v_xor_b32_e32 v0, 16, v99
	s_add_u32 s2, s70, s2
	v_cmp_lt_i32_e32 vcc, v0, v92
	s_addc_u32 s3, s71, 0
	s_add_u32 s8, s4, s8
	v_cndmask_b32_e32 v0, v99, v0, vcc
	v_lshlrev_b32_e32 v82, 2, v0
	v_xor_b32_e32 v0, 32, v99
	v_cmp_lt_i32_e32 vcc, v0, v92
	s_addc_u32 s9, s5, s9
	s_add_u32 s10, s8, s10
	v_cndmask_b32_e32 v0, v99, v0, vcc
	v_lshlrev_b32_e32 v100, 2, v0
	s_addc_u32 s18, s9, 0
	s_mov_b64 s[8:9], 0
	s_waitcnt lgkmcnt(0)
	s_barrier
	s_mov_b32 s100, 0
.LBB0_2762:
	v_mov_b32_e32 v92, v95
	v_mov_b32_e32 v90, v94
	s_add_u32 s16, s10, s8
	s_addc_u32 s17, s18, s9
	v_ashrrev_i32_e32 v91, 31, v90
	v_lshl_add_u64 v[0:1], s[16:17], 0, v[90:91]
	v_lshlrev_b32_e32 v8, 3, v92
	v_lshlrev_b64 v[88:89], 10, v[0:1]
	v_ashrrev_i32_e32 v9, 31, v8
	v_lshl_add_u64 v[10:11], s[0:1], 0, v[88:89]
	v_lshlrev_b32_e32 v2, 4, v92
	v_mul_lo_u32 v3, v90, s22
	v_lshl_add_u64 v[24:25], v[8:9], 2, s[46:47]
	v_lshl_add_u64 v[20:21], v[8:9], 1, v[10:11]
	v_add3_u32 v91, 0, v2, v3
	global_load_dwordx4 v[0:3], v[24:25], off offset:528
	global_load_dwordx4 v[4:7], v[24:25], off offset:512
	s_cmp_lg_u32 s100, 0
	s_cbranch_scc1 .Lqpf_have_1
	global_load_dwordx4 v[234:237], v[20:21], off
	global_load_dwordx4 v[242:245], v[20:21], off offset:64
	global_load_dwordx4 v[246:249], v[20:21], off offset:128
	global_load_dwordx4 v[250:253], v[20:21], off offset:192
	s_waitcnt vmcnt(0)
	s_branch .Lqpf_go_1

; __device__ __forceinline__ void unpack8(const v4u w, float (&o)[8]) { o[0] = bflo(w.x); o[1] = bfhi(w.x); o[2] = bflo(w.y); o[3] = bfhi(w.y); o[4] = bflo(w.z); o[5] = bfhi(w.z); o[6] = bflo(w.w); o[7] = bfhi(w.w); }
; __device__ __forceinline__ bf16x8 pack8(const float (&o)[8]) { v4u w; w.x = pk2(o[0], o[1]); w.y = pk2(o[2], o[3]); w.z = pk2(o[4], o[5]); w.w = pk2(o[6], o[7]); return __builtin_bit_cast(bf16x8, w); }
; template <bool SAMPLE>
; __device__ __forceinline__ void mem_unit(const Params& p, int l, LAS unsigned char* lds, int unit, int tid, int wave, int lane) {
;     ...
;             float qv[4][8]; float ss = 0.f;
; #pragma unroll
;             for (int dc = 0; dc < 4; ++dc) { unpack8(*(const v4u*)(MQ + row * 512 + h * 128 + 32 * dc + 8 * kq), qv[dc]);
; #pragma unroll
;                 for (int e = 0; e < 8; ++e) ss += qv[dc][e] * qv[dc][e]; }
;             ss += __shfl_xor(ss, 16); ss += __shfl_xor(ss, 32);
;             const float rs = rsqrtf(ss * (1.f / 128.f) + EPS) * 0.08838834764831845f;
; #pragma unroll
;             for (int dc = 0; dc < 4; ++dc) { float qg[8]; pg8::ld8f(p.in[I_MQG] + l * 128 + 32 * dc + 8 * kq, qg);
; #pragma unroll
;                 for (int e = 0; e < 8; ++e) qv[dc][e] *= rs * qg[e];
;                 qf[dc] = pack8(qv[dc]); }
.Lqpf_go_1:
	s_mov_b32 s98, 0x20000
	s_mov_b32 s99, 0
	s_mov_b32 s100, 1
	v_lshl_add_u64 v[230:231], v[20:21], 0, s[98:99]
	v_mov_b32_e32 v8, v234
	v_mov_b32_e32 v9, v235
	v_mov_b32_e32 v10, v236
	v_mov_b32_e32 v11, v237
	v_mov_b32_e32 v12, v242
	v_mov_b32_e32 v13, v243
	v_mov_b32_e32 v14, v244
	v_mov_b32_e32 v15, v245
	v_mov_b32_e32 v16, v246
	v_mov_b32_e32 v17, v247
	v_mov_b32_e32 v18, v248
	v_mov_b32_e32 v19, v249
	v_mov_b32_e32 v20, v250
	v_mov_b32_e32 v21, v251
	v_mov_b32_e32 v22, v252
	v_mov_b32_e32 v23, v253
	v_lshlrev_b32_e32 v92, 2, v92
	v_ashrrev_i32_e32 v93, 31, v92
	s_add_u32 s8, s8, 0x80
	s_addc_u32 s9, s9, 0
	s_cmpk_lg_i32 s8, 0x200
	s_waitcnt vmcnt(0)
	v_and_b32_e32 v31, 0xffff0000, v8
	v_lshlrev_b32_e32 v30, 16, v8
	v_mul_f32_e32 v50, v31, v31
	v_lshlrev_b32_e32 v32, 16, v9
	v_fmac_f32_e32 v50, v30, v30
	v_and_b32_e32 v33, 0xffff0000, v9
	v_fmac_f32_e32 v50, v32, v32
	v_lshlrev_b32_e32 v34, 16, v10
	v_fmac_f32_e32 v50, v33, v33
	v_and_b32_e32 v35, 0xffff0000, v10
	v_fmac_f32_e32 v50, v34, v34
	v_lshlrev_b32_e32 v36, 16, v11
	v_fmac_f32_e32 v50, v35, v35
	v_and_b32_e32 v37, 0xffff0000, v11
	v_fmac_f32_e32 v50, v36, v36
	s_waitcnt vmcnt(2)
	v_lshlrev_b32_e32 v38, 16, v12
	v_fmac_f32_e32 v50, v37, v37
	v_and_b32_e32 v39, 0xffff0000, v12
	v_fmac_f32_e32 v50, v38, v38
	v_lshlrev_b32_e32 v40, 16, v13
	v_fmac_f32_e32 v50, v39, v39
	v_and_b32_e32 v41, 0xffff0000, v13
	v_fmac_f32_e32 v50, v40, v40
	v_lshlrev_b32_e32 v42, 16, v14
	v_fmac_f32_e32 v50, v41, v41
	v_and_b32_e32 v43, 0xffff0000, v14
	v_fmac_f32_e32 v50, v42, v42
	v_lshlrev_b32_e32 v44, 16, v15
	v_fmac_f32_e32 v50, v43, v43
	v_and_b32_e32 v45, 0xffff0000, v15
	v_fmac_f32_e32 v50, v44, v44
	s_waitcnt vmcnt(1)
	v_lshlrev_b32_e32 v46, 16, v16
	v_fmac_f32_e32 v50, v45, v45
	v_and_b32_e32 v16, 0xffff0000, v16
	v_fmac_f32_e32 v50, v46, v46
	v_lshlrev_b32_e32 v47, 16, v17
	v_fmac_f32_e32 v50, v16, v16
	v_and_b32_e32 v17, 0xffff0000, v17
	v_fmac_f32_e32 v50, v47, v47
	v_lshlrev_b32_e32 v48, 16, v18
	v_fmac_f32_e32 v50, v17, v17
	v_and_b32_e32 v18, 0xffff0000, v18
	v_fmac_f32_e32 v50, v48, v48
	v_lshlrev_b32_e32 v49, 16, v19
	v_fmac_f32_e32 v50, v18, v18
	v_and_b32_e32 v19, 0xffff0000, v19
	s_waitcnt vmcnt(0)
	v_and_b32_e32 v26, 0xffff0000, v20
	v_lshlrev_b32_e32 v27, 16, v20
	v_fmac_f32_e32 v50, v49, v49
	v_pk_mul_f32 v[8:9], v[26:27], v[26:27]
	v_fmac_f32_e32 v50, v19, v19
	v_and_b32_e32 v20, 0xffff0000, v21
	v_lshlrev_b32_e32 v21, 16, v21
	v_add_f32_e32 v9, v9, v50
	v_pk_mul_f32 v[10:11], v[20:21], v[20:21]
	v_add_f32_e32 v8, v8, v9
	v_and_b32_e32 v28, 0xffff0000, v22
	v_lshlrev_b32_e32 v29, 16, v22
	v_add_f32_e32 v8, v11, v8
	v_pk_mul_f32 v[12:13], v[28:29], v[28:29]
	v_add_f32_e32 v8, v10, v8
	v_and_b32_e32 v22, 0xffff0000, v23
	v_lshlrev_b32_e32 v23, 16, v23
	v_add_f32_e32 v8, v13, v8
	v_pk_mul_f32 v[14:15], v[22:23], v[22:23]
	v_add_f32_e32 v8, v12, v8
	v_add_f32_e32 v8, v15, v8
	v_add_f32_e32 v8, v14, v8
	ds_bpermute_b32 v9, v82, v8
	s_waitcnt lgkmcnt(0)
	v_add_f32_e32 v8, v8, v9
	ds_bpermute_b32 v9, v100, v8
	s_waitcnt lgkmcnt(0)
	v_add_f32_e32 v8, v8, v9
	v_fmamk_f32 v8, v8, 0x3c000000, v98
	v_mul_f32_e32 v9, 0x4b800000, v8
	v_cmp_gt_f32_e32 vcc, s23, v8
	s_nop 1
	v_cndmask_b32_e32 v8, v8, v9, vcc
	v_rsq_f32_e32 v8, v8
	s_nop 0
	v_mul_f32_e32 v9, 0x45800000, v8
	v_cndmask_b32_e32 v8, v8, v9, vcc
	v_mul_f32_e32 v50, 0x3db504f3, v8
	v_mul_f32_e32 v4, v4, v50
	v_mul_f32_e32 v5, v5, v50
	v_mul_f32_e32 v6, v6, v50
	v_mul_f32_e32 v7, v7, v50
	v_mul_f32_e32 v0, v0, v50
	v_mul_f32_e32 v1, v1, v50
	v_mul_f32_e32 v2, v2, v50
	v_mul_f32_e32 v3, v3, v50
	v_mul_f32_e32 v4, v4, v30
	v_mul_f32_e32 v5, v5, v31
	v_mul_f32_e32 v6, v6, v32
	v_mul_f32_e32 v7, v7, v33
	v_mul_f32_e32 v0, v0, v34
	v_mul_f32_e32 v1, v1, v35
	v_mul_f32_e32 v2, v2, v36
	v_mul_f32_e32 v3, v3, v37
	v_cvt_pk_bf16_f32 v8, v4, v5
	v_cvt_pk_bf16_f32 v9, v6, v7
	v_cvt_pk_bf16_f32 v10, v0, v1
	v_cvt_pk_bf16_f32 v11, v2, v3
	global_load_dwordx4 v[0:3], v[24:25], off offset:640
	global_load_dwordx4 v[4:7], v[24:25], off offset:656
	s_waitcnt vmcnt(1)
	v_mul_f32_e32 v0, v0, v50
	v_mul_f32_e32 v1, v1, v50
	v_mul_f32_e32 v2, v2, v50
	v_mul_f32_e32 v3, v3, v50
	s_waitcnt vmcnt(0)
	v_mul_f32_e32 v4, v4, v50
	v_mul_f32_e32 v5, v5, v50
	v_mul_f32_e32 v6, v6, v50
	v_mul_f32_e32 v7, v7, v50
	v_mul_f32_e32 v0, v0, v38
	v_mul_f32_e32 v1, v1, v39
	v_mul_f32_e32 v2, v2, v40
	v_mul_f32_e32 v3, v3, v41
	v_mul_f32_e32 v4, v4, v42
	v_mul_f32_e32 v5, v5, v43
	v_mul_f32_e32 v6, v6, v44
	v_mul_f32_e32 v7, v7, v45
	v_cvt_pk_bf16_f32 v12, v0, v1
	v_cvt_pk_bf16_f32 v13, v2, v3
	v_cvt_pk_bf16_f32 v14, v4, v5
	v_cvt_pk_bf16_f32 v15, v6, v7
	global_load_dwordx4 v[0:3], v[24:25], off offset:768
	global_load_dwordx4 v[4:7], v[24:25], off offset:784
	s_waitcnt vmcnt(1)
	v_mul_f32_e32 v0, v0, v50
	v_mul_f32_e32 v1, v1, v50
	v_mul_f32_e32 v2, v2, v50
	v_mul_f32_e32 v3, v3, v50
	s_waitcnt vmcnt(0)
	v_mul_f32_e32 v4, v4, v50
	v_mul_f32_e32 v5, v5, v50
	v_mul_f32_e32 v6, v6, v50
	v_mul_f32_e32 v7, v7, v50
	v_mul_f32_e32 v0, v0, v46
	v_mul_f32_e32 v1, v1, v16
	v_mul_f32_e32 v2, v2, v47
	v_mul_f32_e32 v3, v3, v17
	v_mul_f32_e32 v16, v4, v48
	v_mul_f32_e32 v17, v5, v18
	v_mul_f32_e32 v18, v6, v49
	v_mul_f32_e32 v7, v7, v19
	v_cvt_pk_bf16_f32 v4, v0, v1
	v_cvt_pk_bf16_f32 v5, v2, v3
	v_cvt_pk_bf16_f32 v6, v16, v17
	v_cvt_pk_bf16_f32 v7, v18, v7
	global_load_dwordx4 v[0:3], v[24:25], off offset:896
	global_load_dwordx4 v[16:19], v[24:25], off offset:912
	s_waitcnt vmcnt(1)
	v_mul_f32_e32 v0, v0, v50
	v_mul_f32_e32 v1, v1, v50
	v_mul_f32_e32 v2, v2, v50
	v_mul_f32_e32 v3, v3, v50
	s_waitcnt vmcnt(0)
; #define LAS __attribute__((address_space(3)))
; __device__ __forceinline__ void unpack8(const v4u w, float (&o)[8]) { o[0] = bflo(w.x); o[1] = bfhi(w.x); o[2] = bflo(w.y); o[3] = bfhi(w.y); o[4] = bflo(w.z); o[5] = bfhi(w.z); o[6] = bflo(w.w); o[7] = bfhi(w.w); }
; template <bool SAMPLE>
; __device__ __forceinline__ void mem_unit(const Params& p, int l, LAS unsigned char* lds, int unit, int tid, int wave, int lane) {
;     ...
;             for (int dc = 0; dc < 4; ++dc) { unpack8(*(const v4u*)(MQ + row * 512 + h * 128 + 32 * dc + 8 * kq), qv[dc]);
;     ...
;         f32x4 S[8][2]; float mx = -INFINITY;
; #pragma unroll
;         for (int cc = 0; cc < 8; ++cc)
; #pragma unroll
;             for (int tt = 0; tt < 2; ++tt) { const int kb = 32 * cc + 16 * tt; f32x4 a = (f32x4){0.f, 0.f, 0.f, 0.f};
; #pragma unroll
;                 for (int dc = 0; dc < 4; ++dc) { const bf16x8 kf = *(const LAS bf16x8*)(Kl + (kb + q16) * MEM_KS + 32 * dc + 8 * kq);
;                     a = __builtin_amdgcn_mfma_f32_16x16x32_bf16(kf, qf[dc], a, 0, 0, 0); }
; #pragma unroll
;                 for (int e = 0; e < 4; ++e) mx = fmaxf(mx, a[e]);
;                 S[cc][tt] = a; }
	global_load_dwordx4 v[234:237], v[230:231], off
	global_load_dwordx4 v[242:245], v[230:231], off offset:64
	global_load_dwordx4 v[246:249], v[230:231], off offset:128
	global_load_dwordx4 v[250:253], v[230:231], off offset:192
	v_mul_f32_e32 v16, v16, v50
	v_mul_f32_e32 v17, v17, v50
	v_mul_f32_e32 v18, v18, v50
	v_mul_f32_e32 v19, v19, v50
	v_mul_f32_e32 v0, v0, v27
	v_mul_f32_e32 v1, v1, v26
	v_mul_f32_e32 v2, v2, v21
	v_mul_f32_e32 v3, v3, v20
	v_mul_f32_e32 v16, v16, v29
	v_mul_f32_e32 v17, v17, v28
	v_mul_f32_e32 v18, v18, v23
	v_mul_f32_e32 v19, v19, v22
	v_cvt_pk_bf16_f32 v0, v0, v1
	v_cvt_pk_bf16_f32 v1, v2, v3
	v_cvt_pk_bf16_f32 v2, v16, v17
	v_cvt_pk_bf16_f32 v3, v18, v19
	ds_read_b128 v[186:189], v91
	ds_read_b128 v[190:193], v91 offset:4352
	ds_read_b128 v[194:197], v91 offset:8704
	ds_read_b128 v[198:201], v91 offset:13056
	ds_read_b128 v[202:205], v91 offset:17408
	s_nop 0
	ds_read_b128 v[20:23], v91 offset:64
	s_nop 0
	ds_read_b128 v[28:31], v91 offset:4416
	s_nop 0
	ds_read_b128 v[36:39], v91 offset:8768
	s_nop 0
	ds_read_b128 v[44:47], v91 offset:13120
	s_nop 0
	ds_read_b128 v[52:55], v91 offset:17472
	ds_read_b128 v[56:59], v91 offset:21760
	ds_read_b128 v[60:63], v91 offset:21824
	ds_read_b128 v[64:67], v91 offset:26112
	ds_read_b128 v[68:71], v91 offset:26176
	ds_read_b128 v[72:75], v91 offset:30464
	ds_read_b128 v[76:79], v91 offset:30528
	ds_read_b128 v[102:105], v91 offset:34816
	ds_read_b128 v[106:109], v91 offset:34880
	ds_read_b128 v[110:113], v91 offset:39168
	ds_read_b128 v[114:117], v91 offset:39232
	ds_read_b128 v[118:121], v91 offset:43520
	ds_read_b128 v[122:125], v91 offset:43584
	ds_read_b128 v[126:129], v91 offset:47872
	ds_read_b128 v[130:133], v91 offset:47936
	ds_read_b128 v[134:137], v91 offset:52224
	ds_read_b128 v[138:141], v91 offset:52288
	ds_read_b128 v[142:145], v91 offset:56576
	ds_read_b128 v[146:149], v91 offset:56640
	ds_read_b128 v[150:153], v91 offset:60928
	ds_read_b128 v[154:157], v91 offset:60992
	ds_read_b128 v[158:161], v91 offset:65280
	ds_read_b128 v[162:165], v91 offset:65344
	s_waitcnt lgkmcnt(14)
	v_mfma_f32_16x16x32_bf16 v[16:19], v[186:189], v[8:11], 0
	v_mfma_f32_16x16x32_bf16 v[24:27], v[190:193], v[8:11], 0
	v_mfma_f32_16x16x32_bf16 v[32:35], v[194:197], v[8:11], 0
	v_mfma_f32_16x16x32_bf16 v[40:43], v[198:201], v[8:11], 0
	v_mfma_f32_16x16x32_bf16 v[48:51], v[202:205], v[8:11], 0
	v_mfma_f32_16x16x32_bf16 v[56:59], v[56:59], v[8:11], 0
	v_mfma_f32_16x16x32_bf16 v[64:67], v[64:67], v[8:11], 0
	v_mfma_f32_16x16x32_bf16 v[72:75], v[72:75], v[8:11], 0
	v_mfma_f32_16x16x32_bf16 v[102:105], v[102:105], v[8:11], 0
	s_waitcnt lgkmcnt(13)
	v_mfma_f32_16x16x32_bf16 v[110:113], v[110:113], v[8:11], 0
	s_waitcnt lgkmcnt(11)
	v_mfma_f32_16x16x32_bf16 v[118:121], v[118:121], v[8:11], 0
	s_waitcnt lgkmcnt(9)
	v_mfma_f32_16x16x32_bf16 v[126:129], v[126:129], v[8:11], 0
	s_waitcnt lgkmcnt(7)
	v_mfma_f32_16x16x32_bf16 v[134:137], v[134:137], v[8:11], 0
	s_waitcnt lgkmcnt(5)
	v_mfma_f32_16x16x32_bf16 v[142:145], v[142:145], v[8:11], 0
	s_waitcnt lgkmcnt(3)
	v_mfma_f32_16x16x32_bf16 v[150:153], v[150:153], v[8:11], 0
	s_waitcnt lgkmcnt(1)
	v_mfma_f32_16x16x32_bf16 v[8:11], v[158:161], v[8:11], 0
	v_mfma_f32_16x16x32_bf16 v[16:19], v[20:23], v[12:15], v[16:19]
	v_mfma_f32_16x16x32_bf16 v[20:23], v[28:31], v[12:15], v[24:27]
	v_mfma_f32_16x16x32_bf16 v[24:27], v[36:39], v[12:15], v[32:35]
	v_mfma_f32_16x16x32_bf16 v[28:31], v[44:47], v[12:15], v[40:43]
	v_mfma_f32_16x16x32_bf16 v[32:35], v[52:55], v[12:15], v[48:51]
	v_mfma_f32_16x16x32_bf16 v[36:39], v[60:63], v[12:15], v[56:59]
	v_mfma_f32_16x16x32_bf16 v[40:43], v[68:71], v[12:15], v[64:67]
	v_mfma_f32_16x16x32_bf16 v[44:47], v[76:79], v[12:15], v[72:75]
	v_mfma_f32_16x16x32_bf16 v[48:51], v[106:109], v[12:15], v[102:105]
	ds_read_b128 v[194:197], v91 offset:128
	ds_read_b128 v[198:201], v91 offset:4480
	ds_read_b128 v[202:205], v91 offset:8832
	v_mfma_f32_16x16x32_bf16 v[52:55], v[114:117], v[12:15], v[110:113]
	v_mfma_f32_16x16x32_bf16 v[56:59], v[122:125], v[12:15], v[118:121]
	v_mfma_f32_16x16x32_bf16 v[60:63], v[130:133], v[12:15], v[126:129]
	v_mfma_f32_16x16x32_bf16 v[64:67], v[138:141], v[12:15], v[134:137]
	v_mfma_f32_16x16x32_bf16 v[68:71], v[146:149], v[12:15], v[142:145]
	ds_read_b128 v[206:209], v91 offset:13184
	ds_read_b128 v[210:213], v91 offset:17536
	ds_read_b128 v[218:221], v91 offset:21888
	ds_read_b128 v[222:225], v91 offset:26240
	ds_read_b128 v[226:229], v91 offset:30592
	v_mfma_f32_16x16x32_bf16 v[102:105], v[154:157], v[12:15], v[150:153]
	s_waitcnt lgkmcnt(8)
	v_mfma_f32_16x16x32_bf16 v[8:11], v[162:165], v[12:15], v[8:11]
	s_nop 0
	ds_read_b128 v[106:109], v91 offset:192
	s_waitcnt lgkmcnt(8)
	v_mfma_f32_16x16x32_bf16 v[12:15], v[194:197], v[4:7], v[16:19]
	s_nop 2
	s_nop 0
	ds_read_b128 v[110:113], v91 offset:4544
	s_waitcnt lgkmcnt(8)
	v_mfma_f32_16x16x32_bf16 v[16:19], v[198:201], v[4:7], v[20:23]
	s_nop 2
	s_nop 0
	ds_read_b128 v[114:117], v91 offset:8896
	s_waitcnt lgkmcnt(8)
	v_mfma_f32_16x16x32_bf16 v[20:23], v[202:205], v[4:7], v[24:27]
	s_nop 2
	s_nop 0
	ds_read_b128 v[118:121], v91 offset:13248
	s_waitcnt lgkmcnt(8)
	ds_read_b128 v[186:189], v91 offset:34944
	ds_read_b128 v[190:193], v91 offset:39296
	ds_read_b128 v[194:197], v91 offset:43648
	ds_read_b128 v[198:201], v91 offset:48000
	ds_read_b128 v[202:205], v91 offset:52352
	v_mfma_f32_16x16x32_bf16 v[24:27], v[206:209], v[4:7], v[28:31]
	s_nop 2
	s_nop 0
	ds_read_b128 v[122:125], v91 offset:17600
	s_waitcnt lgkmcnt(13)
	v_mfma_f32_16x16x32_bf16 v[28:31], v[210:213], v[4:7], v[32:35]
	s_nop 2
	s_nop 0
	ds_read_b128 v[126:129], v91 offset:21952
	s_waitcnt lgkmcnt(13)
; #define LAS __attribute__((address_space(3)))
; __device__ __forceinline__ v2u vtr(const LAS bf16* p) { return __builtin_bit_cast(v2u, __builtin_amdgcn_ds_read_tr16_b64_v4i16((LAS v4i16_t*)p)); }
; template <bool SAMPLE>
; __device__ __forceinline__ void mem_unit(const Params& p, int l, LAS unsigned char* lds, int unit, int tid, int wave, int lane) {
;     ...
;         f32x4 S[8][2]; float mx = -INFINITY;
; #pragma unroll
;         for (int cc = 0; cc < 8; ++cc)
; #pragma unroll
;             for (int tt = 0; tt < 2; ++tt) { const int kb = 32 * cc + 16 * tt; f32x4 a = (f32x4){0.f, 0.f, 0.f, 0.f};
; #pragma unroll
;                 for (int dc = 0; dc < 4; ++dc) { const bf16x8 kf = *(const LAS bf16x8*)(Kl + (kb + q16) * MEM_KS + 32 * dc + 8 * kq);
;                     a = __builtin_amdgcn_mfma_f32_16x16x32_bf16(kf, qf[dc], a, 0, 0, 0); }
; #pragma unroll
;                 for (int e = 0; e < 4; ++e) mx = fmaxf(mx, a[e]);
;                 S[cc][tt] = a; }
;         mx = fmaxf(mx, __shfl_xor(mx, 16)); mx = fmaxf(mx, __shfl_xor(mx, 32));
;     ...
; #pragma unroll
;         for (int dt = 0; dt < 8; ++dt) { f32x4 o = (f32x4){0.f, 0.f, 0.f, 0.f};
; #pragma unroll
;             for (int cc = 0; cc < 8; ++cc) { const LAS bf16* vp = Vt + (32 * cc + 4 * kq + (q16 >> 2)) * MEM_VS + 16 * dt + 4 * (q16 & 3);
;                 const v2u lo = vtr(vp), hi = vtr(vp + 16 * MEM_VS);
	v_mfma_f32_16x16x32_bf16 v[32:35], v[218:221], v[4:7], v[36:39]
	s_nop 2
	s_nop 0
	ds_read_b128 v[130:133], v91 offset:26304
	s_waitcnt lgkmcnt(13)
	v_mfma_f32_16x16x32_bf16 v[134:137], v[222:225], v[4:7], v[40:43]
	s_nop 0
	ds_read_b128 v[138:141], v91 offset:30656
	s_waitcnt lgkmcnt(13)
	v_mfma_f32_16x16x32_bf16 v[142:145], v[226:229], v[4:7], v[44:47]
	s_nop 0
	ds_read_b128 v[146:149], v91 offset:35008
	s_waitcnt lgkmcnt(9)
	ds_read_b128 v[206:209], v91 offset:56704
	ds_read_b128 v[210:213], v91 offset:61056
	ds_read_b128 v[218:221], v91 offset:65408
	v_mfma_f32_16x16x32_bf16 v[150:153], v[186:189], v[4:7], v[48:51]
	s_nop 0
	ds_read_b128 v[154:157], v91 offset:39360
	s_waitcnt lgkmcnt(12)
	v_mfma_f32_16x16x32_bf16 v[158:161], v[190:193], v[4:7], v[52:55]
	s_nop 0
	ds_read_b128 v[162:165], v91 offset:43712
	s_waitcnt lgkmcnt(12)
	v_mfma_f32_16x16x32_bf16 v[166:169], v[194:197], v[4:7], v[56:59]
	s_nop 0
	ds_read_b128 v[170:173], v91 offset:48064
	s_waitcnt lgkmcnt(12)
	v_mfma_f32_16x16x32_bf16 v[174:177], v[198:201], v[4:7], v[60:63]
	s_nop 0
	ds_read_b128 v[178:181], v91 offset:52416
	s_waitcnt lgkmcnt(12)
	v_mfma_f32_16x16x32_bf16 v[182:185], v[202:205], v[4:7], v[64:67]
	s_nop 0
	ds_read_b128 v[72:75], v91 offset:56768
	s_waitcnt lgkmcnt(7)
	v_mfma_f32_16x16x32_bf16 v[76:79], v[206:209], v[4:7], v[68:71]
	s_nop 0
	ds_read_b128 v[64:67], v91 offset:61120
	s_waitcnt lgkmcnt(7)
	v_mfma_f32_16x16x32_bf16 v[68:71], v[210:213], v[4:7], v[102:105]
	s_nop 0
	ds_read_b128 v[56:59], v91 offset:65472
	v_lshrrev_b32_e32 v91, 2, v90
	s_waitcnt lgkmcnt(7)
	v_mfma_f32_16x16x32_bf16 v[60:63], v[218:221], v[4:7], v[8:11]
	v_mfma_f32_16x16x32_bf16 v[52:55], v[106:109], v[0:3], v[12:15]
	v_mfma_f32_16x16x32_bf16 v[48:51], v[110:113], v[0:3], v[16:19]
	v_mfma_f32_16x16x32_bf16 v[44:47], v[114:117], v[0:3], v[20:23]
	v_mfma_f32_16x16x32_bf16 v[40:43], v[118:121], v[0:3], v[24:27]
	v_mfma_f32_16x16x32_bf16 v[36:39], v[122:125], v[0:3], v[28:31]
	v_mfma_f32_16x16x32_bf16 v[32:35], v[126:129], v[0:3], v[32:35]
	v_mfma_f32_16x16x32_bf16 v[28:31], v[130:133], v[0:3], v[134:137]
	v_mfma_f32_16x16x32_bf16 v[24:27], v[138:141], v[0:3], v[142:145]
	v_mfma_f32_16x16x32_bf16 v[20:23], v[146:149], v[0:3], v[150:153]
	v_mfma_f32_16x16x32_bf16 v[16:19], v[154:157], v[0:3], v[158:161]
	v_mfma_f32_16x16x32_bf16 v[12:15], v[162:165], v[0:3], v[166:169]
	v_mfma_f32_16x16x32_bf16 v[8:11], v[170:173], v[0:3], v[174:177]
	v_mfma_f32_16x16x32_bf16 v[4:7], v[178:181], v[0:3], v[182:185]
	v_mfma_f32_16x16x32_bf16 v[72:75], v[72:75], v[0:3], v[76:79]
	v_mfma_f32_16x16x32_bf16 v[66:69], v[64:67], v[0:3], v[68:71]
	s_nop 1
	v_lshlrev_b32_e32 v76, 3, v90
	v_add_u32_e32 v77, v91, v92
	v_and_b32_e32 v76, 24, v76
	s_waitcnt lgkmcnt(0)
	v_mfma_f32_16x16x32_bf16 v[0:3], v[56:59], v[0:3], v[60:63]
	v_max3_f32 v56, v52, s24, v53
	v_max3_f32 v56, v56, v54, v55
	v_max3_f32 v56, v56, v48, v49
	v_max3_f32 v56, v56, v50, v51
	v_max3_f32 v56, v56, v44, v45
	v_max3_f32 v56, v56, v46, v47
	v_max3_f32 v56, v56, v40, v41
	v_max3_f32 v56, v56, v42, v43
	v_max3_f32 v56, v56, v36, v37
	v_max3_f32 v56, v56, v38, v39
	v_max3_f32 v56, v56, v32, v33
	v_max3_f32 v56, v56, v34, v35
	v_max3_f32 v56, v56, v28, v29
	v_max3_f32 v56, v56, v30, v31
	v_max3_f32 v56, v56, v24, v25
	v_max3_f32 v56, v56, v26, v27
	v_max3_f32 v56, v56, v20, v21
	v_max3_f32 v56, v56, v22, v23
	v_max3_f32 v56, v56, v16, v17
	v_max3_f32 v56, v56, v18, v19
	v_max3_f32 v56, v56, v12, v13
	v_max3_f32 v56, v56, v14, v15
	v_max3_f32 v56, v56, v8, v9
	v_max3_f32 v56, v56, v10, v11
	v_max3_f32 v56, v56, v4, v5
	v_max3_f32 v56, v56, v6, v7
	v_max3_f32 v56, v56, v72, v73
	v_max3_f32 v56, v56, v74, v75
	v_max3_f32 v56, v56, v66, v67
	v_max3_f32 v56, v56, v68, v69
	v_max3_f32 v56, v56, v0, v1
	v_max3_f32 v56, v56, v2, v3
	ds_bpermute_b32 v57, v82, v56
	v_mul_lo_u32 v64, v77, s22
	v_add3_u32 v64, s90, v76, v64
	ds_read_b64_tr_b16 v[226:227], v64
	ds_read_b64_tr_b16 v[228:229], v64 offset:4352
	ds_read_b64_tr_b16 v[186:187], v64 offset:8704
	ds_read_b64_tr_b16 v[188:189], v64 offset:13056
	ds_read_b64_tr_b16 v[190:191], v64 offset:17408
	ds_read_b64_tr_b16 v[192:193], v64 offset:21760
	ds_read_b64_tr_b16 v[194:195], v64 offset:26112
	ds_read_b64_tr_b16 v[196:197], v64 offset:30464
	ds_read_b64_tr_b16 v[198:199], v64 offset:34816
	ds_read_b64_tr_b16 v[200:201], v64 offset:39168
	ds_read_b64_tr_b16 v[202:203], v64 offset:32
	ds_read_b64_tr_b16 v[204:205], v64 offset:4384
	s_waitcnt lgkmcnt(12)
	v_max_f32_e32 v57, v57, v57
	v_max_f32_e32 v56, v56, v57
	ds_bpermute_b32 v57, v100, v56
	s_waitcnt lgkmcnt(0)
; template <bool SAMPLE>
; __device__ __forceinline__ void mem_unit(const Params& p, int l, LAS unsigned char* lds, int unit, int tid, int wave, int lane) {
;     ...
;         mx = fmaxf(mx, __shfl_xor(mx, 16)); mx = fmaxf(mx, __shfl_xor(mx, 32));
;         float den = 0.f;
; #pragma unroll
;         for (int cc = 0; cc < 8; ++cc)
; #pragma unroll
;             for (int tt = 0; tt < 2; ++tt)
; #pragma unroll
;                 for (int e = 0; e < 4; ++e) { const float pe = __expf(S[cc][tt][e] - mx); S[cc][tt][e] = pe; den += pe; }
;         den += __shfl_xor(den, 16); den += __shfl_xor(den, 32);
;         const float rden = 1.f / den;
	v_max_f32_e32 v57, v57, v57
	v_max_f32_e32 v56, v56, v57
	v_sub_f32_e32 v52, v52, v56
	v_sub_f32_e32 v53, v53, v56
	v_mul_f32_e32 v52, 0x3fb8aa3b, v52
	v_sub_f32_e32 v54, v54, v56
	v_sub_f32_e32 v57, v72, v56
	v_sub_f32_e32 v58, v73, v56
	v_sub_f32_e32 v59, v74, v56
	v_sub_f32_e32 v60, v75, v56
	v_sub_f32_e32 v61, v66, v56
	v_sub_f32_e32 v62, v67, v56
	v_sub_f32_e32 v63, v68, v56
	v_sub_f32_e32 v65, v69, v56
	v_mul_f32_e32 v53, 0x3fb8aa3b, v53
	v_exp_f32_e32 v52, v52
	v_sub_f32_e32 v55, v55, v56
	v_sub_f32_e32 v48, v48, v56
	v_sub_f32_e32 v49, v49, v56
	v_sub_f32_e32 v50, v50, v56
	v_sub_f32_e32 v51, v51, v56
	v_sub_f32_e32 v44, v44, v56
	v_sub_f32_e32 v45, v45, v56
	v_sub_f32_e32 v46, v46, v56
	v_sub_f32_e32 v47, v47, v56
	v_sub_f32_e32 v40, v40, v56
	v_sub_f32_e32 v41, v41, v56
	v_sub_f32_e32 v42, v42, v56
	v_sub_f32_e32 v43, v43, v56
	v_sub_f32_e32 v36, v36, v56
	v_sub_f32_e32 v37, v37, v56
	v_sub_f32_e32 v38, v38, v56
	v_sub_f32_e32 v39, v39, v56
	v_sub_f32_e32 v32, v32, v56
	v_sub_f32_e32 v33, v33, v56
	v_sub_f32_e32 v34, v34, v56
	v_sub_f32_e32 v35, v35, v56
	v_sub_f32_e32 v28, v28, v56
	v_sub_f32_e32 v29, v29, v56
	v_sub_f32_e32 v30, v30, v56
	v_sub_f32_e32 v31, v31, v56
	v_sub_f32_e32 v24, v24, v56
	v_sub_f32_e32 v25, v25, v56
	v_sub_f32_e32 v26, v26, v56
	v_sub_f32_e32 v27, v27, v56
	v_sub_f32_e32 v20, v20, v56
	v_sub_f32_e32 v21, v21, v56
	v_sub_f32_e32 v22, v22, v56
	v_sub_f32_e32 v23, v23, v56
	v_sub_f32_e32 v16, v16, v56
	v_sub_f32_e32 v17, v17, v56
	v_sub_f32_e32 v18, v18, v56
	v_sub_f32_e32 v19, v19, v56
	v_sub_f32_e32 v12, v12, v56
	v_sub_f32_e32 v13, v13, v56
	v_sub_f32_e32 v14, v14, v56
	v_sub_f32_e32 v15, v15, v56
	v_sub_f32_e32 v8, v8, v56
	v_sub_f32_e32 v9, v9, v56
	v_sub_f32_e32 v10, v10, v56
	v_sub_f32_e32 v11, v11, v56
	v_sub_f32_e32 v4, v4, v56
	v_sub_f32_e32 v5, v5, v56
	v_sub_f32_e32 v6, v6, v56
	v_sub_f32_e32 v7, v7, v56
	v_sub_f32_e32 v0, v0, v56
	v_sub_f32_e32 v1, v1, v56
	v_sub_f32_e32 v2, v2, v56
	v_sub_f32_e32 v3, v3, v56
	v_mul_f32_e32 v54, 0x3fb8aa3b, v54
	v_mul_f32_e32 v56, 0x3fb8aa3b, v57
	v_mul_f32_e32 v57, 0x3fb8aa3b, v58
	v_mul_f32_e32 v58, 0x3fb8aa3b, v59
	v_mul_f32_e32 v59, 0x3fb8aa3b, v60
	v_mul_f32_e32 v60, 0x3fb8aa3b, v61
	v_mul_f32_e32 v61, 0x3fb8aa3b, v62
	v_mul_f32_e32 v62, 0x3fb8aa3b, v63
	v_mul_f32_e32 v63, 0x3fb8aa3b, v65
	v_exp_f32_e32 v65, v53
	v_mul_f32_e32 v55, 0x3fb8aa3b, v55
	v_exp_f32_e32 v66, v54
	v_mul_f32_e32 v48, 0x3fb8aa3b, v48
	v_exp_f32_e32 v67, v55
	v_mul_f32_e32 v49, 0x3fb8aa3b, v49
	v_mul_f32_e32 v0, 0x3fb8aa3b, v0
	v_exp_f32_e32 v68, v48
	v_add_f32_e32 v147, 0, v52
	v_mul_f32_e32 v50, 0x3fb8aa3b, v50
	v_exp_f32_e32 v69, v49
	v_exp_f32_e32 v143, v0
	v_cvt_pk_bf16_f32 v0, v52, v65
	v_add_f32_e32 v65, v65, v147
	v_mul_f32_e32 v51, 0x3fb8aa3b, v51
	v_exp_f32_e32 v70, v50
	v_add_f32_e32 v65, v66, v65
	v_mul_f32_e32 v44, 0x3fb8aa3b, v44
	v_exp_f32_e32 v71, v51
	v_add_f32_e32 v65, v67, v65
	v_mul_f32_e32 v45, 0x3fb8aa3b, v45
	v_exp_f32_e32 v72, v44
	v_add_f32_e32 v65, v68, v65
	v_mul_f32_e32 v46, 0x3fb8aa3b, v46
	v_exp_f32_e32 v73, v45
	v_add_f32_e32 v65, v69, v65
	v_mul_f32_e32 v47, 0x3fb8aa3b, v47
	v_exp_f32_e32 v74, v46
	v_add_f32_e32 v65, v70, v65
	v_mul_f32_e32 v40, 0x3fb8aa3b, v40
	v_exp_f32_e32 v75, v47
	v_add_f32_e32 v65, v71, v65
	v_mul_f32_e32 v41, 0x3fb8aa3b, v41
	v_mul_f32_e32 v42, 0x3fb8aa3b, v42
	v_mul_f32_e32 v43, 0x3fb8aa3b, v43
	v_mul_f32_e32 v36, 0x3fb8aa3b, v36
	v_mul_f32_e32 v37, 0x3fb8aa3b, v37
	v_mul_f32_e32 v38, 0x3fb8aa3b, v38
	v_mul_f32_e32 v39, 0x3fb8aa3b, v39
	v_mul_f32_e32 v32, 0x3fb8aa3b, v32
	v_mul_f32_e32 v33, 0x3fb8aa3b, v33
	v_mul_f32_e32 v34, 0x3fb8aa3b, v34
	v_mul_f32_e32 v35, 0x3fb8aa3b, v35
	v_mul_f32_e32 v28, 0x3fb8aa3b, v28
	v_mul_f32_e32 v29, 0x3fb8aa3b, v29
	v_mul_f32_e32 v30, 0x3fb8aa3b, v30
	v_mul_f32_e32 v31, 0x3fb8aa3b, v31
	v_mul_f32_e32 v24, 0x3fb8aa3b, v24
	v_mul_f32_e32 v25, 0x3fb8aa3b, v25
	v_mul_f32_e32 v26, 0x3fb8aa3b, v26
	v_mul_f32_e32 v27, 0x3fb8aa3b, v27
	v_mul_f32_e32 v20, 0x3fb8aa3b, v20
	v_mul_f32_e32 v21, 0x3fb8aa3b, v21
	v_mul_f32_e32 v22, 0x3fb8aa3b, v22
	v_mul_f32_e32 v23, 0x3fb8aa3b, v23
	v_mul_f32_e32 v16, 0x3fb8aa3b, v16
	v_mul_f32_e32 v17, 0x3fb8aa3b, v17
	v_mul_f32_e32 v18, 0x3fb8aa3b, v18
	v_mul_f32_e32 v19, 0x3fb8aa3b, v19
	v_mul_f32_e32 v12, 0x3fb8aa3b, v12
	v_mul_f32_e32 v13, 0x3fb8aa3b, v13
	v_mul_f32_e32 v14, 0x3fb8aa3b, v14
	v_mul_f32_e32 v15, 0x3fb8aa3b, v15
	v_mul_f32_e32 v8, 0x3fb8aa3b, v8
	v_mul_f32_e32 v9, 0x3fb8aa3b, v9
	v_mul_f32_e32 v10, 0x3fb8aa3b, v10
	v_mul_f32_e32 v11, 0x3fb8aa3b, v11
	v_mul_f32_e32 v4, 0x3fb8aa3b, v4
	v_mul_f32_e32 v5, 0x3fb8aa3b, v5
	v_mul_f32_e32 v6, 0x3fb8aa3b, v6
	v_mul_f32_e32 v7, 0x3fb8aa3b, v7
	v_mul_f32_e32 v1, 0x3fb8aa3b, v1
	v_mul_f32_e32 v2, 0x3fb8aa3b, v2
	v_mul_f32_e32 v3, 0x3fb8aa3b, v3
	v_exp_f32_e32 v76, v40
	v_add_f32_e32 v65, v72, v65
	v_exp_f32_e32 v77, v41
	v_exp_f32_e32 v78, v42
	v_exp_f32_e32 v79, v43
	v_exp_f32_e32 v90, v36
	v_exp_f32_e32 v91, v37
	v_exp_f32_e32 v101, v38
	v_exp_f32_e32 v102, v39
	v_exp_f32_e32 v103, v32
	v_exp_f32_e32 v104, v33
	v_exp_f32_e32 v105, v34
	v_exp_f32_e32 v106, v35
	v_exp_f32_e32 v107, v28
	v_exp_f32_e32 v108, v29
	v_exp_f32_e32 v109, v30
	v_exp_f32_e32 v110, v31
	v_exp_f32_e32 v111, v24
	v_exp_f32_e32 v112, v25
	v_exp_f32_e32 v113, v26
	v_exp_f32_e32 v114, v27
	v_exp_f32_e32 v115, v20
	v_exp_f32_e32 v116, v21
	v_exp_f32_e32 v117, v22
	v_exp_f32_e32 v118, v23
	v_exp_f32_e32 v119, v16
	v_exp_f32_e32 v120, v17
	v_exp_f32_e32 v121, v18
	v_exp_f32_e32 v122, v19
	v_exp_f32_e32 v123, v12
	v_exp_f32_e32 v124, v13
	v_exp_f32_e32 v125, v14
	v_exp_f32_e32 v126, v15
	v_exp_f32_e32 v127, v8
	v_exp_f32_e32 v128, v9
	v_exp_f32_e32 v129, v10
; #define LAS __attribute__((address_space(3)))
; __device__ __forceinline__ unsigned pk2(float lo, float hi) { return pg8::cvt_pk_bf16(lo, hi); }
; __device__ __forceinline__ bf16x8 pack8(const float (&o)[8]) { v4u w; w.x = pk2(o[0], o[1]); w.y = pk2(o[2], o[3]); w.z = pk2(o[4], o[5]); w.w = pk2(o[6], o[7]); return __builtin_bit_cast(bf16x8, w); }
; __device__ __forceinline__ v2u vtr(const LAS bf16* p) { return __builtin_bit_cast(v2u, __builtin_amdgcn_ds_read_tr16_b64_v4i16((LAS v4i16_t*)p)); }
; template <bool SAMPLE>
; __device__ __forceinline__ void mem_unit(const Params& p, int l, LAS unsigned char* lds, int unit, int tid, int wave, int lane) {
;     ...
;         for (int cc = 0; cc < 8; ++cc)
; #pragma unroll
;             for (int tt = 0; tt < 2; ++tt)
; #pragma unroll
;                 for (int e = 0; e < 4; ++e) { const float pe = __expf(S[cc][tt][e] - mx); S[cc][tt][e] = pe; den += pe; }
;         den += __shfl_xor(den, 16); den += __shfl_xor(den, 32);
;         const float rden = 1.f / den;
;         bf16x8 pf[8];
; #pragma unroll
;         for (int cc = 0; cc < 8; ++cc) { float t8[8];
; #pragma unroll
;             for (int e = 0; e < 4; ++e) { t8[e] = S[cc][0][e]; t8[4 + e] = S[cc][1][e]; }
;             pf[cc] = pack8(t8); }
; #pragma unroll
;         for (int dt = 0; dt < 8; ++dt) { f32x4 o = (f32x4){0.f, 0.f, 0.f, 0.f};
; #pragma unroll
;             for (int cc = 0; cc < 8; ++cc) { const LAS bf16* vp = Vt + (32 * cc + 4 * kq + (q16 >> 2)) * MEM_VS + 16 * dt + 4 * (q16 & 3);
;                 const v2u lo = vtr(vp), hi = vtr(vp + 16 * MEM_VS);
;                 v4u av; av.x = lo.x; av.y = lo.y; av.z = hi.x; av.w = hi.y;
;                 o = __builtin_amdgcn_mfma_f32_16x16x32_bf16(__builtin_bit_cast(bf16x8, av), pf[cc], o, 0, 0, 0); }
;             if (st) { v2u w; w.x = pk2(o[0] * rden, o[1] * rden); w.y = pk2(o[2] * rden, o[3] * rden);
;                 *(v2u*)(MO + row * 512 + h * 128 + 16 * dt + 4 * kq) = w; } }
	v_exp_f32_e32 v130, v11
	v_exp_f32_e32 v131, v4
	v_exp_f32_e32 v132, v5
	v_exp_f32_e32 v133, v6
	v_exp_f32_e32 v134, v7
	v_exp_f32_e32 v135, v56
	v_exp_f32_e32 v136, v57
	v_exp_f32_e32 v137, v58
	v_exp_f32_e32 v138, v59
	v_exp_f32_e32 v139, v60
	v_exp_f32_e32 v140, v61
	v_exp_f32_e32 v141, v62
	v_exp_f32_e32 v142, v63
	v_exp_f32_e32 v144, v1
	v_exp_f32_e32 v145, v2
	v_exp_f32_e32 v146, v3
	v_cvt_pk_bf16_f32 v1, v66, v67
	v_cvt_pk_bf16_f32 v2, v68, v69
	v_cvt_pk_bf16_f32 v3, v70, v71
	v_cvt_pk_bf16_f32 v4, v72, v73
	v_cvt_pk_bf16_f32 v5, v74, v75
	v_cvt_pk_bf16_f32 v6, v76, v77
	v_cvt_pk_bf16_f32 v7, v78, v79
	v_cvt_pk_bf16_f32 v8, v90, v91
	v_cvt_pk_bf16_f32 v9, v101, v102
	v_cvt_pk_bf16_f32 v10, v103, v104
	v_cvt_pk_bf16_f32 v11, v105, v106
	v_cvt_pk_bf16_f32 v12, v107, v108
	v_cvt_pk_bf16_f32 v13, v109, v110
	v_cvt_pk_bf16_f32 v14, v111, v112
	v_cvt_pk_bf16_f32 v15, v113, v114
	v_cvt_pk_bf16_f32 v16, v115, v116
	v_cvt_pk_bf16_f32 v17, v117, v118
	v_cvt_pk_bf16_f32 v18, v119, v120
	v_cvt_pk_bf16_f32 v19, v121, v122
	v_cvt_pk_bf16_f32 v24, v123, v124
	v_cvt_pk_bf16_f32 v25, v125, v126
	v_cvt_pk_bf16_f32 v26, v127, v128
	v_cvt_pk_bf16_f32 v27, v129, v130
	v_cvt_pk_bf16_f32 v28, v131, v132
	v_cvt_pk_bf16_f32 v29, v133, v134
	v_cvt_pk_bf16_f32 v30, v135, v136
	v_cvt_pk_bf16_f32 v31, v137, v138
	v_cvt_pk_bf16_f32 v20, v139, v140
	v_cvt_pk_bf16_f32 v21, v141, v142
	v_cvt_pk_bf16_f32 v22, v143, v144
	v_cvt_pk_bf16_f32 v23, v145, v146
	s_nop 7
	s_nop 1
	ds_read_b64_tr_b16 v[52:53], v64 offset:43520
	ds_read_b64_tr_b16 v[54:55], v64 offset:47872
	ds_read_b64_tr_b16 v[56:57], v64 offset:52224
	ds_read_b64_tr_b16 v[58:59], v64 offset:56576
	ds_read_b64_tr_b16 v[60:61], v64 offset:60928
	ds_read_b64_tr_b16 v[62:63], v64 offset:65280
	v_add_f32_e32 v65, v73, v65
	s_nop 0
	v_mfma_f32_16x16x32_bf16 v[32:35], v[226:229], v[0:3], 0
	v_add_f32_e32 v65, v74, v65
	v_add_f32_e32 v65, v75, v65
	v_add_f32_e32 v65, v76, v65
	v_add_f32_e32 v65, v77, v65
	s_nop 0
	ds_read_b64_tr_b16 v[206:207], v64 offset:8736
	ds_read_b64_tr_b16 v[208:209], v64 offset:13088
	ds_read_b64_tr_b16 v[210:211], v64 offset:17440
	ds_read_b64_tr_b16 v[212:213], v64 offset:21792
	ds_read_b64_tr_b16 v[218:219], v64 offset:26144
	ds_read_b64_tr_b16 v[220:221], v64 offset:30496
	ds_read_b64_tr_b16 v[222:223], v64 offset:34848
	ds_read_b64_tr_b16 v[224:225], v64 offset:39200
	ds_read_b64_tr_b16 v[226:227], v64 offset:43552
	ds_read_b64_tr_b16 v[228:229], v64 offset:47904
	v_mfma_f32_16x16x32_bf16 v[32:35], v[186:189], v[4:7], v[32:35]
	v_add_f32_e32 v36, v78, v65
	v_add_f32_e32 v36, v79, v36
	v_add_f32_e32 v36, v90, v36
	v_add_f32_e32 v36, v91, v36
	s_nop 0
	v_mfma_f32_16x16x32_bf16 v[32:35], v[190:193], v[8:11], v[32:35]
	v_add_f32_e32 v36, v101, v36
	v_add_f32_e32 v36, v102, v36
	v_add_f32_e32 v36, v103, v36
	v_add_f32_e32 v36, v104, v36
	s_nop 0
	v_mfma_f32_16x16x32_bf16 v[32:35], v[194:197], v[12:15], v[32:35]
	v_add_f32_e32 v36, v105, v36
	v_add_f32_e32 v36, v106, v36
	v_add_f32_e32 v36, v107, v36
	v_add_f32_e32 v36, v108, v36
	s_nop 0
	v_mfma_f32_16x16x32_bf16 v[32:35], v[198:201], v[16:19], v[32:35]
	v_add_f32_e32 v36, v109, v36
	v_add_f32_e32 v36, v110, v36
	v_add_f32_e32 v36, v111, v36
	v_add_f32_e32 v36, v112, v36
	s_waitcnt lgkmcnt(14)
	v_mfma_f32_16x16x32_bf16 v[32:35], v[52:55], v[24:27], v[32:35]
	v_add_f32_e32 v36, v113, v36
	v_add_f32_e32 v36, v114, v36
	v_add_f32_e32 v36, v115, v36
	v_add_f32_e32 v36, v116, v36
	s_waitcnt lgkmcnt(12)
	v_mfma_f32_16x16x32_bf16 v[32:35], v[56:59], v[28:31], v[32:35]
	v_add_f32_e32 v36, v117, v36
	v_add_f32_e32 v36, v118, v36
	v_add_f32_e32 v36, v119, v36
	v_add_f32_e32 v40, v120, v36
	s_waitcnt lgkmcnt(10)
	v_mfma_f32_16x16x32_bf16 v[36:39], v[60:63], v[20:23], v[32:35]
	s_nop 2
	v_add_f32_e32 v32, v121, v40
	v_add_f32_e32 v32, v122, v32
	v_add_f32_e32 v32, v123, v32
	v_add_f32_e32 v32, v124, v32
	v_add_f32_e32 v32, v125, v32
	v_add_f32_e32 v32, v126, v32
	v_add_f32_e32 v32, v127, v32
	v_add_f32_e32 v32, v128, v32
	v_add_f32_e32 v32, v129, v32
	v_add_f32_e32 v32, v130, v32
	v_add_f32_e32 v32, v131, v32
	v_add_f32_e32 v32, v132, v32
	v_add_f32_e32 v32, v133, v32
	v_add_f32_e32 v32, v134, v32
	v_add_f32_e32 v32, v135, v32
	v_add_f32_e32 v32, v136, v32
	v_add_f32_e32 v32, v137, v32
	v_add_f32_e32 v32, v138, v32
	v_add_f32_e32 v32, v139, v32
	v_add_f32_e32 v32, v140, v32
	v_add_f32_e32 v32, v141, v32
	v_add_f32_e32 v32, v142, v32
	v_add_f32_e32 v32, v143, v32
	v_add_f32_e32 v32, v144, v32
	v_add_f32_e32 v32, v145, v32
	v_add_f32_e32 v32, v146, v32
	ds_bpermute_b32 v33, v82, v32
	s_waitcnt lgkmcnt(0)
	v_add_f32_e32 v32, v32, v33
	ds_bpermute_b32 v33, v100, v32
	s_waitcnt lgkmcnt(0)
	v_add_f32_e32 v32, v32, v33
	v_div_scale_f32 v33, s[16:17], v32, v32, 1.0
	v_rcp_f32_e32 v35, v33
	v_div_scale_f32 v34, vcc, 1.0, v32, 1.0
	v_fma_f32 v40, -v33, v35, 1.0
	v_fmac_f32_e32 v35, v40, v35
	v_mul_f32_e32 v40, v34, v35
	v_fma_f32 v41, -v33, v40, v34
	v_fmac_f32_e32 v40, v41, v35
	v_fma_f32 v33, -v33, v40, v34
	v_div_fmas_f32 v33, v33, v35, v40
	v_div_fixup_f32 v34, v33, v32, 1.0
	v_mul_f32_e32 v32, v36, v34
	v_mul_f32_e32 v36, v39, v34
	v_mul_f32_e32 v33, v37, v34
	v_mul_f32_e32 v35, v38, v34
	v_cvt_pk_bf16_f32 v52, v32, v33
	v_cvt_pk_bf16_f32 v53, v35, v36
	s_nop 5
	v_mfma_f32_16x16x32_bf16 v[36:39], v[202:205], v[0:3], 0
	s_nop 1
	v_lshl_add_u64 v[32:33], s[2:3], 0, v[88:89]
	v_lshl_add_u64 v[32:33], v[92:93], 1, v[32:33]
	s_nop 0
	ds_read_b64_tr_b16 v[186:187], v64 offset:52256
	ds_read_b64_tr_b16 v[188:189], v64 offset:56608
	ds_read_b64_tr_b16 v[190:191], v64 offset:60960
	ds_read_b64_tr_b16 v[192:193], v64 offset:65312
	ds_read_b64_tr_b16 v[194:195], v64 offset:64
	ds_read_b64_tr_b16 v[196:197], v64 offset:4416
	ds_read_b64_tr_b16 v[198:199], v64 offset:8768
	ds_read_b64_tr_b16 v[200:201], v64 offset:13120
	ds_read_b64_tr_b16 v[202:203], v64 offset:17472
	ds_read_b64_tr_b16 v[204:205], v64 offset:21824
	v_mfma_f32_16x16x32_bf16 v[36:39], v[206:209], v[4:7], v[36:39]
	s_nop 2
	v_mfma_f32_16x16x32_bf16 v[36:39], v[210:213], v[8:11], v[36:39]
	s_nop 2
	v_mfma_f32_16x16x32_bf16 v[36:39], v[218:221], v[12:15], v[36:39]
	s_nop 2
	v_mfma_f32_16x16x32_bf16 v[36:39], v[222:225], v[16:19], v[36:39]
	s_nop 2
	global_store_dwordx2 v[32:33], v[52:53], off
	s_nop 0
	v_mfma_f32_16x16x32_bf16 v[36:39], v[226:229], v[24:27], v[36:39]
	s_waitcnt lgkmcnt(8)
; #define LAS __attribute__((address_space(3)))
; __device__ __forceinline__ unsigned pk2(float lo, float hi) { return pg8::cvt_pk_bf16(lo, hi); }
; __device__ __forceinline__ v2u vtr(const LAS bf16* p) { return __builtin_bit_cast(v2u, __builtin_amdgcn_ds_read_tr16_b64_v4i16((LAS v4i16_t*)p)); }
; template <bool SAMPLE>
; __device__ __forceinline__ void mem_unit(const Params& p, int l, LAS unsigned char* lds, int unit, int tid, int wave, int lane) {
;     ...
; #pragma unroll
;         for (int dt = 0; dt < 8; ++dt) { f32x4 o = (f32x4){0.f, 0.f, 0.f, 0.f};
; #pragma unroll
;             for (int cc = 0; cc < 8; ++cc) { const LAS bf16* vp = Vt + (32 * cc + 4 * kq + (q16 >> 2)) * MEM_VS + 16 * dt + 4 * (q16 & 3);
;                 const v2u lo = vtr(vp), hi = vtr(vp + 16 * MEM_VS);
;                 v4u av; av.x = lo.x; av.y = lo.y; av.z = hi.x; av.w = hi.y;
;                 o = __builtin_amdgcn_mfma_f32_16x16x32_bf16(__builtin_bit_cast(bf16x8, av), pf[cc], o, 0, 0, 0); }
;             if (st) { v2u w; w.x = pk2(o[0] * rden, o[1] * rden); w.y = pk2(o[2] * rden, o[3] * rden);
;                 *(v2u*)(MO + row * 512 + h * 128 + 16 * dt + 4 * kq) = w; } }
	ds_read_b64_tr_b16 v[206:207], v64 offset:26176
	ds_read_b64_tr_b16 v[208:209], v64 offset:30528
	ds_read_b64_tr_b16 v[210:211], v64 offset:34880
	ds_read_b64_tr_b16 v[212:213], v64 offset:39232
	ds_read_b64_tr_b16 v[218:219], v64 offset:43584
	ds_read_b64_tr_b16 v[220:221], v64 offset:47936
	ds_read_b64_tr_b16 v[222:223], v64 offset:52288
	ds_read_b64_tr_b16 v[224:225], v64 offset:56640
	ds_read_b64_tr_b16 v[226:227], v64 offset:60992
	ds_read_b64_tr_b16 v[228:229], v64 offset:65344
	v_mfma_f32_16x16x32_bf16 v[36:39], v[186:189], v[28:31], v[36:39]
	s_waitcnt lgkmcnt(15)
	v_mfma_f32_16x16x32_bf16 v[36:39], v[190:193], v[20:23], v[36:39]
	s_nop 7
	v_mul_f32_e32 v35, v34, v36
	v_mul_f32_e32 v36, v34, v37
	v_mul_f32_e32 v37, v34, v38
	v_mul_f32_e32 v38, v34, v39
	v_cvt_pk_bf16_f32 v52, v35, v36
	v_cvt_pk_bf16_f32 v53, v37, v38
	s_nop 4
	s_waitcnt lgkmcnt(14)
	v_mfma_f32_16x16x32_bf16 v[36:39], v[194:197], v[0:3], 0
	s_nop 1
	s_waitcnt lgkmcnt(12)
	v_mfma_f32_16x16x32_bf16 v[36:39], v[198:201], v[4:7], v[36:39]
	s_nop 1
	s_waitcnt lgkmcnt(10)
	v_mfma_f32_16x16x32_bf16 v[36:39], v[202:205], v[8:11], v[36:39]
	s_nop 1
	s_waitcnt lgkmcnt(8)
	ds_read_b64_tr_b16 v[186:187], v64 offset:96
	ds_read_b64_tr_b16 v[188:189], v64 offset:4448
	ds_read_b64_tr_b16 v[190:191], v64 offset:8800
	ds_read_b64_tr_b16 v[192:193], v64 offset:13152
	ds_read_b64_tr_b16 v[194:195], v64 offset:17504
	ds_read_b64_tr_b16 v[196:197], v64 offset:21856
	ds_read_b64_tr_b16 v[198:199], v64 offset:26208
	ds_read_b64_tr_b16 v[200:201], v64 offset:30560
	ds_read_b64_tr_b16 v[202:203], v64 offset:34912
	ds_read_b64_tr_b16 v[204:205], v64 offset:39264
	v_mfma_f32_16x16x32_bf16 v[36:39], v[206:209], v[12:15], v[36:39]
	s_nop 1
	s_waitcnt lgkmcnt(15)
	v_mfma_f32_16x16x32_bf16 v[36:39], v[210:213], v[16:19], v[36:39]
	s_nop 2
	global_store_dwordx2 v[32:33], v[52:53], off offset:32
	s_waitcnt lgkmcnt(14)
	v_mfma_f32_16x16x32_bf16 v[36:39], v[218:221], v[24:27], v[36:39]
	s_waitcnt lgkmcnt(12)
	v_mfma_f32_16x16x32_bf16 v[36:39], v[222:225], v[28:31], v[36:39]
	s_waitcnt lgkmcnt(10)
	v_mfma_f32_16x16x32_bf16 v[36:39], v[226:229], v[20:23], v[36:39]
	s_nop 7
	v_mul_f32_e32 v35, v34, v36
	v_mul_f32_e32 v36, v34, v37
	v_mul_f32_e32 v37, v34, v38
	v_mul_f32_e32 v38, v34, v39
	v_cvt_pk_bf16_f32 v52, v35, v36
	v_cvt_pk_bf16_f32 v53, v37, v38
	s_nop 4
	s_waitcnt lgkmcnt(8)
	ds_read_b64_tr_b16 v[206:207], v64 offset:43616
	ds_read_b64_tr_b16 v[208:209], v64 offset:47968
	ds_read_b64_tr_b16 v[210:211], v64 offset:52320
	ds_read_b64_tr_b16 v[212:213], v64 offset:56672
	ds_read_b64_tr_b16 v[218:219], v64 offset:61024
	ds_read_b64_tr_b16 v[220:221], v64 offset:65376
	ds_read_b64_tr_b16 v[222:223], v64 offset:128
	ds_read_b64_tr_b16 v[224:225], v64 offset:4480
	ds_read_b64_tr_b16 v[226:227], v64 offset:8832
	ds_read_b64_tr_b16 v[228:229], v64 offset:13184
	v_mfma_f32_16x16x32_bf16 v[36:39], v[186:189], v[0:3], 0
	s_nop 1
	s_waitcnt lgkmcnt(15)
	v_mfma_f32_16x16x32_bf16 v[36:39], v[190:193], v[4:7], v[36:39]
	s_nop 1
	s_waitcnt lgkmcnt(14)
	v_mfma_f32_16x16x32_bf16 v[36:39], v[194:197], v[8:11], v[36:39]
	s_nop 1
	s_waitcnt lgkmcnt(12)
	v_mfma_f32_16x16x32_bf16 v[36:39], v[198:201], v[12:15], v[36:39]
	s_nop 1
	s_waitcnt lgkmcnt(10)
	v_mfma_f32_16x16x32_bf16 v[36:39], v[202:205], v[16:19], v[36:39]
	s_nop 2
	global_store_dwordx2 v[32:33], v[52:53], off offset:64
	s_waitcnt lgkmcnt(8)
	ds_read_b64_tr_b16 v[186:187], v64 offset:17536
	ds_read_b64_tr_b16 v[188:189], v64 offset:21888
	ds_read_b64_tr_b16 v[190:191], v64 offset:26240
	ds_read_b64_tr_b16 v[192:193], v64 offset:30592
	ds_read_b64_tr_b16 v[194:195], v64 offset:34944
	ds_read_b64_tr_b16 v[196:197], v64 offset:39296
	ds_read_b64_tr_b16 v[198:199], v64 offset:43648
	ds_read_b64_tr_b16 v[200:201], v64 offset:48000
	ds_read_b64_tr_b16 v[202:203], v64 offset:52352
	ds_read_b64_tr_b16 v[204:205], v64 offset:56704
	v_mfma_f32_16x16x32_bf16 v[36:39], v[206:209], v[24:27], v[36:39]
	s_waitcnt lgkmcnt(15)
	v_mfma_f32_16x16x32_bf16 v[36:39], v[210:213], v[28:31], v[36:39]
	s_waitcnt lgkmcnt(14)
	v_mfma_f32_16x16x32_bf16 v[36:39], v[218:221], v[20:23], v[36:39]
	s_nop 7
	v_mul_f32_e32 v35, v34, v36
	v_mul_f32_e32 v36, v34, v37
	v_mul_f32_e32 v37, v34, v38
	v_mul_f32_e32 v38, v34, v39
	v_cvt_pk_bf16_f32 v52, v35, v36
	v_cvt_pk_bf16_f32 v53, v37, v38
	s_nop 4
	s_waitcnt lgkmcnt(12)
	v_mfma_f32_16x16x32_bf16 v[36:39], v[222:225], v[0:3], 0
	s_nop 1
	s_waitcnt lgkmcnt(10)
	v_mfma_f32_16x16x32_bf16 v[36:39], v[226:229], v[4:7], v[36:39]
	s_nop 1
	s_waitcnt lgkmcnt(8)
	ds_read_b64_tr_b16 v[206:207], v64 offset:61056
	ds_read_b64_tr_b16 v[208:209], v64 offset:65408
	ds_read_b64_tr_b16 v[210:211], v64 offset:160
	ds_read_b64_tr_b16 v[212:213], v64 offset:4512
	ds_read_b64_tr_b16 v[218:219], v64 offset:8864
	ds_read_b64_tr_b16 v[220:221], v64 offset:13216
	ds_read_b64_tr_b16 v[222:223], v64 offset:17568
	ds_read_b64_tr_b16 v[224:225], v64 offset:21920
	ds_read_b64_tr_b16 v[226:227], v64 offset:26272
	ds_read_b64_tr_b16 v[228:229], v64 offset:30624
	v_mfma_f32_16x16x32_bf16 v[36:39], v[186:189], v[8:11], v[36:39]
	s_nop 1
	s_waitcnt lgkmcnt(15)
	v_mfma_f32_16x16x32_bf16 v[36:39], v[190:193], v[12:15], v[36:39]
	s_nop 1
	s_waitcnt lgkmcnt(14)
	v_mfma_f32_16x16x32_bf16 v[36:39], v[194:197], v[16:19], v[36:39]
	s_nop 2
	global_store_dwordx2 v[32:33], v[52:53], off offset:96
	s_waitcnt lgkmcnt(12)
; #define LAS __attribute__((address_space(3)))
; __device__ __forceinline__ unsigned pk2(float lo, float hi) { return pg8::cvt_pk_bf16(lo, hi); }
; __device__ __forceinline__ v2u vtr(const LAS bf16* p) { return __builtin_bit_cast(v2u, __builtin_amdgcn_ds_read_tr16_b64_v4i16((LAS v4i16_t*)p)); }
; template <bool SAMPLE>
; __device__ __forceinline__ void mem_unit(const Params& p, int l, LAS unsigned char* lds, int unit, int tid, int wave, int lane) {
;     ...
; #pragma unroll
;         for (int dt = 0; dt < 8; ++dt) { f32x4 o = (f32x4){0.f, 0.f, 0.f, 0.f};
; #pragma unroll
;             for (int cc = 0; cc < 8; ++cc) { const LAS bf16* vp = Vt + (32 * cc + 4 * kq + (q16 >> 2)) * MEM_VS + 16 * dt + 4 * (q16 & 3);
;                 const v2u lo = vtr(vp), hi = vtr(vp + 16 * MEM_VS);
;                 v4u av; av.x = lo.x; av.y = lo.y; av.z = hi.x; av.w = hi.y;
;                 o = __builtin_amdgcn_mfma_f32_16x16x32_bf16(__builtin_bit_cast(bf16x8, av), pf[cc], o, 0, 0, 0); }
;             if (st) { v2u w; w.x = pk2(o[0] * rden, o[1] * rden); w.y = pk2(o[2] * rden, o[3] * rden);
;                 *(v2u*)(MO + row * 512 + h * 128 + 16 * dt + 4 * kq) = w; } }
	v_mfma_f32_16x16x32_bf16 v[36:39], v[198:201], v[24:27], v[36:39]
	s_waitcnt lgkmcnt(10)
	v_mfma_f32_16x16x32_bf16 v[36:39], v[202:205], v[28:31], v[36:39]
	s_waitcnt lgkmcnt(8)
	ds_read_b64_tr_b16 v[186:187], v64 offset:34976
	ds_read_b64_tr_b16 v[188:189], v64 offset:39328
	ds_read_b64_tr_b16 v[190:191], v64 offset:43680
	ds_read_b64_tr_b16 v[192:193], v64 offset:48032
	ds_read_b64_tr_b16 v[194:195], v64 offset:52384
	ds_read_b64_tr_b16 v[196:197], v64 offset:56736
	ds_read_b64_tr_b16 v[198:199], v64 offset:61088
	ds_read_b64_tr_b16 v[200:201], v64 offset:65440
	ds_read_b64_tr_b16 v[202:203], v64 offset:192
	ds_read_b64_tr_b16 v[204:205], v64 offset:4544
	v_mfma_f32_16x16x32_bf16 v[36:39], v[206:209], v[20:23], v[36:39]
	s_nop 7
	v_mul_f32_e32 v35, v34, v36
	v_mul_f32_e32 v36, v34, v37
	v_mul_f32_e32 v37, v34, v38
	v_mul_f32_e32 v38, v34, v39
	v_cvt_pk_bf16_f32 v52, v35, v36
	v_cvt_pk_bf16_f32 v53, v37, v38
	s_nop 4
	s_waitcnt lgkmcnt(15)
	v_mfma_f32_16x16x32_bf16 v[36:39], v[210:213], v[0:3], 0
	s_nop 1
	s_waitcnt lgkmcnt(14)
	v_mfma_f32_16x16x32_bf16 v[36:39], v[218:221], v[4:7], v[36:39]
	s_nop 1
	s_waitcnt lgkmcnt(12)
	v_mfma_f32_16x16x32_bf16 v[36:39], v[222:225], v[8:11], v[36:39]
	s_nop 1
	s_waitcnt lgkmcnt(10)
	v_mfma_f32_16x16x32_bf16 v[36:39], v[226:229], v[12:15], v[36:39]
	s_nop 1
	s_waitcnt lgkmcnt(8)
	ds_read_b64_tr_b16 v[206:207], v64 offset:8896
	ds_read_b64_tr_b16 v[208:209], v64 offset:13248
	ds_read_b64_tr_b16 v[210:211], v64 offset:17600
	ds_read_b64_tr_b16 v[212:213], v64 offset:21952
	ds_read_b64_tr_b16 v[218:219], v64 offset:26304
	ds_read_b64_tr_b16 v[220:221], v64 offset:30656
	ds_read_b64_tr_b16 v[222:223], v64 offset:35008
	ds_read_b64_tr_b16 v[224:225], v64 offset:39360
	ds_read_b64_tr_b16 v[226:227], v64 offset:43712
	ds_read_b64_tr_b16 v[228:229], v64 offset:48064
	v_mfma_f32_16x16x32_bf16 v[36:39], v[186:189], v[16:19], v[36:39]
	s_nop 2
	global_store_dwordx2 v[32:33], v[52:53], off offset:128
	s_waitcnt lgkmcnt(15)
	v_mfma_f32_16x16x32_bf16 v[36:39], v[190:193], v[24:27], v[36:39]
	s_waitcnt lgkmcnt(14)
	v_mfma_f32_16x16x32_bf16 v[36:39], v[194:197], v[28:31], v[36:39]
	s_waitcnt lgkmcnt(12)
	v_mfma_f32_16x16x32_bf16 v[36:39], v[198:201], v[20:23], v[36:39]
	s_nop 7
	v_mul_f32_e32 v35, v34, v36
	v_mul_f32_e32 v36, v34, v37
	v_mul_f32_e32 v37, v34, v38
	v_mul_f32_e32 v38, v34, v39
	v_cvt_pk_bf16_f32 v52, v35, v36
	v_cvt_pk_bf16_f32 v53, v37, v38
	s_nop 4
	s_waitcnt lgkmcnt(10)
	v_mfma_f32_16x16x32_bf16 v[36:39], v[202:205], v[0:3], 0
	s_nop 1
	s_waitcnt lgkmcnt(8)
	ds_read_b64_tr_b16 v[186:187], v64 offset:61120
	ds_read_b64_tr_b16 v[188:189], v64 offset:65472
	ds_read_b64_tr_b16 v[190:191], v64 offset:224
	ds_read_b64_tr_b16 v[192:193], v64 offset:4576
	ds_read_b64_tr_b16 v[194:195], v64 offset:35040
	ds_read_b64_tr_b16 v[196:197], v64 offset:39392
	v_mfma_f32_16x16x32_bf16 v[36:39], v[206:209], v[4:7], v[36:39]
	s_nop 1
	s_waitcnt lgkmcnt(12)
	v_mfma_f32_16x16x32_bf16 v[36:39], v[210:213], v[8:11], v[36:39]
	s_nop 1
	s_waitcnt lgkmcnt(10)
	v_mfma_f32_16x16x32_bf16 v[36:39], v[218:221], v[12:15], v[36:39]
	s_nop 0
	ds_read_b64_tr_b16 v[48:49], v64 offset:52416
	s_waitcnt lgkmcnt(9)
	v_mfma_f32_16x16x32_bf16 v[36:39], v[222:225], v[16:19], v[36:39]
	ds_read_b64_tr_b16 v[50:51], v64 offset:56768
	s_nop 1
	global_store_dwordx2 v[32:33], v[52:53], off offset:160
	s_waitcnt lgkmcnt(8)
	v_mfma_f32_16x16x32_bf16 v[36:39], v[226:229], v[24:27], v[36:39]
	s_waitcnt lgkmcnt(0)
	v_mfma_f32_16x16x32_bf16 v[36:39], v[48:51], v[28:31], v[36:39]
	s_nop 0
	v_mfma_f32_16x16x32_bf16 v[36:39], v[186:189], v[20:23], v[36:39]
	s_nop 7
	v_mul_f32_e32 v35, v34, v36
	v_mul_f32_e32 v36, v34, v37
	v_mul_f32_e32 v37, v34, v38
	v_mul_f32_e32 v38, v34, v39
	v_cvt_pk_bf16_f32 v48, v35, v36
	v_cvt_pk_bf16_f32 v49, v37, v38
	s_nop 1
	ds_read_b64_tr_b16 v[40:41], v64 offset:8928
	ds_read_b64_tr_b16 v[42:43], v64 offset:13280
	ds_read_b64_tr_b16 v[44:45], v64 offset:17632
	s_nop 0
	v_mfma_f32_16x16x32_bf16 v[0:3], v[190:193], v[0:3], 0
	ds_read_b64_tr_b16 v[46:47], v64 offset:21984
	ds_read_b64_tr_b16 v[36:37], v64 offset:26336
	s_waitcnt lgkmcnt(3)
	v_mfma_f32_16x16x32_bf16 v[0:3], v[40:43], v[4:7], v[0:3]
	ds_read_b64_tr_b16 v[38:39], v64 offset:30688
	s_nop 0
	s_waitcnt lgkmcnt(2)
	v_mfma_f32_16x16x32_bf16 v[0:3], v[44:47], v[8:11], v[0:3]
	s_nop 0
	ds_read_b64_tr_b16 v[8:9], v64 offset:43744
	s_waitcnt lgkmcnt(1)
	v_mfma_f32_16x16x32_bf16 v[0:3], v[36:39], v[12:15], v[0:3]
	ds_read_b64_tr_b16 v[10:11], v64 offset:48096
	ds_read_b64_tr_b16 v[12:13], v64 offset:52448
	s_nop 0
	v_mfma_f32_16x16x32_bf16 v[0:3], v[194:197], v[16:19], v[0:3]
	ds_read_b64_tr_b16 v[14:15], v64 offset:56800
	ds_read_b64_tr_b16 v[4:5], v64 offset:61152
	ds_read_b64_tr_b16 v[6:7], v64 offset:65504
	global_store_dwordx2 v[32:33], v[48:49], off offset:192
	s_waitcnt lgkmcnt(4)
	v_mfma_f32_16x16x32_bf16 v[0:3], v[8:11], v[24:27], v[0:3]
	s_waitcnt lgkmcnt(2)
	v_mfma_f32_16x16x32_bf16 v[0:3], v[12:15], v[28:31], v[0:3]
	s_waitcnt lgkmcnt(0)
	v_mfma_f32_16x16x32_bf16 v[0:3], v[4:7], v[20:23], v[0:3]
	s_nop 7
	v_mul_f32_e32 v0, v34, v0
	v_mul_f32_e32 v1, v34, v1
	v_mul_f32_e32 v2, v34, v2
	v_mul_f32_e32 v3, v34, v3
	v_cvt_pk_bf16_f32 v0, v0, v1
	v_cvt_pk_bf16_f32 v1, v2, v3
	global_store_dwordx2 v[32:33], v[0:1], off offset:224
	s_cbranch_scc1 .LBB0_2762
	s_nop 0
	s_nop 0
	s_nop 0
	s_nop 0
	s_nop 0
	s_nop 0
	s_nop 0
	s_nop 0
	s_nop 0
	s_nop 0
	s_nop 0
	s_barrier
	s_branch .LBB0_2727
